# K-loop MFMA groups at s_setprio 3 (was 2), trailing MFMA 3; otherwise v58
# baseline (speedup 1.0000x reference)
; #define PG8_STAGE(bufoff, gbase, voff) do { _Pragma("unroll") for (int _i = 0; _i < 2; ++_i) \
;         __builtin_amdgcn_global_load_lds((const unsigned*)((const char*)(gbase) + (voff)[_i]), (PG8_LAS unsigned*)(lds + (bufoff) + ldsw + _i * 8192), 16, 0, 0); } while (0)
; #define PG8_LDA(dst, b, h) do { _Pragma("unroll") for (int m = 0; m < 4; ++m) _Pragma("unroll") for (int k = 0; k < 2; ++k) dst[m][k] = *(const PG8_LAS bf16x8*)(lds + PG8_SA(b, h) + aoff + m * 2048 + k * 1024); } while (0)
; #define PG8_LDB(dst, b, h) do { _Pragma("unroll") for (int n = 0; n < 2; ++n) _Pragma("unroll") for (int k = 0; k < 2; ++k) dst[n][k] = *(const PG8_LAS bf16x8*)(lds + PG8_SB(b, h) + boff + n * 2048 + k * 1024); } while (0)
; #define PG8_MMA(ai, bj, At, Bt) do { __builtin_amdgcn_s_setprio(1); _Pragma("unroll") for (int m = 0; m < 4; ++m) _Pragma("unroll") for (int n = 0; n < 2; ++n) _Pragma("unroll") for (int k = 0; k < 2; ++k) \
;         acc[ai][bj][m][n] = __builtin_amdgcn_mfma_f32_16x16x32_bf16(Bt[n][k], At[m][k], acc[ai][bj][m][n], 0, 0, 0); __builtin_amdgcn_s_setprio(0); } while (0)
; #define PG8_WAIT_V(n) asm volatile("s_waitcnt vmcnt(" #n ")" ::: "memory")
; #define PG8_WAIT_L(n) asm volatile("s_waitcnt lgkmcnt(" #n ")" ::: "memory")
; #define PG8_BAR __builtin_amdgcn_s_barrier()
; template <class Epi, class Sched, bool ALIGN_EPI = false, bool SP2 = false>
; __device__ __forceinline__ void gemm_phase(PG8_LAS unsigned char* lds, const Gemm g, const Sched& S, const Epi& E, const int wv  ) {
;     ...
;         for (int t = 0; t < nt; t += 2) {
;             const bool last = (t == nt - 2);
;             const char* a1 = cA + (size_t)(t + 1) * kstep;
;             const char* a2 = last ? nA : cA + (size_t)(t + 2) * kstep; const char* b2 = last ? nB : cB + (size_t)(t + 2) * kstep;
;             const char* a3 = a2 + kstep; const char* b3 = b2 + kstep;
;             if (last && has_next) S.a_ready(nxt);
;             if constexpr (SP2) {
;             PG8_LDB(B0, 0, 0); PG8_LDB(B1, 0, 1); PG8_SCHED; PG8_LDA(At, 0, 0); PG8_STAGE(PG8_SA(1, 1), a1 + hstepA, voffA);
;             PG8_WAIT_V(8); PG8_WAIT_L(0); PG8_BAR; PG8_MMA(0, 0, At, B0); PG8_MMA(0, 1, At, B1); PG8_BAR; PG8_SCHED;
;             PG8_LDA(At, 0, 1); PG8_STAGE(PG8_SB(0, 0), b2, voffB); PG8_STAGE(PG8_SB(0, 1), b2 + hstepB, voffB); PG8_STAGE(PG8_SA(0, 0), a2, voffA);
.LBB0_121:
	ds_read_b128 v[146:149], v152
	ds_read_b128 v[156:159], v152 offset:1024
	ds_read_b128 v[160:163], v152 offset:2048
	ds_read_b128 v[164:167], v152 offset:3072
	ds_read_b128 v[168:171], v153
	ds_read_b128 v[172:175], v153 offset:1024
	ds_read_b128 v[176:179], v153 offset:2048
	ds_read_b128 v[180:183], v153 offset:3072
	s_add_u32 s66, s64, 0xfff00080
	s_addc_u32 s67, s65, -1
	s_cmp_eq_u32 s96, 60
	s_cselect_b32 s69, s57, s67
	s_cselect_b32 s68, s92, s66
	s_cselect_b32 s67, s55, s95
	s_cselect_b32 s66, s93, s94
	v_lshl_add_u64 v[216:217], s[64:65], 0, v[138:139]
	s_add_i32 m0, s75, 0xc000
	ds_read_b128 v[184:187], v154
	ds_read_b128 v[188:191], v154 offset:1024
	ds_read_b128 v[192:195], v154 offset:2048
	ds_read_b128 v[196:199], v154 offset:3072
	ds_read_b128 v[200:203], v154 offset:4096
	ds_read_b128 v[204:207], v154 offset:5120
	ds_read_b128 v[208:211], v154 offset:6144
	ds_read_b128 v[212:215], v154 offset:7168
	global_load_lds_dwordx4 v[216:217], off
	v_lshl_add_u64 v[216:217], s[64:65], 0, v[140:141]
	s_add_i32 m0, s75, 0xe000
	s_nop 0
	global_load_lds_dwordx4 v[216:217], off
	s_waitcnt vmcnt(8)
	s_waitcnt lgkmcnt(0)
	s_barrier
	s_setprio 3
	s_waitcnt lgkmcnt(0)
	v_mfma_f32_16x16x32_bf16 v[76:79], v[146:149], v[184:187], v[76:79]
	v_mfma_f32_16x16x32_bf16 v[72:75], v[160:163], v[184:187], v[72:75]
	v_mfma_f32_16x16x32_bf16 v[68:71], v[146:149], v[192:195], v[68:71]
	v_mfma_f32_16x16x32_bf16 v[64:67], v[160:163], v[192:195], v[64:67]
	v_mfma_f32_16x16x32_bf16 v[56:59], v[146:149], v[200:203], v[56:59]
	v_mfma_f32_16x16x32_bf16 v[52:55], v[160:163], v[200:203], v[52:55]
	v_mfma_f32_16x16x32_bf16 v[44:47], v[146:149], v[208:211], v[44:47]
	v_mfma_f32_16x16x32_bf16 v[40:43], v[160:163], v[208:211], v[40:43]
	v_mfma_f32_16x16x32_bf16 v[76:79], v[156:159], v[188:191], v[76:79]
	v_mfma_f32_16x16x32_bf16 v[72:75], v[164:167], v[188:191], v[72:75]
	v_mfma_f32_16x16x32_bf16 v[68:71], v[156:159], v[196:199], v[68:71]
	v_mfma_f32_16x16x32_bf16 v[64:67], v[164:167], v[196:199], v[64:67]
	v_mfma_f32_16x16x32_bf16 v[56:59], v[156:159], v[204:207], v[56:59]
	v_mfma_f32_16x16x32_bf16 v[52:55], v[164:167], v[204:207], v[52:55]
	v_mfma_f32_16x16x32_bf16 v[44:47], v[156:159], v[212:215], v[44:47]
	v_mfma_f32_16x16x32_bf16 v[40:43], v[164:167], v[212:215], v[40:43]
	s_setprio 0
	s_setprio 3
	v_mfma_f32_16x16x32_bf16 v[124:127], v[168:171], v[184:187], v[124:127]
	v_mfma_f32_16x16x32_bf16 v[120:123], v[176:179], v[184:187], v[120:123]
	v_mfma_f32_16x16x32_bf16 v[116:119], v[168:171], v[192:195], v[116:119]
	v_mfma_f32_16x16x32_bf16 v[112:115], v[176:179], v[192:195], v[112:115]
	v_mfma_f32_16x16x32_bf16 v[108:111], v[168:171], v[200:203], v[108:111]
	v_mfma_f32_16x16x32_bf16 v[104:107], v[176:179], v[200:203], v[104:107]
	v_mfma_f32_16x16x32_bf16 v[100:103], v[168:171], v[208:211], v[100:103]
	v_mfma_f32_16x16x32_bf16 v[96:99], v[176:179], v[208:211], v[96:99]
	v_mfma_f32_16x16x32_bf16 v[124:127], v[172:175], v[188:191], v[124:127]
	v_mfma_f32_16x16x32_bf16 v[120:123], v[180:183], v[188:191], v[120:123]
	v_mfma_f32_16x16x32_bf16 v[116:119], v[172:175], v[196:199], v[116:119]
	v_mfma_f32_16x16x32_bf16 v[112:115], v[180:183], v[196:199], v[112:115]
	v_mfma_f32_16x16x32_bf16 v[108:111], v[172:175], v[204:207], v[108:111]
	v_mfma_f32_16x16x32_bf16 v[104:107], v[180:183], v[204:207], v[104:107]
	v_mfma_f32_16x16x32_bf16 v[100:103], v[172:175], v[212:215], v[100:103]
	s_setprio 3
	s_barrier
	v_mfma_f32_16x16x32_bf16 v[96:99], v[180:183], v[212:215], v[96:99]
	s_setprio 0
	s_add_i32 s97, s84, s74
	v_lshl_add_u64 v[216:217], s[66:67], 0, v[130:131]
	s_mov_b32 m0, s97
	ds_read_b128 v[184:187], v154 offset:16384
	ds_read_b128 v[188:191], v154 offset:17408
	ds_read_b128 v[192:195], v154 offset:18432
	ds_read_b128 v[196:199], v154 offset:19456
	ds_read_b128 v[200:203], v154 offset:20480
	ds_read_b128 v[204:207], v154 offset:21504
	ds_read_b128 v[208:211], v154 offset:22528
	ds_read_b128 v[212:215], v154 offset:23552
	global_load_lds_dwordx4 v[216:217], off
	s_add_i32 m0, s97, 0x2000
	s_add_u32 vcc_lo, s66, 0x100000
	v_lshl_add_u64 v[218:219], s[66:67], 0, v[134:135]
	s_addc_u32 vcc_hi, s67, 0
	s_add_i32 s97, s85, s74
	global_load_lds_dwordx4 v[218:219], off
	v_lshl_add_u64 v[220:221], vcc, 0, v[130:131]
	s_mov_b32 m0, s97
	v_lshl_add_u64 v[222:223], s[68:69], 0, v[132:133]
	global_load_lds_dwordx4 v[220:221], off
	v_lshl_add_u64 v[220:221], vcc, 0, v[134:135]
	s_add_i32 m0, s97, 0x2000
	s_nop 0
	global_load_lds_dwordx4 v[220:221], off
	v_lshl_add_u64 v[220:221], s[68:69], 0, v[128:129]
	s_mov_b32 m0, s75
	s_nop 0
	global_load_lds_dwordx4 v[220:221], off
	s_mov_b32 m0, s76
	s_nop 0
	global_load_lds_dwordx4 v[222:223], off
	s_waitcnt vmcnt(8)
	s_waitcnt lgkmcnt(0)
	s_barrier
; #define PG8_STAGE(bufoff, gbase, voff) do { _Pragma("unroll") for (int _i = 0; _i < 2; ++_i) \
;         __builtin_amdgcn_global_load_lds((const unsigned*)((const char*)(gbase) + (voff)[_i]), (PG8_LAS unsigned*)(lds + (bufoff) + ldsw + _i * 8192), 16, 0, 0); } while (0)
; #define PG8_LDA(dst, b, h) do { _Pragma("unroll") for (int m = 0; m < 4; ++m) _Pragma("unroll") for (int k = 0; k < 2; ++k) dst[m][k] = *(const PG8_LAS bf16x8*)(lds + PG8_SA(b, h) + aoff + m * 2048 + k * 1024); } while (0)
; #define PG8_LDB(dst, b, h) do { _Pragma("unroll") for (int n = 0; n < 2; ++n) _Pragma("unroll") for (int k = 0; k < 2; ++k) dst[n][k] = *(const PG8_LAS bf16x8*)(lds + PG8_SB(b, h) + boff + n * 2048 + k * 1024); } while (0)
; #define PG8_MMA(ai, bj, At, Bt) do { __builtin_amdgcn_s_setprio(1); _Pragma("unroll") for (int m = 0; m < 4; ++m) _Pragma("unroll") for (int n = 0; n < 2; ++n) _Pragma("unroll") for (int k = 0; k < 2; ++k) \
;         acc[ai][bj][m][n] = __builtin_amdgcn_mfma_f32_16x16x32_bf16(Bt[n][k], At[m][k], acc[ai][bj][m][n], 0, 0, 0); __builtin_amdgcn_s_setprio(0); } while (0)
; #define PG8_WAIT_V(n) asm volatile("s_waitcnt vmcnt(" #n ")" ::: "memory")
; #define PG8_WAIT_L(n) asm volatile("s_waitcnt lgkmcnt(" #n ")" ::: "memory")
; #define PG8_BAR __builtin_amdgcn_s_barrier()
; #define PG8_SCHED __builtin_amdgcn_sched_barrier(0)
; template <class Epi, class Sched, bool ALIGN_EPI = false, bool SP2 = false>
; __device__ __forceinline__ void gemm_phase(PG8_LAS unsigned char* lds, const Gemm g, const Sched& S, const Epi& E, const int wv  ) {
;     ...
;             PG8_WAIT_V(8); PG8_WAIT_L(0); PG8_BAR; PG8_MMA(1, 0, At, B0); PG8_MMA(1, 1, At, B1); PG8_BAR; PG8_SCHED;
;             PG8_LDB(B0, 1, 0); PG8_LDB(B1, 1, 1); PG8_SCHED; PG8_LDA(At, 1, 0); PG8_STAGE(PG8_SA(0, 1), a2 + hstepA, voffA);
;             PG8_WAIT_V(8); PG8_WAIT_L(0); PG8_BAR; PG8_MMA(0, 0, At, B0); PG8_MMA(0, 1, At, B1); PG8_BAR; PG8_SCHED;
	s_setprio 3
	s_waitcnt lgkmcnt(0)
	v_mfma_f32_16x16x32_bf16 v[28:31], v[146:149], v[184:187], v[28:31]
	v_mfma_f32_16x16x32_bf16 v[24:27], v[160:163], v[184:187], v[24:27]
	v_mfma_f32_16x16x32_bf16 v[20:23], v[146:149], v[192:195], v[20:23]
	v_mfma_f32_16x16x32_bf16 v[16:19], v[160:163], v[192:195], v[16:19]
	v_mfma_f32_16x16x32_bf16 v[12:15], v[146:149], v[200:203], v[12:15]
	v_mfma_f32_16x16x32_bf16 v[8:11], v[160:163], v[200:203], v[8:11]
	v_mfma_f32_16x16x32_bf16 v[4:7], v[146:149], v[208:211], v[4:7]
	v_mfma_f32_16x16x32_bf16 v[0:3], v[160:163], v[208:211], v[0:3]
	v_mfma_f32_16x16x32_bf16 v[28:31], v[156:159], v[188:191], v[28:31]
	v_mfma_f32_16x16x32_bf16 v[24:27], v[164:167], v[188:191], v[24:27]
	v_mfma_f32_16x16x32_bf16 v[20:23], v[156:159], v[196:199], v[20:23]
	v_mfma_f32_16x16x32_bf16 v[16:19], v[164:167], v[196:199], v[16:19]
	v_mfma_f32_16x16x32_bf16 v[12:15], v[156:159], v[204:207], v[12:15]
	v_mfma_f32_16x16x32_bf16 v[8:11], v[164:167], v[204:207], v[8:11]
	v_mfma_f32_16x16x32_bf16 v[4:7], v[156:159], v[212:215], v[4:7]
	v_mfma_f32_16x16x32_bf16 v[0:3], v[164:167], v[212:215], v[0:3]
	s_setprio 0
	s_setprio 3
	v_mfma_f32_16x16x32_bf16 v[92:95], v[168:171], v[184:187], v[92:95]
	v_mfma_f32_16x16x32_bf16 v[88:91], v[176:179], v[184:187], v[88:91]
	v_mfma_f32_16x16x32_bf16 v[84:87], v[168:171], v[192:195], v[84:87]
	v_mfma_f32_16x16x32_bf16 v[80:83], v[176:179], v[192:195], v[80:83]
	v_mfma_f32_16x16x32_bf16 v[60:63], v[168:171], v[200:203], v[60:63]
	v_mfma_f32_16x16x32_bf16 v[48:51], v[176:179], v[200:203], v[48:51]
	v_mfma_f32_16x16x32_bf16 v[36:39], v[168:171], v[208:211], v[36:39]
	v_mfma_f32_16x16x32_bf16 v[32:35], v[176:179], v[208:211], v[32:35]
	v_mfma_f32_16x16x32_bf16 v[92:95], v[172:175], v[188:191], v[92:95]
	v_mfma_f32_16x16x32_bf16 v[88:91], v[180:183], v[188:191], v[88:91]
	v_mfma_f32_16x16x32_bf16 v[84:87], v[172:175], v[196:199], v[84:87]
	v_mfma_f32_16x16x32_bf16 v[80:83], v[180:183], v[196:199], v[80:83]
	v_mfma_f32_16x16x32_bf16 v[60:63], v[172:175], v[204:207], v[60:63]
	v_mfma_f32_16x16x32_bf16 v[48:51], v[180:183], v[204:207], v[48:51]
	v_mfma_f32_16x16x32_bf16 v[36:39], v[172:175], v[212:215], v[36:39]
	s_setprio 3
	s_barrier
	v_mfma_f32_16x16x32_bf16 v[32:35], v[180:183], v[212:215], v[32:35]
	s_setprio 0
	s_add_i32 s97, 0, 0x18000
	v_add_u32_e32 v155, s97, v150
	s_add_i32 vcc_lo, 0, 0x1c000
	ds_read_b128 v[146:149], v155
	ds_read_b128 v[156:159], v155 offset:1024
	ds_read_b128 v[160:163], v155 offset:2048
	ds_read_b128 v[164:167], v155 offset:3072
	v_add_u32_e32 v155, vcc_lo, v150
	ds_read_b128 v[168:171], v155
	ds_read_b128 v[172:175], v155 offset:1024
	ds_read_b128 v[176:179], v155 offset:2048
	ds_read_b128 v[180:183], v155 offset:3072
	s_add_u32 s68, s68, 0x100000
	s_addc_u32 s69, s69, 0
	s_mov_b32 m0, s77
	v_lshl_add_u64 v[224:225], s[68:69], 0, v[128:129]
	ds_read_b128 v[184:187], v154 offset:32768
	ds_read_b128 v[188:191], v154 offset:33792
	ds_read_b128 v[192:195], v154 offset:34816
	ds_read_b128 v[196:199], v154 offset:35840
	ds_read_b128 v[200:203], v154 offset:36864
	ds_read_b128 v[204:207], v154 offset:37888
	ds_read_b128 v[208:211], v154 offset:38912
	ds_read_b128 v[212:215], v154 offset:39936
	global_load_lds_dwordx4 v[224:225], off
	v_lshl_add_u64 v[224:225], s[68:69], 0, v[132:133]
	s_mov_b32 m0, s78
	s_nop 0
	global_load_lds_dwordx4 v[224:225], off
	s_waitcnt vmcnt(8)
	s_waitcnt lgkmcnt(0)
	s_barrier
	s_setprio 3
	s_waitcnt lgkmcnt(0)
	v_mfma_f32_16x16x32_bf16 v[76:79], v[146:149], v[184:187], v[76:79]
	v_mfma_f32_16x16x32_bf16 v[72:75], v[160:163], v[184:187], v[72:75]
	v_mfma_f32_16x16x32_bf16 v[68:71], v[146:149], v[192:195], v[68:71]
	v_mfma_f32_16x16x32_bf16 v[64:67], v[160:163], v[192:195], v[64:67]
	v_mfma_f32_16x16x32_bf16 v[56:59], v[146:149], v[200:203], v[56:59]
	v_mfma_f32_16x16x32_bf16 v[52:55], v[160:163], v[200:203], v[52:55]
	v_mfma_f32_16x16x32_bf16 v[44:47], v[146:149], v[208:211], v[44:47]
	v_mfma_f32_16x16x32_bf16 v[40:43], v[160:163], v[208:211], v[40:43]
	v_mfma_f32_16x16x32_bf16 v[76:79], v[156:159], v[188:191], v[76:79]
	v_mfma_f32_16x16x32_bf16 v[72:75], v[164:167], v[188:191], v[72:75]
	v_mfma_f32_16x16x32_bf16 v[68:71], v[156:159], v[196:199], v[68:71]
	v_mfma_f32_16x16x32_bf16 v[64:67], v[164:167], v[196:199], v[64:67]
	v_mfma_f32_16x16x32_bf16 v[56:59], v[156:159], v[204:207], v[56:59]
	v_mfma_f32_16x16x32_bf16 v[52:55], v[164:167], v[204:207], v[52:55]
	v_mfma_f32_16x16x32_bf16 v[44:47], v[156:159], v[212:215], v[44:47]
	v_mfma_f32_16x16x32_bf16 v[40:43], v[164:167], v[212:215], v[40:43]
	s_setprio 0
	s_setprio 3
	v_mfma_f32_16x16x32_bf16 v[124:127], v[168:171], v[184:187], v[124:127]
	v_mfma_f32_16x16x32_bf16 v[120:123], v[176:179], v[184:187], v[120:123]
	v_mfma_f32_16x16x32_bf16 v[116:119], v[168:171], v[192:195], v[116:119]
	v_mfma_f32_16x16x32_bf16 v[112:115], v[176:179], v[192:195], v[112:115]
	v_mfma_f32_16x16x32_bf16 v[108:111], v[168:171], v[200:203], v[108:111]
	v_mfma_f32_16x16x32_bf16 v[104:107], v[176:179], v[200:203], v[104:107]
	v_mfma_f32_16x16x32_bf16 v[100:103], v[168:171], v[208:211], v[100:103]
	v_mfma_f32_16x16x32_bf16 v[96:99], v[176:179], v[208:211], v[96:99]
	v_mfma_f32_16x16x32_bf16 v[124:127], v[172:175], v[188:191], v[124:127]
	v_mfma_f32_16x16x32_bf16 v[120:123], v[180:183], v[188:191], v[120:123]
	v_mfma_f32_16x16x32_bf16 v[116:119], v[172:175], v[196:199], v[116:119]
	v_mfma_f32_16x16x32_bf16 v[112:115], v[180:183], v[196:199], v[112:115]
	v_mfma_f32_16x16x32_bf16 v[108:111], v[172:175], v[204:207], v[108:111]
	v_mfma_f32_16x16x32_bf16 v[104:107], v[180:183], v[204:207], v[104:107]
	v_mfma_f32_16x16x32_bf16 v[100:103], v[172:175], v[212:215], v[100:103]
	s_setprio 3
	s_barrier
; #define PG8_STAGE(bufoff, gbase, voff) do { _Pragma("unroll") for (int _i = 0; _i < 2; ++_i) \
;         __builtin_amdgcn_global_load_lds((const unsigned*)((const char*)(gbase) + (voff)[_i]), (PG8_LAS unsigned*)(lds + (bufoff) + ldsw + _i * 8192), 16, 0, 0); } while (0)
; #define PG8_LDA(dst, b, h) do { _Pragma("unroll") for (int m = 0; m < 4; ++m) _Pragma("unroll") for (int k = 0; k < 2; ++k) dst[m][k] = *(const PG8_LAS bf16x8*)(lds + PG8_SA(b, h) + aoff + m * 2048 + k * 1024); } while (0)
; #define PG8_MMA(ai, bj, At, Bt) do { __builtin_amdgcn_s_setprio(1); _Pragma("unroll") for (int m = 0; m < 4; ++m) _Pragma("unroll") for (int n = 0; n < 2; ++n) _Pragma("unroll") for (int k = 0; k < 2; ++k) \
;         acc[ai][bj][m][n] = __builtin_amdgcn_mfma_f32_16x16x32_bf16(Bt[n][k], At[m][k], acc[ai][bj][m][n], 0, 0, 0); __builtin_amdgcn_s_setprio(0); } while (0)
; #define PG8_WAIT_V(n) asm volatile("s_waitcnt vmcnt(" #n ")" ::: "memory")
; #define PG8_WAIT_L(n) asm volatile("s_waitcnt lgkmcnt(" #n ")" ::: "memory")
; #define PG8_BAR __builtin_amdgcn_s_barrier()
; #define PG8_SCHED __builtin_amdgcn_sched_barrier(0)
; template <class Epi, class Sched, bool ALIGN_EPI = false, bool SP2 = false>
; __device__ __forceinline__ void gemm_phase(PG8_LAS unsigned char* lds, const Gemm g, const Sched& S, const Epi& E, const int wv  ) {
;     ...
;             PG8_LDA(At, 1, 1); PG8_STAGE(PG8_SB(1, 0), b3, voffB); PG8_STAGE(PG8_SB(1, 1), b3 + hstepB, voffB); PG8_STAGE(PG8_SA(1, 0), a3, voffA);
;             PG8_WAIT_V(8); PG8_WAIT_L(0); PG8_BAR; PG8_MMA(1, 0, At, B0); PG8_MMA(1, 1, At, B1); PG8_BAR; PG8_SCHED;
;     ...
;         if constexpr (ALIGN_EPI) { if (wr == 0) PG8_BAR; }
	v_mfma_f32_16x16x32_bf16 v[96:99], v[180:183], v[212:215], v[96:99]
	s_setprio 0
	s_add_i32 s68, s97, s74
	v_lshl_add_u64 v[216:217], v[216:217], 0, s[18:19]
	s_mov_b32 m0, s68
	ds_read_b128 v[184:187], v154 offset:49152
	ds_read_b128 v[188:191], v154 offset:50176
	ds_read_b128 v[192:195], v154 offset:51200
	ds_read_b128 v[196:199], v154 offset:52224
	ds_read_b128 v[200:203], v154 offset:53248
	ds_read_b128 v[204:207], v154 offset:54272
	ds_read_b128 v[208:211], v154 offset:55296
	ds_read_b128 v[212:215], v154 offset:56320
	global_load_lds_dwordx4 v[216:217], off
	s_add_i32 m0, s68, 0x2000
	s_add_u32 s66, s66, 0x100080
	v_lshl_add_u64 v[216:217], v[218:219], 0, s[18:19]
	s_addc_u32 s67, s67, 0
	s_add_i32 s68, vcc_lo, s74
	global_load_lds_dwordx4 v[216:217], off
	v_lshl_add_u64 v[216:217], s[66:67], 0, v[130:131]
	s_mov_b32 m0, s68
	s_nop 0
	global_load_lds_dwordx4 v[216:217], off
	v_lshl_add_u64 v[216:217], s[66:67], 0, v[134:135]
	s_add_i32 m0, s68, 0x2000
	s_nop 0
	global_load_lds_dwordx4 v[216:217], off
	v_lshl_add_u64 v[216:217], v[220:221], 0, s[18:19]
	s_mov_b32 m0, s81
	s_nop 0
	global_load_lds_dwordx4 v[216:217], off
	v_lshl_add_u64 v[216:217], v[222:223], 0, s[18:19]
	s_mov_b32 m0, s82
	s_nop 0
	global_load_lds_dwordx4 v[216:217], off
	s_waitcnt vmcnt(8)
	s_waitcnt lgkmcnt(0)
	s_barrier
	s_setprio 3
	s_waitcnt lgkmcnt(0)
	v_mfma_f32_16x16x32_bf16 v[28:31], v[146:149], v[184:187], v[28:31]
	v_mfma_f32_16x16x32_bf16 v[24:27], v[160:163], v[184:187], v[24:27]
	v_mfma_f32_16x16x32_bf16 v[20:23], v[146:149], v[192:195], v[20:23]
	v_mfma_f32_16x16x32_bf16 v[16:19], v[160:163], v[192:195], v[16:19]
	v_mfma_f32_16x16x32_bf16 v[12:15], v[146:149], v[200:203], v[12:15]
	v_mfma_f32_16x16x32_bf16 v[8:11], v[160:163], v[200:203], v[8:11]
	v_mfma_f32_16x16x32_bf16 v[4:7], v[146:149], v[208:211], v[4:7]
	v_mfma_f32_16x16x32_bf16 v[0:3], v[160:163], v[208:211], v[0:3]
	v_mfma_f32_16x16x32_bf16 v[28:31], v[156:159], v[188:191], v[28:31]
	v_mfma_f32_16x16x32_bf16 v[24:27], v[164:167], v[188:191], v[24:27]
	v_mfma_f32_16x16x32_bf16 v[20:23], v[156:159], v[196:199], v[20:23]
	v_mfma_f32_16x16x32_bf16 v[16:19], v[164:167], v[196:199], v[16:19]
	v_mfma_f32_16x16x32_bf16 v[12:15], v[156:159], v[204:207], v[12:15]
	v_mfma_f32_16x16x32_bf16 v[8:11], v[164:167], v[204:207], v[8:11]
	v_mfma_f32_16x16x32_bf16 v[4:7], v[156:159], v[212:215], v[4:7]
	v_mfma_f32_16x16x32_bf16 v[0:3], v[164:167], v[212:215], v[0:3]
	s_setprio 0
	s_setprio 3
	v_mfma_f32_16x16x32_bf16 v[92:95], v[168:171], v[184:187], v[92:95]
	v_mfma_f32_16x16x32_bf16 v[88:91], v[176:179], v[184:187], v[88:91]
	v_mfma_f32_16x16x32_bf16 v[84:87], v[168:171], v[192:195], v[84:87]
	v_mfma_f32_16x16x32_bf16 v[80:83], v[176:179], v[192:195], v[80:83]
	v_mfma_f32_16x16x32_bf16 v[60:63], v[168:171], v[200:203], v[60:63]
	v_mfma_f32_16x16x32_bf16 v[48:51], v[176:179], v[200:203], v[48:51]
	v_mfma_f32_16x16x32_bf16 v[36:39], v[168:171], v[208:211], v[36:39]
	v_mfma_f32_16x16x32_bf16 v[32:35], v[176:179], v[208:211], v[32:35]
	v_mfma_f32_16x16x32_bf16 v[92:95], v[172:175], v[188:191], v[92:95]
	v_mfma_f32_16x16x32_bf16 v[88:91], v[180:183], v[188:191], v[88:91]
	v_mfma_f32_16x16x32_bf16 v[84:87], v[172:175], v[196:199], v[84:87]
	v_mfma_f32_16x16x32_bf16 v[80:83], v[180:183], v[196:199], v[80:83]
	v_mfma_f32_16x16x32_bf16 v[60:63], v[172:175], v[204:207], v[60:63]
	v_mfma_f32_16x16x32_bf16 v[48:51], v[180:183], v[204:207], v[48:51]
	v_mfma_f32_16x16x32_bf16 v[36:39], v[172:175], v[212:215], v[36:39]
	s_setprio 3
	s_barrier
	v_mfma_f32_16x16x32_bf16 v[32:35], v[180:183], v[212:215], v[32:35]
	s_setprio 0
	s_add_i32 s96, s96, 2
	s_add_u32 s64, s64, 0x100
	s_addc_u32 s65, s65, 0
	s_add_u32 s94, s94, 0x100
	s_addc_u32 s95, s95, 0
	s_cmp_gt_u32 s96, 61
	s_cbranch_scc0 .LBB0_121
	s_and_b64 vcc, exec, s[20:21]
	s_cbranch_vccz .LBB0_124
	s_barrier

; #define PG8_STAGE(bufoff, gbase, voff) do { _Pragma("unroll") for (int _i = 0; _i < 2; ++_i) \
;         __builtin_amdgcn_global_load_lds((const unsigned*)((const char*)(gbase) + (voff)[_i]), (PG8_LAS unsigned*)(lds + (bufoff) + ldsw + _i * 8192), 16, 0, 0); } while (0)
; #define PG8_LDA(dst, b, h) do { _Pragma("unroll") for (int m = 0; m < 4; ++m) _Pragma("unroll") for (int k = 0; k < 2; ++k) dst[m][k] = *(const PG8_LAS bf16x8*)(lds + PG8_SA(b, h) + aoff + m * 2048 + k * 1024); } while (0)
; #define PG8_LDB(dst, b, h) do { _Pragma("unroll") for (int n = 0; n < 2; ++n) _Pragma("unroll") for (int k = 0; k < 2; ++k) dst[n][k] = *(const PG8_LAS bf16x8*)(lds + PG8_SB(b, h) + boff + n * 2048 + k * 1024); } while (0)
; #define PG8_MMA(ai, bj, At, Bt) do { __builtin_amdgcn_s_setprio(1); _Pragma("unroll") for (int m = 0; m < 4; ++m) _Pragma("unroll") for (int n = 0; n < 2; ++n) _Pragma("unroll") for (int k = 0; k < 2; ++k) \
;         acc[ai][bj][m][n] = __builtin_amdgcn_mfma_f32_16x16x32_bf16(Bt[n][k], At[m][k], acc[ai][bj][m][n], 0, 0, 0); __builtin_amdgcn_s_setprio(0); } while (0)
; #define PG8_WAIT_V(n) asm volatile("s_waitcnt vmcnt(" #n ")" ::: "memory")
; #define PG8_WAIT_L(n) asm volatile("s_waitcnt lgkmcnt(" #n ")" ::: "memory")
; #define PG8_BAR __builtin_amdgcn_s_barrier()
; template <class Epi, class Sched, bool ALIGN_EPI = false, bool SP2 = false>
; __device__ __forceinline__ void gemm_phase(PG8_LAS unsigned char* lds, const Gemm g, const Sched& S, const Epi& E, const int wv  ) {
;     ...
;             const char* a1 = cA + (size_t)(t + 1) * kstep;
;             const char* a2 = last ? nA : cA + (size_t)(t + 2) * kstep; const char* b2 = last ? nB : cB + (size_t)(t + 2) * kstep;
;             const char* a3 = a2 + kstep; const char* b3 = b2 + kstep;
;             if (last && has_next) S.a_ready(nxt);
;             if constexpr (SP2) {
;             PG8_LDB(B0, 0, 0); PG8_LDB(B1, 0, 1); PG8_SCHED; PG8_LDA(At, 0, 0); PG8_STAGE(PG8_SA(1, 1), a1 + hstepA, voffA);
;             PG8_WAIT_V(8); PG8_WAIT_L(0); PG8_BAR; PG8_MMA(0, 0, At, B0); PG8_MMA(0, 1, At, B1); PG8_BAR; PG8_SCHED;
;             PG8_LDA(At, 0, 1); PG8_STAGE(PG8_SB(0, 0), b2, voffB); PG8_STAGE(PG8_SB(0, 1), b2 + hstepB, voffB); PG8_STAGE(PG8_SA(0, 0), a2, voffA);
;             PG8_WAIT_V(8); PG8_WAIT_L(0); PG8_BAR; PG8_MMA(1, 0, At, B0); PG8_MMA(1, 1, At, B1); PG8_BAR; PG8_SCHED;
.LBB0_706:
	ds_read_b128 v[146:149], v152
	ds_read_b128 v[156:159], v152 offset:1024
	ds_read_b128 v[160:163], v152 offset:2048
	ds_read_b128 v[164:167], v152 offset:3072
	ds_read_b128 v[168:171], v153
	ds_read_b128 v[172:175], v153 offset:1024
	ds_read_b128 v[176:179], v153 offset:2048
	ds_read_b128 v[180:183], v153 offset:3072
	s_add_u32 s60, s58, 0xfff00080
	s_addc_u32 s61, s59, -1
	s_cmp_eq_u32 s87, 60
	s_cselect_b32 s63, s51, s61
	s_cselect_b32 s62, s83, s60
	s_cselect_b32 s61, s49, s86
	s_cselect_b32 s60, s84, s85
	v_lshl_add_u64 v[216:217], s[58:59], 0, v[138:139]
	s_add_i32 m0, s68, 0xc000
	ds_read_b128 v[184:187], v154
	ds_read_b128 v[188:191], v154 offset:1024
	ds_read_b128 v[192:195], v154 offset:2048
	ds_read_b128 v[196:199], v154 offset:3072
	ds_read_b128 v[200:203], v154 offset:4096
	ds_read_b128 v[204:207], v154 offset:5120
	ds_read_b128 v[208:211], v154 offset:6144
	ds_read_b128 v[212:215], v154 offset:7168
	global_load_lds_dwordx4 v[216:217], off
	v_lshl_add_u64 v[216:217], s[58:59], 0, v[140:141]
	s_add_i32 m0, s68, 0xe000
	s_nop 0
	global_load_lds_dwordx4 v[216:217], off
	s_waitcnt vmcnt(8)
	s_waitcnt lgkmcnt(0)
	s_barrier
	s_setprio 3
	s_waitcnt lgkmcnt(0)
	v_mfma_f32_16x16x32_bf16 v[76:79], v[146:149], v[184:187], v[76:79]
	v_mfma_f32_16x16x32_bf16 v[72:75], v[160:163], v[184:187], v[72:75]
	v_mfma_f32_16x16x32_bf16 v[68:71], v[146:149], v[192:195], v[68:71]
	v_mfma_f32_16x16x32_bf16 v[64:67], v[160:163], v[192:195], v[64:67]
	v_mfma_f32_16x16x32_bf16 v[56:59], v[146:149], v[200:203], v[56:59]
	v_mfma_f32_16x16x32_bf16 v[52:55], v[160:163], v[200:203], v[52:55]
	v_mfma_f32_16x16x32_bf16 v[44:47], v[146:149], v[208:211], v[44:47]
	v_mfma_f32_16x16x32_bf16 v[40:43], v[160:163], v[208:211], v[40:43]
	v_mfma_f32_16x16x32_bf16 v[76:79], v[156:159], v[188:191], v[76:79]
	v_mfma_f32_16x16x32_bf16 v[72:75], v[164:167], v[188:191], v[72:75]
	v_mfma_f32_16x16x32_bf16 v[68:71], v[156:159], v[196:199], v[68:71]
	v_mfma_f32_16x16x32_bf16 v[64:67], v[164:167], v[196:199], v[64:67]
	v_mfma_f32_16x16x32_bf16 v[56:59], v[156:159], v[204:207], v[56:59]
	v_mfma_f32_16x16x32_bf16 v[52:55], v[164:167], v[204:207], v[52:55]
	v_mfma_f32_16x16x32_bf16 v[44:47], v[156:159], v[212:215], v[44:47]
	v_mfma_f32_16x16x32_bf16 v[40:43], v[164:167], v[212:215], v[40:43]
	s_setprio 0
	s_setprio 3
	v_mfma_f32_16x16x32_bf16 v[124:127], v[168:171], v[184:187], v[124:127]
	v_mfma_f32_16x16x32_bf16 v[120:123], v[176:179], v[184:187], v[120:123]
	v_mfma_f32_16x16x32_bf16 v[116:119], v[168:171], v[192:195], v[116:119]
	v_mfma_f32_16x16x32_bf16 v[112:115], v[176:179], v[192:195], v[112:115]
	v_mfma_f32_16x16x32_bf16 v[108:111], v[168:171], v[200:203], v[108:111]
	v_mfma_f32_16x16x32_bf16 v[104:107], v[176:179], v[200:203], v[104:107]
	v_mfma_f32_16x16x32_bf16 v[100:103], v[168:171], v[208:211], v[100:103]
	v_mfma_f32_16x16x32_bf16 v[96:99], v[176:179], v[208:211], v[96:99]
	v_mfma_f32_16x16x32_bf16 v[124:127], v[172:175], v[188:191], v[124:127]
	v_mfma_f32_16x16x32_bf16 v[120:123], v[180:183], v[188:191], v[120:123]
	v_mfma_f32_16x16x32_bf16 v[116:119], v[172:175], v[196:199], v[116:119]
	v_mfma_f32_16x16x32_bf16 v[112:115], v[180:183], v[196:199], v[112:115]
	v_mfma_f32_16x16x32_bf16 v[108:111], v[172:175], v[204:207], v[108:111]
	v_mfma_f32_16x16x32_bf16 v[104:107], v[180:183], v[204:207], v[104:107]
	v_mfma_f32_16x16x32_bf16 v[100:103], v[172:175], v[212:215], v[100:103]
	s_setprio 3
	s_barrier
	v_mfma_f32_16x16x32_bf16 v[96:99], v[180:183], v[212:215], v[96:99]
	s_setprio 0
	s_add_i32 s90, s77, s67
	v_lshl_add_u64 v[216:217], s[60:61], 0, v[130:131]
	s_mov_b32 m0, s90
	ds_read_b128 v[184:187], v154 offset:16384
	ds_read_b128 v[188:191], v154 offset:17408
	ds_read_b128 v[192:195], v154 offset:18432
	ds_read_b128 v[196:199], v154 offset:19456
	ds_read_b128 v[200:203], v154 offset:20480
	ds_read_b128 v[204:207], v154 offset:21504
	ds_read_b128 v[208:211], v154 offset:22528
	ds_read_b128 v[212:215], v154 offset:23552
	global_load_lds_dwordx4 v[216:217], off
	s_add_i32 m0, s90, 0x2000
	s_add_u32 s90, s60, 0x100000
	v_lshl_add_u64 v[218:219], s[60:61], 0, v[134:135]
	s_addc_u32 s91, s61, 0
	s_add_i32 s92, s78, s67
	global_load_lds_dwordx4 v[218:219], off
	v_lshl_add_u64 v[220:221], s[90:91], 0, v[130:131]
	s_mov_b32 m0, s92
	v_lshl_add_u64 v[222:223], s[62:63], 0, v[132:133]
	global_load_lds_dwordx4 v[220:221], off
	v_lshl_add_u64 v[220:221], s[90:91], 0, v[134:135]
	s_add_i32 m0, s92, 0x2000
	s_nop 0
	global_load_lds_dwordx4 v[220:221], off
	v_lshl_add_u64 v[220:221], s[62:63], 0, v[128:129]
	s_mov_b32 m0, s68
	s_nop 0
	global_load_lds_dwordx4 v[220:221], off
	s_mov_b32 m0, s69
	s_nop 0
	global_load_lds_dwordx4 v[222:223], off
	s_waitcnt vmcnt(8)
	s_waitcnt lgkmcnt(0)
	s_barrier
; #define PG8_STAGE(bufoff, gbase, voff) do { _Pragma("unroll") for (int _i = 0; _i < 2; ++_i) \
;         __builtin_amdgcn_global_load_lds((const unsigned*)((const char*)(gbase) + (voff)[_i]), (PG8_LAS unsigned*)(lds + (bufoff) + ldsw + _i * 8192), 16, 0, 0); } while (0)
; #define PG8_LDA(dst, b, h) do { _Pragma("unroll") for (int m = 0; m < 4; ++m) _Pragma("unroll") for (int k = 0; k < 2; ++k) dst[m][k] = *(const PG8_LAS bf16x8*)(lds + PG8_SA(b, h) + aoff + m * 2048 + k * 1024); } while (0)
; #define PG8_LDB(dst, b, h) do { _Pragma("unroll") for (int n = 0; n < 2; ++n) _Pragma("unroll") for (int k = 0; k < 2; ++k) dst[n][k] = *(const PG8_LAS bf16x8*)(lds + PG8_SB(b, h) + boff + n * 2048 + k * 1024); } while (0)
; #define PG8_MMA(ai, bj, At, Bt) do { __builtin_amdgcn_s_setprio(1); _Pragma("unroll") for (int m = 0; m < 4; ++m) _Pragma("unroll") for (int n = 0; n < 2; ++n) _Pragma("unroll") for (int k = 0; k < 2; ++k) \
;         acc[ai][bj][m][n] = __builtin_amdgcn_mfma_f32_16x16x32_bf16(Bt[n][k], At[m][k], acc[ai][bj][m][n], 0, 0, 0); __builtin_amdgcn_s_setprio(0); } while (0)
; #define PG8_WAIT_V(n) asm volatile("s_waitcnt vmcnt(" #n ")" ::: "memory")
; #define PG8_WAIT_L(n) asm volatile("s_waitcnt lgkmcnt(" #n ")" ::: "memory")
; #define PG8_BAR __builtin_amdgcn_s_barrier()
; #define PG8_SCHED __builtin_amdgcn_sched_barrier(0)
; template <class Epi, class Sched, bool ALIGN_EPI = false, bool SP2 = false>
; __device__ __forceinline__ void gemm_phase(PG8_LAS unsigned char* lds, const Gemm g, const Sched& S, const Epi& E, const int wv  ) {
;     ...
;             PG8_LDA(At, 0, 1); PG8_STAGE(PG8_SB(0, 0), b2, voffB); PG8_STAGE(PG8_SB(0, 1), b2 + hstepB, voffB); PG8_STAGE(PG8_SA(0, 0), a2, voffA);
;             PG8_WAIT_V(8); PG8_WAIT_L(0); PG8_BAR; PG8_MMA(1, 0, At, B0); PG8_MMA(1, 1, At, B1); PG8_BAR; PG8_SCHED;
;             PG8_LDB(B0, 1, 0); PG8_LDB(B1, 1, 1); PG8_SCHED; PG8_LDA(At, 1, 0); PG8_STAGE(PG8_SA(0, 1), a2 + hstepA, voffA);
;             PG8_WAIT_V(8); PG8_WAIT_L(0); PG8_BAR; PG8_MMA(0, 0, At, B0); PG8_MMA(0, 1, At, B1); PG8_BAR; PG8_SCHED;
	s_setprio 3
	s_waitcnt lgkmcnt(0)
	v_mfma_f32_16x16x32_bf16 v[28:31], v[146:149], v[184:187], v[28:31]
	v_mfma_f32_16x16x32_bf16 v[24:27], v[160:163], v[184:187], v[24:27]
	v_mfma_f32_16x16x32_bf16 v[20:23], v[146:149], v[192:195], v[20:23]
	v_mfma_f32_16x16x32_bf16 v[16:19], v[160:163], v[192:195], v[16:19]
	v_mfma_f32_16x16x32_bf16 v[12:15], v[146:149], v[200:203], v[12:15]
	v_mfma_f32_16x16x32_bf16 v[8:11], v[160:163], v[200:203], v[8:11]
	v_mfma_f32_16x16x32_bf16 v[4:7], v[146:149], v[208:211], v[4:7]
	v_mfma_f32_16x16x32_bf16 v[0:3], v[160:163], v[208:211], v[0:3]
	v_mfma_f32_16x16x32_bf16 v[28:31], v[156:159], v[188:191], v[28:31]
	v_mfma_f32_16x16x32_bf16 v[24:27], v[164:167], v[188:191], v[24:27]
	v_mfma_f32_16x16x32_bf16 v[20:23], v[156:159], v[196:199], v[20:23]
	v_mfma_f32_16x16x32_bf16 v[16:19], v[164:167], v[196:199], v[16:19]
	v_mfma_f32_16x16x32_bf16 v[12:15], v[156:159], v[204:207], v[12:15]
	v_mfma_f32_16x16x32_bf16 v[8:11], v[164:167], v[204:207], v[8:11]
	v_mfma_f32_16x16x32_bf16 v[4:7], v[156:159], v[212:215], v[4:7]
	v_mfma_f32_16x16x32_bf16 v[0:3], v[164:167], v[212:215], v[0:3]
	s_setprio 0
	s_setprio 3
	v_mfma_f32_16x16x32_bf16 v[92:95], v[168:171], v[184:187], v[92:95]
	v_mfma_f32_16x16x32_bf16 v[88:91], v[176:179], v[184:187], v[88:91]
	v_mfma_f32_16x16x32_bf16 v[84:87], v[168:171], v[192:195], v[84:87]
	v_mfma_f32_16x16x32_bf16 v[80:83], v[176:179], v[192:195], v[80:83]
	v_mfma_f32_16x16x32_bf16 v[60:63], v[168:171], v[200:203], v[60:63]
	v_mfma_f32_16x16x32_bf16 v[48:51], v[176:179], v[200:203], v[48:51]
	v_mfma_f32_16x16x32_bf16 v[36:39], v[168:171], v[208:211], v[36:39]
	v_mfma_f32_16x16x32_bf16 v[32:35], v[176:179], v[208:211], v[32:35]
	v_mfma_f32_16x16x32_bf16 v[92:95], v[172:175], v[188:191], v[92:95]
	v_mfma_f32_16x16x32_bf16 v[88:91], v[180:183], v[188:191], v[88:91]
	v_mfma_f32_16x16x32_bf16 v[84:87], v[172:175], v[196:199], v[84:87]
	v_mfma_f32_16x16x32_bf16 v[80:83], v[180:183], v[196:199], v[80:83]
	v_mfma_f32_16x16x32_bf16 v[60:63], v[172:175], v[204:207], v[60:63]
	v_mfma_f32_16x16x32_bf16 v[48:51], v[180:183], v[204:207], v[48:51]
	v_mfma_f32_16x16x32_bf16 v[36:39], v[172:175], v[212:215], v[36:39]
	s_setprio 3
	s_barrier
	v_mfma_f32_16x16x32_bf16 v[32:35], v[180:183], v[212:215], v[32:35]
	s_setprio 0
	s_add_i32 s90, 0, 0x18000
	v_add_u32_e32 v155, s90, v150
	s_add_i32 s91, 0, 0x1c000
	ds_read_b128 v[146:149], v155
	ds_read_b128 v[156:159], v155 offset:1024
	ds_read_b128 v[160:163], v155 offset:2048
	ds_read_b128 v[164:167], v155 offset:3072
	v_add_u32_e32 v155, s91, v150
	ds_read_b128 v[168:171], v155
	ds_read_b128 v[172:175], v155 offset:1024
	ds_read_b128 v[176:179], v155 offset:2048
	ds_read_b128 v[180:183], v155 offset:3072
	s_add_u32 s62, s62, 0x100000
	s_addc_u32 s63, s63, 0
	s_mov_b32 m0, s70
	v_lshl_add_u64 v[224:225], s[62:63], 0, v[128:129]
	ds_read_b128 v[184:187], v154 offset:32768
	ds_read_b128 v[188:191], v154 offset:33792
	ds_read_b128 v[192:195], v154 offset:34816
	ds_read_b128 v[196:199], v154 offset:35840
	ds_read_b128 v[200:203], v154 offset:36864
	ds_read_b128 v[204:207], v154 offset:37888
	ds_read_b128 v[208:211], v154 offset:38912
	ds_read_b128 v[212:215], v154 offset:39936
	global_load_lds_dwordx4 v[224:225], off
	v_lshl_add_u64 v[224:225], s[62:63], 0, v[132:133]
	s_mov_b32 m0, s71
	s_nop 0
	global_load_lds_dwordx4 v[224:225], off
	s_waitcnt vmcnt(8)
	s_waitcnt lgkmcnt(0)
	s_barrier
	s_setprio 3
	s_waitcnt lgkmcnt(0)
	v_mfma_f32_16x16x32_bf16 v[76:79], v[146:149], v[184:187], v[76:79]
	v_mfma_f32_16x16x32_bf16 v[72:75], v[160:163], v[184:187], v[72:75]
	v_mfma_f32_16x16x32_bf16 v[68:71], v[146:149], v[192:195], v[68:71]
	v_mfma_f32_16x16x32_bf16 v[64:67], v[160:163], v[192:195], v[64:67]
	v_mfma_f32_16x16x32_bf16 v[56:59], v[146:149], v[200:203], v[56:59]
	v_mfma_f32_16x16x32_bf16 v[52:55], v[160:163], v[200:203], v[52:55]
	v_mfma_f32_16x16x32_bf16 v[44:47], v[146:149], v[208:211], v[44:47]
	v_mfma_f32_16x16x32_bf16 v[40:43], v[160:163], v[208:211], v[40:43]
	v_mfma_f32_16x16x32_bf16 v[76:79], v[156:159], v[188:191], v[76:79]
	v_mfma_f32_16x16x32_bf16 v[72:75], v[164:167], v[188:191], v[72:75]
	v_mfma_f32_16x16x32_bf16 v[68:71], v[156:159], v[196:199], v[68:71]
	v_mfma_f32_16x16x32_bf16 v[64:67], v[164:167], v[196:199], v[64:67]
	v_mfma_f32_16x16x32_bf16 v[56:59], v[156:159], v[204:207], v[56:59]
	v_mfma_f32_16x16x32_bf16 v[52:55], v[164:167], v[204:207], v[52:55]
	v_mfma_f32_16x16x32_bf16 v[44:47], v[156:159], v[212:215], v[44:47]
	v_mfma_f32_16x16x32_bf16 v[40:43], v[164:167], v[212:215], v[40:43]
	s_setprio 0
	s_setprio 3
	v_mfma_f32_16x16x32_bf16 v[124:127], v[168:171], v[184:187], v[124:127]
	v_mfma_f32_16x16x32_bf16 v[120:123], v[176:179], v[184:187], v[120:123]
	v_mfma_f32_16x16x32_bf16 v[116:119], v[168:171], v[192:195], v[116:119]
	v_mfma_f32_16x16x32_bf16 v[112:115], v[176:179], v[192:195], v[112:115]
	v_mfma_f32_16x16x32_bf16 v[108:111], v[168:171], v[200:203], v[108:111]
	v_mfma_f32_16x16x32_bf16 v[104:107], v[176:179], v[200:203], v[104:107]
	v_mfma_f32_16x16x32_bf16 v[100:103], v[168:171], v[208:211], v[100:103]
	v_mfma_f32_16x16x32_bf16 v[96:99], v[176:179], v[208:211], v[96:99]
	v_mfma_f32_16x16x32_bf16 v[124:127], v[172:175], v[188:191], v[124:127]
	v_mfma_f32_16x16x32_bf16 v[120:123], v[180:183], v[188:191], v[120:123]
	v_mfma_f32_16x16x32_bf16 v[116:119], v[172:175], v[196:199], v[116:119]
	v_mfma_f32_16x16x32_bf16 v[112:115], v[180:183], v[196:199], v[112:115]
	v_mfma_f32_16x16x32_bf16 v[108:111], v[172:175], v[204:207], v[108:111]
	v_mfma_f32_16x16x32_bf16 v[104:107], v[180:183], v[204:207], v[104:107]
	v_mfma_f32_16x16x32_bf16 v[100:103], v[172:175], v[212:215], v[100:103]
	s_setprio 3
	s_barrier
; #define PG8_STAGE(bufoff, gbase, voff) do { _Pragma("unroll") for (int _i = 0; _i < 2; ++_i) \
;         __builtin_amdgcn_global_load_lds((const unsigned*)((const char*)(gbase) + (voff)[_i]), (PG8_LAS unsigned*)(lds + (bufoff) + ldsw + _i * 8192), 16, 0, 0); } while (0)
; #define PG8_LDA(dst, b, h) do { _Pragma("unroll") for (int m = 0; m < 4; ++m) _Pragma("unroll") for (int k = 0; k < 2; ++k) dst[m][k] = *(const PG8_LAS bf16x8*)(lds + PG8_SA(b, h) + aoff + m * 2048 + k * 1024); } while (0)
; #define PG8_MMA(ai, bj, At, Bt) do { __builtin_amdgcn_s_setprio(1); _Pragma("unroll") for (int m = 0; m < 4; ++m) _Pragma("unroll") for (int n = 0; n < 2; ++n) _Pragma("unroll") for (int k = 0; k < 2; ++k) \
;         acc[ai][bj][m][n] = __builtin_amdgcn_mfma_f32_16x16x32_bf16(Bt[n][k], At[m][k], acc[ai][bj][m][n], 0, 0, 0); __builtin_amdgcn_s_setprio(0); } while (0)
; #define PG8_WAIT_V(n) asm volatile("s_waitcnt vmcnt(" #n ")" ::: "memory")
; #define PG8_WAIT_L(n) asm volatile("s_waitcnt lgkmcnt(" #n ")" ::: "memory")
; #define PG8_BAR __builtin_amdgcn_s_barrier()
; #define PG8_SCHED __builtin_amdgcn_sched_barrier(0)
; template <class Epi, class Sched, bool ALIGN_EPI = false, bool SP2 = false>
; __device__ __forceinline__ void gemm_phase(PG8_LAS unsigned char* lds, const Gemm g, const Sched& S, const Epi& E, const int wv  ) {
;     ...
;             PG8_LDA(At, 1, 1); PG8_STAGE(PG8_SB(1, 0), b3, voffB); PG8_STAGE(PG8_SB(1, 1), b3 + hstepB, voffB); PG8_STAGE(PG8_SA(1, 0), a3, voffA);
;             PG8_WAIT_V(8); PG8_WAIT_L(0); PG8_BAR; PG8_MMA(1, 0, At, B0); PG8_MMA(1, 1, At, B1); PG8_BAR; PG8_SCHED;
;     ...
;         if constexpr (ALIGN_EPI) { if (wr == 0) PG8_BAR; }
	v_mfma_f32_16x16x32_bf16 v[96:99], v[180:183], v[212:215], v[96:99]
	s_setprio 0
	s_add_i32 s62, s90, s67
	v_lshl_add_u64 v[216:217], v[216:217], 0, s[12:13]
	s_mov_b32 m0, s62
	ds_read_b128 v[184:187], v154 offset:49152
	ds_read_b128 v[188:191], v154 offset:50176
	ds_read_b128 v[192:195], v154 offset:51200
	ds_read_b128 v[196:199], v154 offset:52224
	ds_read_b128 v[200:203], v154 offset:53248
	ds_read_b128 v[204:207], v154 offset:54272
	ds_read_b128 v[208:211], v154 offset:55296
	ds_read_b128 v[212:215], v154 offset:56320
	global_load_lds_dwordx4 v[216:217], off
	s_add_i32 m0, s62, 0x2000
	s_add_u32 s60, s60, 0x100080
	v_lshl_add_u64 v[216:217], v[218:219], 0, s[12:13]
	s_addc_u32 s61, s61, 0
	s_add_i32 s62, s91, s67
	global_load_lds_dwordx4 v[216:217], off
	v_lshl_add_u64 v[216:217], s[60:61], 0, v[130:131]
	s_mov_b32 m0, s62
	s_nop 0
	global_load_lds_dwordx4 v[216:217], off
	v_lshl_add_u64 v[216:217], s[60:61], 0, v[134:135]
	s_add_i32 m0, s62, 0x2000
	s_nop 0
	global_load_lds_dwordx4 v[216:217], off
	v_lshl_add_u64 v[216:217], v[220:221], 0, s[12:13]
	s_mov_b32 m0, s74
	s_nop 0
	global_load_lds_dwordx4 v[216:217], off
	v_lshl_add_u64 v[216:217], v[222:223], 0, s[12:13]
	s_mov_b32 m0, s75
	s_nop 0
	global_load_lds_dwordx4 v[216:217], off
	s_waitcnt vmcnt(8)
	s_waitcnt lgkmcnt(0)
	s_barrier
	s_setprio 3
	s_waitcnt lgkmcnt(0)
	v_mfma_f32_16x16x32_bf16 v[28:31], v[146:149], v[184:187], v[28:31]
	v_mfma_f32_16x16x32_bf16 v[24:27], v[160:163], v[184:187], v[24:27]
	v_mfma_f32_16x16x32_bf16 v[20:23], v[146:149], v[192:195], v[20:23]
	v_mfma_f32_16x16x32_bf16 v[16:19], v[160:163], v[192:195], v[16:19]
	v_mfma_f32_16x16x32_bf16 v[12:15], v[146:149], v[200:203], v[12:15]
	v_mfma_f32_16x16x32_bf16 v[8:11], v[160:163], v[200:203], v[8:11]
	v_mfma_f32_16x16x32_bf16 v[4:7], v[146:149], v[208:211], v[4:7]
	v_mfma_f32_16x16x32_bf16 v[0:3], v[160:163], v[208:211], v[0:3]
	v_mfma_f32_16x16x32_bf16 v[28:31], v[156:159], v[188:191], v[28:31]
	v_mfma_f32_16x16x32_bf16 v[24:27], v[164:167], v[188:191], v[24:27]
	v_mfma_f32_16x16x32_bf16 v[20:23], v[156:159], v[196:199], v[20:23]
	v_mfma_f32_16x16x32_bf16 v[16:19], v[164:167], v[196:199], v[16:19]
	v_mfma_f32_16x16x32_bf16 v[12:15], v[156:159], v[204:207], v[12:15]
	v_mfma_f32_16x16x32_bf16 v[8:11], v[164:167], v[204:207], v[8:11]
	v_mfma_f32_16x16x32_bf16 v[4:7], v[156:159], v[212:215], v[4:7]
	v_mfma_f32_16x16x32_bf16 v[0:3], v[164:167], v[212:215], v[0:3]
	s_setprio 0
	s_setprio 3
	v_mfma_f32_16x16x32_bf16 v[92:95], v[168:171], v[184:187], v[92:95]
	v_mfma_f32_16x16x32_bf16 v[88:91], v[176:179], v[184:187], v[88:91]
	v_mfma_f32_16x16x32_bf16 v[84:87], v[168:171], v[192:195], v[84:87]
	v_mfma_f32_16x16x32_bf16 v[80:83], v[176:179], v[192:195], v[80:83]
	v_mfma_f32_16x16x32_bf16 v[60:63], v[168:171], v[200:203], v[60:63]
	v_mfma_f32_16x16x32_bf16 v[48:51], v[176:179], v[200:203], v[48:51]
	v_mfma_f32_16x16x32_bf16 v[36:39], v[168:171], v[208:211], v[36:39]
	v_mfma_f32_16x16x32_bf16 v[32:35], v[176:179], v[208:211], v[32:35]
	v_mfma_f32_16x16x32_bf16 v[92:95], v[172:175], v[188:191], v[92:95]
	v_mfma_f32_16x16x32_bf16 v[88:91], v[180:183], v[188:191], v[88:91]
	v_mfma_f32_16x16x32_bf16 v[84:87], v[172:175], v[196:199], v[84:87]
	v_mfma_f32_16x16x32_bf16 v[80:83], v[180:183], v[196:199], v[80:83]
	v_mfma_f32_16x16x32_bf16 v[60:63], v[172:175], v[204:207], v[60:63]
	v_mfma_f32_16x16x32_bf16 v[48:51], v[180:183], v[204:207], v[48:51]
	v_mfma_f32_16x16x32_bf16 v[36:39], v[172:175], v[212:215], v[36:39]
	s_setprio 3
	s_barrier
	v_mfma_f32_16x16x32_bf16 v[32:35], v[180:183], v[212:215], v[32:35]
	s_setprio 0
	s_add_i32 s87, s87, 2
	s_add_u32 s58, s58, 0x100
	s_addc_u32 s59, s59, 0
	s_add_u32 s85, s85, 0x100
	s_addc_u32 s86, s86, 0
	s_cmp_gt_u32 s87, 61
	s_cbranch_scc0 .LBB0_706
	s_and_b64 vcc, exec, s[14:15]
	s_cbranch_vccz .LBB0_709
	s_barrier

; #define PG8_STAGE(bufoff, gbase, voff) do { _Pragma("unroll") for (int _i = 0; _i < 2; ++_i) \
;         __builtin_amdgcn_global_load_lds((const unsigned*)((const char*)(gbase) + (voff)[_i]), (PG8_LAS unsigned*)(lds + (bufoff) + ldsw + _i * 8192), 16, 0, 0); } while (0)
; #define PG8_LDA(dst, b, h) do { _Pragma("unroll") for (int m = 0; m < 4; ++m) _Pragma("unroll") for (int k = 0; k < 2; ++k) dst[m][k] = *(const PG8_LAS bf16x8*)(lds + PG8_SA(b, h) + aoff + m * 2048 + k * 1024); } while (0)
; #define PG8_LDB(dst, b, h) do { _Pragma("unroll") for (int n = 0; n < 2; ++n) _Pragma("unroll") for (int k = 0; k < 2; ++k) dst[n][k] = *(const PG8_LAS bf16x8*)(lds + PG8_SB(b, h) + boff + n * 2048 + k * 1024); } while (0)
; #define PG8_MMA(ai, bj, At, Bt) do { __builtin_amdgcn_s_setprio(1); _Pragma("unroll") for (int m = 0; m < 4; ++m) _Pragma("unroll") for (int n = 0; n < 2; ++n) _Pragma("unroll") for (int k = 0; k < 2; ++k) \
;         acc[ai][bj][m][n] = __builtin_amdgcn_mfma_f32_16x16x32_bf16(Bt[n][k], At[m][k], acc[ai][bj][m][n], 0, 0, 0); __builtin_amdgcn_s_setprio(0); } while (0)
; #define PG8_WAIT_V(n) asm volatile("s_waitcnt vmcnt(" #n ")" ::: "memory")
; #define PG8_WAIT_L(n) asm volatile("s_waitcnt lgkmcnt(" #n ")" ::: "memory")
; #define PG8_BAR __builtin_amdgcn_s_barrier()
; template <class Epi, class Sched, bool ALIGN_EPI = false, bool SP2 = false>
; __device__ __forceinline__ void gemm_phase(PG8_LAS unsigned char* lds, const Gemm g, const Sched& S, const Epi& E, const int wv  ) {
;     ...
;             const char* a1 = cA + (size_t)(t + 1) * kstep;
;             const char* a2 = last ? nA : cA + (size_t)(t + 2) * kstep; const char* b2 = last ? nB : cB + (size_t)(t + 2) * kstep;
;             const char* a3 = a2 + kstep; const char* b3 = b2 + kstep;
;             if (last && has_next) S.a_ready(nxt);
;             if constexpr (SP2) {
;             PG8_LDB(B0, 0, 0); PG8_LDB(B1, 0, 1); PG8_SCHED; PG8_LDA(At, 0, 0); PG8_STAGE(PG8_SA(1, 1), a1 + hstepA, voffA);
;             PG8_WAIT_V(8); PG8_WAIT_L(0); PG8_BAR; PG8_MMA(0, 0, At, B0); PG8_MMA(0, 1, At, B1); PG8_BAR; PG8_SCHED;
;             PG8_LDA(At, 0, 1); PG8_STAGE(PG8_SB(0, 0), b2, voffB); PG8_STAGE(PG8_SB(0, 1), b2 + hstepB, voffB); PG8_STAGE(PG8_SA(0, 0), a2, voffA);
;             PG8_WAIT_V(8); PG8_WAIT_L(0); PG8_BAR; PG8_MMA(1, 0, At, B0); PG8_MMA(1, 1, At, B1); PG8_BAR; PG8_SCHED;
.LBB0_850:
	ds_read_b128 v[146:149], v152
	ds_read_b128 v[156:159], v152 offset:1024
	ds_read_b128 v[160:163], v152 offset:2048
	ds_read_b128 v[164:167], v152 offset:3072
	ds_read_b128 v[168:171], v153
	ds_read_b128 v[172:175], v153 offset:1024
	ds_read_b128 v[176:179], v153 offset:2048
	ds_read_b128 v[180:183], v153 offset:3072
	s_add_u32 s60, s58, 0xfff00080
	s_addc_u32 s61, s59, -1
	s_cmp_eq_u32 s92, 60
	s_cselect_b32 s63, s51, s61
	s_cselect_b32 s62, s86, s60
	s_cselect_b32 s61, s49, s91
	s_cselect_b32 s60, s87, s90
	v_lshl_add_u64 v[216:217], s[58:59], 0, v[138:139]
	s_add_i32 m0, s71, 0xc000
	ds_read_b128 v[184:187], v154
	ds_read_b128 v[188:191], v154 offset:1024
	ds_read_b128 v[192:195], v154 offset:2048
	ds_read_b128 v[196:199], v154 offset:3072
	ds_read_b128 v[200:203], v154 offset:4096
	ds_read_b128 v[204:207], v154 offset:5120
	ds_read_b128 v[208:211], v154 offset:6144
	ds_read_b128 v[212:215], v154 offset:7168
	global_load_lds_dwordx4 v[216:217], off
	v_lshl_add_u64 v[216:217], s[58:59], 0, v[140:141]
	s_add_i32 m0, s71, 0xe000
	s_nop 0
	global_load_lds_dwordx4 v[216:217], off
	s_waitcnt vmcnt(8)
	s_waitcnt lgkmcnt(0)
	s_barrier
	s_setprio 3
	s_waitcnt lgkmcnt(0)
	v_mfma_f32_16x16x32_bf16 v[76:79], v[146:149], v[184:187], v[76:79]
	v_mfma_f32_16x16x32_bf16 v[72:75], v[160:163], v[184:187], v[72:75]
	v_mfma_f32_16x16x32_bf16 v[68:71], v[146:149], v[192:195], v[68:71]
	v_mfma_f32_16x16x32_bf16 v[64:67], v[160:163], v[192:195], v[64:67]
	v_mfma_f32_16x16x32_bf16 v[56:59], v[146:149], v[200:203], v[56:59]
	v_mfma_f32_16x16x32_bf16 v[52:55], v[160:163], v[200:203], v[52:55]
	v_mfma_f32_16x16x32_bf16 v[44:47], v[146:149], v[208:211], v[44:47]
	v_mfma_f32_16x16x32_bf16 v[40:43], v[160:163], v[208:211], v[40:43]
	v_mfma_f32_16x16x32_bf16 v[76:79], v[156:159], v[188:191], v[76:79]
	v_mfma_f32_16x16x32_bf16 v[72:75], v[164:167], v[188:191], v[72:75]
	v_mfma_f32_16x16x32_bf16 v[68:71], v[156:159], v[196:199], v[68:71]
	v_mfma_f32_16x16x32_bf16 v[64:67], v[164:167], v[196:199], v[64:67]
	v_mfma_f32_16x16x32_bf16 v[56:59], v[156:159], v[204:207], v[56:59]
	v_mfma_f32_16x16x32_bf16 v[52:55], v[164:167], v[204:207], v[52:55]
	v_mfma_f32_16x16x32_bf16 v[44:47], v[156:159], v[212:215], v[44:47]
	v_mfma_f32_16x16x32_bf16 v[40:43], v[164:167], v[212:215], v[40:43]
	s_setprio 0
	s_setprio 3
	v_mfma_f32_16x16x32_bf16 v[124:127], v[168:171], v[184:187], v[124:127]
	v_mfma_f32_16x16x32_bf16 v[120:123], v[176:179], v[184:187], v[120:123]
	v_mfma_f32_16x16x32_bf16 v[116:119], v[168:171], v[192:195], v[116:119]
	v_mfma_f32_16x16x32_bf16 v[112:115], v[176:179], v[192:195], v[112:115]
	v_mfma_f32_16x16x32_bf16 v[108:111], v[168:171], v[200:203], v[108:111]
	v_mfma_f32_16x16x32_bf16 v[104:107], v[176:179], v[200:203], v[104:107]
	v_mfma_f32_16x16x32_bf16 v[100:103], v[168:171], v[208:211], v[100:103]
	v_mfma_f32_16x16x32_bf16 v[96:99], v[176:179], v[208:211], v[96:99]
	v_mfma_f32_16x16x32_bf16 v[124:127], v[172:175], v[188:191], v[124:127]
	v_mfma_f32_16x16x32_bf16 v[120:123], v[180:183], v[188:191], v[120:123]
	v_mfma_f32_16x16x32_bf16 v[116:119], v[172:175], v[196:199], v[116:119]
	v_mfma_f32_16x16x32_bf16 v[112:115], v[180:183], v[196:199], v[112:115]
	v_mfma_f32_16x16x32_bf16 v[108:111], v[172:175], v[204:207], v[108:111]
	v_mfma_f32_16x16x32_bf16 v[104:107], v[180:183], v[204:207], v[104:107]
	v_mfma_f32_16x16x32_bf16 v[100:103], v[172:175], v[212:215], v[100:103]
	s_setprio 3
	s_barrier
	v_mfma_f32_16x16x32_bf16 v[96:99], v[180:183], v[212:215], v[96:99]
	s_setprio 0
	s_add_i32 s93, s80, s70
	v_lshl_add_u64 v[216:217], s[60:61], 0, v[130:131]
	s_mov_b32 m0, s93
	ds_read_b128 v[184:187], v154 offset:16384
	ds_read_b128 v[188:191], v154 offset:17408
	ds_read_b128 v[192:195], v154 offset:18432
	ds_read_b128 v[196:199], v154 offset:19456
	ds_read_b128 v[200:203], v154 offset:20480
	ds_read_b128 v[204:207], v154 offset:21504
	ds_read_b128 v[208:211], v154 offset:22528
	ds_read_b128 v[212:215], v154 offset:23552
	global_load_lds_dwordx4 v[216:217], off
	s_add_i32 m0, s93, 0x2000
	s_add_u32 s94, s60, 0x100000
	v_lshl_add_u64 v[218:219], s[60:61], 0, v[134:135]
	s_addc_u32 s95, s61, 0
	s_add_i32 s93, s81, s70
	global_load_lds_dwordx4 v[218:219], off
	v_lshl_add_u64 v[220:221], s[94:95], 0, v[130:131]
	s_mov_b32 m0, s93
	v_lshl_add_u64 v[222:223], s[62:63], 0, v[132:133]
	global_load_lds_dwordx4 v[220:221], off
	v_lshl_add_u64 v[220:221], s[94:95], 0, v[134:135]
	s_add_i32 m0, s93, 0x2000
	s_nop 0
	global_load_lds_dwordx4 v[220:221], off
	v_lshl_add_u64 v[220:221], s[62:63], 0, v[128:129]
	s_mov_b32 m0, s71
	s_nop 0
	global_load_lds_dwordx4 v[220:221], off
	s_mov_b32 m0, s72
	s_nop 0
	global_load_lds_dwordx4 v[222:223], off
	s_waitcnt vmcnt(8)
	s_waitcnt lgkmcnt(0)
	s_barrier
; #define PG8_STAGE(bufoff, gbase, voff) do { _Pragma("unroll") for (int _i = 0; _i < 2; ++_i) \
;         __builtin_amdgcn_global_load_lds((const unsigned*)((const char*)(gbase) + (voff)[_i]), (PG8_LAS unsigned*)(lds + (bufoff) + ldsw + _i * 8192), 16, 0, 0); } while (0)
; #define PG8_LDA(dst, b, h) do { _Pragma("unroll") for (int m = 0; m < 4; ++m) _Pragma("unroll") for (int k = 0; k < 2; ++k) dst[m][k] = *(const PG8_LAS bf16x8*)(lds + PG8_SA(b, h) + aoff + m * 2048 + k * 1024); } while (0)
; #define PG8_LDB(dst, b, h) do { _Pragma("unroll") for (int n = 0; n < 2; ++n) _Pragma("unroll") for (int k = 0; k < 2; ++k) dst[n][k] = *(const PG8_LAS bf16x8*)(lds + PG8_SB(b, h) + boff + n * 2048 + k * 1024); } while (0)
; #define PG8_MMA(ai, bj, At, Bt) do { __builtin_amdgcn_s_setprio(1); _Pragma("unroll") for (int m = 0; m < 4; ++m) _Pragma("unroll") for (int n = 0; n < 2; ++n) _Pragma("unroll") for (int k = 0; k < 2; ++k) \
;         acc[ai][bj][m][n] = __builtin_amdgcn_mfma_f32_16x16x32_bf16(Bt[n][k], At[m][k], acc[ai][bj][m][n], 0, 0, 0); __builtin_amdgcn_s_setprio(0); } while (0)
; #define PG8_WAIT_V(n) asm volatile("s_waitcnt vmcnt(" #n ")" ::: "memory")
; #define PG8_WAIT_L(n) asm volatile("s_waitcnt lgkmcnt(" #n ")" ::: "memory")
; #define PG8_BAR __builtin_amdgcn_s_barrier()
; #define PG8_SCHED __builtin_amdgcn_sched_barrier(0)
; template <class Epi, class Sched, bool ALIGN_EPI = false, bool SP2 = false>
; __device__ __forceinline__ void gemm_phase(PG8_LAS unsigned char* lds, const Gemm g, const Sched& S, const Epi& E, const int wv  ) {
;     ...
;             PG8_LDA(At, 0, 1); PG8_STAGE(PG8_SB(0, 0), b2, voffB); PG8_STAGE(PG8_SB(0, 1), b2 + hstepB, voffB); PG8_STAGE(PG8_SA(0, 0), a2, voffA);
;             PG8_WAIT_V(8); PG8_WAIT_L(0); PG8_BAR; PG8_MMA(1, 0, At, B0); PG8_MMA(1, 1, At, B1); PG8_BAR; PG8_SCHED;
;             PG8_LDB(B0, 1, 0); PG8_LDB(B1, 1, 1); PG8_SCHED; PG8_LDA(At, 1, 0); PG8_STAGE(PG8_SA(0, 1), a2 + hstepA, voffA);
;             PG8_WAIT_V(8); PG8_WAIT_L(0); PG8_BAR; PG8_MMA(0, 0, At, B0); PG8_MMA(0, 1, At, B1); PG8_BAR; PG8_SCHED;
	s_setprio 3
	s_waitcnt lgkmcnt(0)
	v_mfma_f32_16x16x32_bf16 v[28:31], v[146:149], v[184:187], v[28:31]
	v_mfma_f32_16x16x32_bf16 v[24:27], v[160:163], v[184:187], v[24:27]
	v_mfma_f32_16x16x32_bf16 v[20:23], v[146:149], v[192:195], v[20:23]
	v_mfma_f32_16x16x32_bf16 v[16:19], v[160:163], v[192:195], v[16:19]
	v_mfma_f32_16x16x32_bf16 v[12:15], v[146:149], v[200:203], v[12:15]
	v_mfma_f32_16x16x32_bf16 v[8:11], v[160:163], v[200:203], v[8:11]
	v_mfma_f32_16x16x32_bf16 v[4:7], v[146:149], v[208:211], v[4:7]
	v_mfma_f32_16x16x32_bf16 v[0:3], v[160:163], v[208:211], v[0:3]
	v_mfma_f32_16x16x32_bf16 v[28:31], v[156:159], v[188:191], v[28:31]
	v_mfma_f32_16x16x32_bf16 v[24:27], v[164:167], v[188:191], v[24:27]
	v_mfma_f32_16x16x32_bf16 v[20:23], v[156:159], v[196:199], v[20:23]
	v_mfma_f32_16x16x32_bf16 v[16:19], v[164:167], v[196:199], v[16:19]
	v_mfma_f32_16x16x32_bf16 v[12:15], v[156:159], v[204:207], v[12:15]
	v_mfma_f32_16x16x32_bf16 v[8:11], v[164:167], v[204:207], v[8:11]
	v_mfma_f32_16x16x32_bf16 v[4:7], v[156:159], v[212:215], v[4:7]
	v_mfma_f32_16x16x32_bf16 v[0:3], v[164:167], v[212:215], v[0:3]
	s_setprio 0
	s_setprio 3
	v_mfma_f32_16x16x32_bf16 v[92:95], v[168:171], v[184:187], v[92:95]
	v_mfma_f32_16x16x32_bf16 v[88:91], v[176:179], v[184:187], v[88:91]
	v_mfma_f32_16x16x32_bf16 v[84:87], v[168:171], v[192:195], v[84:87]
	v_mfma_f32_16x16x32_bf16 v[80:83], v[176:179], v[192:195], v[80:83]
	v_mfma_f32_16x16x32_bf16 v[60:63], v[168:171], v[200:203], v[60:63]
	v_mfma_f32_16x16x32_bf16 v[48:51], v[176:179], v[200:203], v[48:51]
	v_mfma_f32_16x16x32_bf16 v[36:39], v[168:171], v[208:211], v[36:39]
	v_mfma_f32_16x16x32_bf16 v[32:35], v[176:179], v[208:211], v[32:35]
	v_mfma_f32_16x16x32_bf16 v[92:95], v[172:175], v[188:191], v[92:95]
	v_mfma_f32_16x16x32_bf16 v[88:91], v[180:183], v[188:191], v[88:91]
	v_mfma_f32_16x16x32_bf16 v[84:87], v[172:175], v[196:199], v[84:87]
	v_mfma_f32_16x16x32_bf16 v[80:83], v[180:183], v[196:199], v[80:83]
	v_mfma_f32_16x16x32_bf16 v[60:63], v[172:175], v[204:207], v[60:63]
	v_mfma_f32_16x16x32_bf16 v[48:51], v[180:183], v[204:207], v[48:51]
	v_mfma_f32_16x16x32_bf16 v[36:39], v[172:175], v[212:215], v[36:39]
	s_setprio 3
	s_barrier
	v_mfma_f32_16x16x32_bf16 v[32:35], v[180:183], v[212:215], v[32:35]
	s_setprio 0
	s_add_i32 s93, 0, 0x18000
	v_add_u32_e32 v155, s93, v150
	s_add_i32 s94, 0, 0x1c000
	ds_read_b128 v[146:149], v155
	ds_read_b128 v[156:159], v155 offset:1024
	ds_read_b128 v[160:163], v155 offset:2048
	ds_read_b128 v[164:167], v155 offset:3072
	v_add_u32_e32 v155, s94, v150
	ds_read_b128 v[168:171], v155
	ds_read_b128 v[172:175], v155 offset:1024
	ds_read_b128 v[176:179], v155 offset:2048
	ds_read_b128 v[180:183], v155 offset:3072
	s_add_u32 s62, s62, 0x100000
	s_addc_u32 s63, s63, 0
	s_mov_b32 m0, s73
	v_lshl_add_u64 v[224:225], s[62:63], 0, v[128:129]
	ds_read_b128 v[184:187], v154 offset:32768
	ds_read_b128 v[188:191], v154 offset:33792
	ds_read_b128 v[192:195], v154 offset:34816
	ds_read_b128 v[196:199], v154 offset:35840
	ds_read_b128 v[200:203], v154 offset:36864
	ds_read_b128 v[204:207], v154 offset:37888
	ds_read_b128 v[208:211], v154 offset:38912
	ds_read_b128 v[212:215], v154 offset:39936
	global_load_lds_dwordx4 v[224:225], off
	v_lshl_add_u64 v[224:225], s[62:63], 0, v[132:133]
	s_mov_b32 m0, s74
	s_nop 0
	global_load_lds_dwordx4 v[224:225], off
	s_waitcnt vmcnt(8)
	s_waitcnt lgkmcnt(0)
	s_barrier
	s_setprio 3
	s_waitcnt lgkmcnt(0)
	v_mfma_f32_16x16x32_bf16 v[76:79], v[146:149], v[184:187], v[76:79]
	v_mfma_f32_16x16x32_bf16 v[72:75], v[160:163], v[184:187], v[72:75]
	v_mfma_f32_16x16x32_bf16 v[68:71], v[146:149], v[192:195], v[68:71]
	v_mfma_f32_16x16x32_bf16 v[64:67], v[160:163], v[192:195], v[64:67]
	v_mfma_f32_16x16x32_bf16 v[56:59], v[146:149], v[200:203], v[56:59]
	v_mfma_f32_16x16x32_bf16 v[52:55], v[160:163], v[200:203], v[52:55]
	v_mfma_f32_16x16x32_bf16 v[44:47], v[146:149], v[208:211], v[44:47]
	v_mfma_f32_16x16x32_bf16 v[40:43], v[160:163], v[208:211], v[40:43]
	v_mfma_f32_16x16x32_bf16 v[76:79], v[156:159], v[188:191], v[76:79]
	v_mfma_f32_16x16x32_bf16 v[72:75], v[164:167], v[188:191], v[72:75]
	v_mfma_f32_16x16x32_bf16 v[68:71], v[156:159], v[196:199], v[68:71]
	v_mfma_f32_16x16x32_bf16 v[64:67], v[164:167], v[196:199], v[64:67]
	v_mfma_f32_16x16x32_bf16 v[56:59], v[156:159], v[204:207], v[56:59]
	v_mfma_f32_16x16x32_bf16 v[52:55], v[164:167], v[204:207], v[52:55]
	v_mfma_f32_16x16x32_bf16 v[44:47], v[156:159], v[212:215], v[44:47]
	v_mfma_f32_16x16x32_bf16 v[40:43], v[164:167], v[212:215], v[40:43]
	s_setprio 0
	s_setprio 3
	v_mfma_f32_16x16x32_bf16 v[124:127], v[168:171], v[184:187], v[124:127]
	v_mfma_f32_16x16x32_bf16 v[120:123], v[176:179], v[184:187], v[120:123]
	v_mfma_f32_16x16x32_bf16 v[116:119], v[168:171], v[192:195], v[116:119]
	v_mfma_f32_16x16x32_bf16 v[112:115], v[176:179], v[192:195], v[112:115]
	v_mfma_f32_16x16x32_bf16 v[108:111], v[168:171], v[200:203], v[108:111]
	v_mfma_f32_16x16x32_bf16 v[104:107], v[176:179], v[200:203], v[104:107]
	v_mfma_f32_16x16x32_bf16 v[100:103], v[168:171], v[208:211], v[100:103]
	v_mfma_f32_16x16x32_bf16 v[96:99], v[176:179], v[208:211], v[96:99]
	v_mfma_f32_16x16x32_bf16 v[124:127], v[172:175], v[188:191], v[124:127]
	v_mfma_f32_16x16x32_bf16 v[120:123], v[180:183], v[188:191], v[120:123]
	v_mfma_f32_16x16x32_bf16 v[116:119], v[172:175], v[196:199], v[116:119]
	v_mfma_f32_16x16x32_bf16 v[112:115], v[180:183], v[196:199], v[112:115]
	v_mfma_f32_16x16x32_bf16 v[108:111], v[172:175], v[204:207], v[108:111]
	v_mfma_f32_16x16x32_bf16 v[104:107], v[180:183], v[204:207], v[104:107]
	v_mfma_f32_16x16x32_bf16 v[100:103], v[172:175], v[212:215], v[100:103]
	s_setprio 3
	s_barrier
; #define PG8_STAGE(bufoff, gbase, voff) do { _Pragma("unroll") for (int _i = 0; _i < 2; ++_i) \
;         __builtin_amdgcn_global_load_lds((const unsigned*)((const char*)(gbase) + (voff)[_i]), (PG8_LAS unsigned*)(lds + (bufoff) + ldsw + _i * 8192), 16, 0, 0); } while (0)
; #define PG8_LDA(dst, b, h) do { _Pragma("unroll") for (int m = 0; m < 4; ++m) _Pragma("unroll") for (int k = 0; k < 2; ++k) dst[m][k] = *(const PG8_LAS bf16x8*)(lds + PG8_SA(b, h) + aoff + m * 2048 + k * 1024); } while (0)
; #define PG8_MMA(ai, bj, At, Bt) do { __builtin_amdgcn_s_setprio(1); _Pragma("unroll") for (int m = 0; m < 4; ++m) _Pragma("unroll") for (int n = 0; n < 2; ++n) _Pragma("unroll") for (int k = 0; k < 2; ++k) \
;         acc[ai][bj][m][n] = __builtin_amdgcn_mfma_f32_16x16x32_bf16(Bt[n][k], At[m][k], acc[ai][bj][m][n], 0, 0, 0); __builtin_amdgcn_s_setprio(0); } while (0)
; #define PG8_WAIT_V(n) asm volatile("s_waitcnt vmcnt(" #n ")" ::: "memory")
; #define PG8_WAIT_L(n) asm volatile("s_waitcnt lgkmcnt(" #n ")" ::: "memory")
; #define PG8_BAR __builtin_amdgcn_s_barrier()
; #define PG8_SCHED __builtin_amdgcn_sched_barrier(0)
; template <class Epi, class Sched, bool ALIGN_EPI = false, bool SP2 = false>
; __device__ __forceinline__ void gemm_phase(PG8_LAS unsigned char* lds, const Gemm g, const Sched& S, const Epi& E, const int wv  ) {
;     ...
;             PG8_LDA(At, 1, 1); PG8_STAGE(PG8_SB(1, 0), b3, voffB); PG8_STAGE(PG8_SB(1, 1), b3 + hstepB, voffB); PG8_STAGE(PG8_SA(1, 0), a3, voffA);
;             PG8_WAIT_V(8); PG8_WAIT_L(0); PG8_BAR; PG8_MMA(1, 0, At, B0); PG8_MMA(1, 1, At, B1); PG8_BAR; PG8_SCHED;
;     ...
;         if constexpr (ALIGN_EPI) { if (wr == 0) PG8_BAR; }
	v_mfma_f32_16x16x32_bf16 v[96:99], v[180:183], v[212:215], v[96:99]
	s_setprio 0
	s_add_i32 s62, s93, s70
	v_lshl_add_u64 v[216:217], v[216:217], 0, s[10:11]
	s_mov_b32 m0, s62
	ds_read_b128 v[184:187], v154 offset:49152
	ds_read_b128 v[188:191], v154 offset:50176
	ds_read_b128 v[192:195], v154 offset:51200
	ds_read_b128 v[196:199], v154 offset:52224
	ds_read_b128 v[200:203], v154 offset:53248
	ds_read_b128 v[204:207], v154 offset:54272
	ds_read_b128 v[208:211], v154 offset:55296
	ds_read_b128 v[212:215], v154 offset:56320
	global_load_lds_dwordx4 v[216:217], off
	s_add_i32 m0, s62, 0x2000
	s_add_u32 s60, s60, 0x100080
	v_lshl_add_u64 v[216:217], v[218:219], 0, s[10:11]
	s_addc_u32 s61, s61, 0
	s_add_i32 s62, s94, s70
	global_load_lds_dwordx4 v[216:217], off
	v_lshl_add_u64 v[216:217], s[60:61], 0, v[130:131]
	s_mov_b32 m0, s62
	s_nop 0
	global_load_lds_dwordx4 v[216:217], off
	v_lshl_add_u64 v[216:217], s[60:61], 0, v[134:135]
	s_add_i32 m0, s62, 0x2000
	s_nop 0
	global_load_lds_dwordx4 v[216:217], off
	v_lshl_add_u64 v[216:217], v[220:221], 0, s[10:11]
	s_mov_b32 m0, s77
	s_nop 0
	global_load_lds_dwordx4 v[216:217], off
	v_lshl_add_u64 v[216:217], v[222:223], 0, s[10:11]
	s_mov_b32 m0, s78
	s_nop 0
	global_load_lds_dwordx4 v[216:217], off
	s_waitcnt vmcnt(8)
	s_waitcnt lgkmcnt(0)
	s_barrier
	s_setprio 3
	s_waitcnt lgkmcnt(0)
	v_mfma_f32_16x16x32_bf16 v[28:31], v[146:149], v[184:187], v[28:31]
	v_mfma_f32_16x16x32_bf16 v[24:27], v[160:163], v[184:187], v[24:27]
	v_mfma_f32_16x16x32_bf16 v[20:23], v[146:149], v[192:195], v[20:23]
	v_mfma_f32_16x16x32_bf16 v[16:19], v[160:163], v[192:195], v[16:19]
	v_mfma_f32_16x16x32_bf16 v[12:15], v[146:149], v[200:203], v[12:15]
	v_mfma_f32_16x16x32_bf16 v[8:11], v[160:163], v[200:203], v[8:11]
	v_mfma_f32_16x16x32_bf16 v[4:7], v[146:149], v[208:211], v[4:7]
	v_mfma_f32_16x16x32_bf16 v[0:3], v[160:163], v[208:211], v[0:3]
	v_mfma_f32_16x16x32_bf16 v[28:31], v[156:159], v[188:191], v[28:31]
	v_mfma_f32_16x16x32_bf16 v[24:27], v[164:167], v[188:191], v[24:27]
	v_mfma_f32_16x16x32_bf16 v[20:23], v[156:159], v[196:199], v[20:23]
	v_mfma_f32_16x16x32_bf16 v[16:19], v[164:167], v[196:199], v[16:19]
	v_mfma_f32_16x16x32_bf16 v[12:15], v[156:159], v[204:207], v[12:15]
	v_mfma_f32_16x16x32_bf16 v[8:11], v[164:167], v[204:207], v[8:11]
	v_mfma_f32_16x16x32_bf16 v[4:7], v[156:159], v[212:215], v[4:7]
	v_mfma_f32_16x16x32_bf16 v[0:3], v[164:167], v[212:215], v[0:3]
	s_setprio 0
	s_setprio 3
	v_mfma_f32_16x16x32_bf16 v[92:95], v[168:171], v[184:187], v[92:95]
	v_mfma_f32_16x16x32_bf16 v[88:91], v[176:179], v[184:187], v[88:91]
	v_mfma_f32_16x16x32_bf16 v[84:87], v[168:171], v[192:195], v[84:87]
	v_mfma_f32_16x16x32_bf16 v[80:83], v[176:179], v[192:195], v[80:83]
	v_mfma_f32_16x16x32_bf16 v[60:63], v[168:171], v[200:203], v[60:63]
	v_mfma_f32_16x16x32_bf16 v[48:51], v[176:179], v[200:203], v[48:51]
	v_mfma_f32_16x16x32_bf16 v[36:39], v[168:171], v[208:211], v[36:39]
	v_mfma_f32_16x16x32_bf16 v[32:35], v[176:179], v[208:211], v[32:35]
	v_mfma_f32_16x16x32_bf16 v[92:95], v[172:175], v[188:191], v[92:95]
	v_mfma_f32_16x16x32_bf16 v[88:91], v[180:183], v[188:191], v[88:91]
	v_mfma_f32_16x16x32_bf16 v[84:87], v[172:175], v[196:199], v[84:87]
	v_mfma_f32_16x16x32_bf16 v[80:83], v[180:183], v[196:199], v[80:83]
	v_mfma_f32_16x16x32_bf16 v[60:63], v[172:175], v[204:207], v[60:63]
	v_mfma_f32_16x16x32_bf16 v[48:51], v[180:183], v[204:207], v[48:51]
	v_mfma_f32_16x16x32_bf16 v[36:39], v[172:175], v[212:215], v[36:39]
	s_setprio 3
	s_barrier
	v_mfma_f32_16x16x32_bf16 v[32:35], v[180:183], v[212:215], v[32:35]
	s_setprio 0
	s_add_i32 s92, s92, 2
	s_add_u32 s58, s58, 0x100
	s_addc_u32 s59, s59, 0
	s_add_u32 s90, s90, 0x100
	s_addc_u32 s91, s91, 0
	s_cmp_gt_u32 s92, 61
	s_cbranch_scc0 .LBB0_850
	s_and_b64 vcc, exec, s[12:13]
	s_cbranch_vccz .LBB0_853
	s_barrier

; #define PG8_STAGE(bufoff, gbase, voff) do { _Pragma("unroll") for (int _i = 0; _i < 2; ++_i) \
;         __builtin_amdgcn_global_load_lds((const unsigned*)((const char*)(gbase) + (voff)[_i]), (PG8_LAS unsigned*)(lds + (bufoff) + ldsw + _i * 8192), 16, 0, 0); } while (0)
; #define PG8_LDA(dst, b, h) do { _Pragma("unroll") for (int m = 0; m < 4; ++m) _Pragma("unroll") for (int k = 0; k < 2; ++k) dst[m][k] = *(const PG8_LAS bf16x8*)(lds + PG8_SA(b, h) + aoff + m * 2048 + k * 1024); } while (0)
; #define PG8_LDB(dst, b, h) do { _Pragma("unroll") for (int n = 0; n < 2; ++n) _Pragma("unroll") for (int k = 0; k < 2; ++k) dst[n][k] = *(const PG8_LAS bf16x8*)(lds + PG8_SB(b, h) + boff + n * 2048 + k * 1024); } while (0)
; #define PG8_MMA(ai, bj, At, Bt) do { __builtin_amdgcn_s_setprio(1); _Pragma("unroll") for (int m = 0; m < 4; ++m) _Pragma("unroll") for (int n = 0; n < 2; ++n) _Pragma("unroll") for (int k = 0; k < 2; ++k) \
;         acc[ai][bj][m][n] = __builtin_amdgcn_mfma_f32_16x16x32_bf16(Bt[n][k], At[m][k], acc[ai][bj][m][n], 0, 0, 0); __builtin_amdgcn_s_setprio(0); } while (0)
; #define PG8_WAIT_V(n) asm volatile("s_waitcnt vmcnt(" #n ")" ::: "memory")
; #define PG8_WAIT_L(n) asm volatile("s_waitcnt lgkmcnt(" #n ")" ::: "memory")
; #define PG8_BAR __builtin_amdgcn_s_barrier()
; template <class Epi, class Sched, bool ALIGN_EPI = false, bool SP2 = false>
; __device__ __forceinline__ void gemm_phase(PG8_LAS unsigned char* lds, const Gemm g, const Sched& S, const Epi& E, const int wv  ) {
;     ...
;             const char* a1 = cA + (size_t)(t + 1) * kstep;
;             const char* a2 = last ? nA : cA + (size_t)(t + 2) * kstep; const char* b2 = last ? nB : cB + (size_t)(t + 2) * kstep;
;             const char* a3 = a2 + kstep; const char* b3 = b2 + kstep;
;             if (last && has_next) S.a_ready(nxt);
;             if constexpr (SP2) {
;             PG8_LDB(B0, 0, 0); PG8_LDB(B1, 0, 1); PG8_SCHED; PG8_LDA(At, 0, 0); PG8_STAGE(PG8_SA(1, 1), a1 + hstepA, voffA);
;             PG8_WAIT_V(8); PG8_WAIT_L(0); PG8_BAR; PG8_MMA(0, 0, At, B0); PG8_MMA(0, 1, At, B1); PG8_BAR; PG8_SCHED;
;             PG8_LDA(At, 0, 1); PG8_STAGE(PG8_SB(0, 0), b2, voffB); PG8_STAGE(PG8_SB(0, 1), b2 + hstepB, voffB); PG8_STAGE(PG8_SA(0, 0), a2, voffA);
;             PG8_WAIT_V(8); PG8_WAIT_L(0); PG8_BAR; PG8_MMA(1, 0, At, B0); PG8_MMA(1, 1, At, B1); PG8_BAR; PG8_SCHED;
.LBB0_871:
	ds_read_b128 v[142:145], v148
	ds_read_b128 v[152:155], v148 offset:1024
	ds_read_b128 v[156:159], v148 offset:2048
	ds_read_b128 v[160:163], v148 offset:3072
	ds_read_b128 v[164:167], v149
	ds_read_b128 v[168:171], v149 offset:1024
	ds_read_b128 v[172:175], v149 offset:2048
	ds_read_b128 v[176:179], v149 offset:3072
	s_add_u32 s60, s58, 0xfff00080
	s_addc_u32 s61, s59, -1
	s_cmp_eq_u32 s96, 60
	s_cselect_b32 s63, s49, s61
	s_cselect_b32 s62, s92, s60
	s_cselect_b32 s61, s47, s95
	s_cselect_b32 s60, s93, s94
	v_lshl_add_u64 v[212:213], s[58:59], 0, v[138:139]
	s_add_i32 m0, s75, 0xc000
	ds_read_b128 v[180:183], v150
	ds_read_b128 v[184:187], v150 offset:1024
	ds_read_b128 v[188:191], v150 offset:2048
	ds_read_b128 v[192:195], v150 offset:3072
	ds_read_b128 v[196:199], v150 offset:4096
	ds_read_b128 v[200:203], v150 offset:5120
	ds_read_b128 v[204:207], v150 offset:6144
	ds_read_b128 v[208:211], v150 offset:7168
	global_load_lds_dwordx4 v[212:213], off
	v_lshl_add_u64 v[212:213], s[58:59], 0, v[140:141]
	s_add_i32 m0, s75, 0xe000
	s_nop 0
	global_load_lds_dwordx4 v[212:213], off
	s_waitcnt vmcnt(8)
	s_waitcnt lgkmcnt(0)
	s_barrier
	s_setprio 3
	s_waitcnt lgkmcnt(0)
	v_mfma_f32_16x16x32_bf16 v[76:79], v[142:145], v[180:183], v[76:79]
	v_mfma_f32_16x16x32_bf16 v[72:75], v[156:159], v[180:183], v[72:75]
	v_mfma_f32_16x16x32_bf16 v[68:71], v[142:145], v[188:191], v[68:71]
	v_mfma_f32_16x16x32_bf16 v[64:67], v[156:159], v[188:191], v[64:67]
	v_mfma_f32_16x16x32_bf16 v[56:59], v[142:145], v[196:199], v[56:59]
	v_mfma_f32_16x16x32_bf16 v[52:55], v[156:159], v[196:199], v[52:55]
	v_mfma_f32_16x16x32_bf16 v[44:47], v[142:145], v[204:207], v[44:47]
	v_mfma_f32_16x16x32_bf16 v[40:43], v[156:159], v[204:207], v[40:43]
	v_mfma_f32_16x16x32_bf16 v[76:79], v[152:155], v[184:187], v[76:79]
	v_mfma_f32_16x16x32_bf16 v[72:75], v[160:163], v[184:187], v[72:75]
	v_mfma_f32_16x16x32_bf16 v[68:71], v[152:155], v[192:195], v[68:71]
	v_mfma_f32_16x16x32_bf16 v[64:67], v[160:163], v[192:195], v[64:67]
	v_mfma_f32_16x16x32_bf16 v[56:59], v[152:155], v[200:203], v[56:59]
	v_mfma_f32_16x16x32_bf16 v[52:55], v[160:163], v[200:203], v[52:55]
	v_mfma_f32_16x16x32_bf16 v[44:47], v[152:155], v[208:211], v[44:47]
	v_mfma_f32_16x16x32_bf16 v[40:43], v[160:163], v[208:211], v[40:43]
	s_setprio 0
	s_setprio 3
	v_mfma_f32_16x16x32_bf16 v[124:127], v[164:167], v[180:183], v[124:127]
	v_mfma_f32_16x16x32_bf16 v[120:123], v[172:175], v[180:183], v[120:123]
	v_mfma_f32_16x16x32_bf16 v[116:119], v[164:167], v[188:191], v[116:119]
	v_mfma_f32_16x16x32_bf16 v[112:115], v[172:175], v[188:191], v[112:115]
	v_mfma_f32_16x16x32_bf16 v[108:111], v[164:167], v[196:199], v[108:111]
	v_mfma_f32_16x16x32_bf16 v[104:107], v[172:175], v[196:199], v[104:107]
	v_mfma_f32_16x16x32_bf16 v[100:103], v[164:167], v[204:207], v[100:103]
	v_mfma_f32_16x16x32_bf16 v[96:99], v[172:175], v[204:207], v[96:99]
	v_mfma_f32_16x16x32_bf16 v[124:127], v[168:171], v[184:187], v[124:127]
	v_mfma_f32_16x16x32_bf16 v[120:123], v[176:179], v[184:187], v[120:123]
	v_mfma_f32_16x16x32_bf16 v[116:119], v[168:171], v[192:195], v[116:119]
	v_mfma_f32_16x16x32_bf16 v[112:115], v[176:179], v[192:195], v[112:115]
	v_mfma_f32_16x16x32_bf16 v[108:111], v[168:171], v[200:203], v[108:111]
	v_mfma_f32_16x16x32_bf16 v[104:107], v[176:179], v[200:203], v[104:107]
	v_mfma_f32_16x16x32_bf16 v[100:103], v[168:171], v[208:211], v[100:103]
	s_setprio 3
	s_barrier
	v_mfma_f32_16x16x32_bf16 v[96:99], v[176:179], v[208:211], v[96:99]
	s_setprio 0
	s_add_i32 s97, s84, s73
	v_lshl_add_u64 v[212:213], s[60:61], 0, v[132:133]
	s_mov_b32 m0, s97
	ds_read_b128 v[180:183], v150 offset:16384
	ds_read_b128 v[184:187], v150 offset:17408
	ds_read_b128 v[188:191], v150 offset:18432
	ds_read_b128 v[192:195], v150 offset:19456
	ds_read_b128 v[196:199], v150 offset:20480
	ds_read_b128 v[200:203], v150 offset:21504
	ds_read_b128 v[204:207], v150 offset:22528
	ds_read_b128 v[208:211], v150 offset:23552
	global_load_lds_dwordx4 v[212:213], off
	s_add_i32 m0, s97, 0x2000
	s_add_u32 vcc_lo, s60, 0x100000
	v_lshl_add_u64 v[214:215], s[60:61], 0, v[128:129]
	s_addc_u32 vcc_hi, s61, 0
	s_add_i32 s97, s85, s73
	global_load_lds_dwordx4 v[214:215], off
	v_lshl_add_u64 v[216:217], vcc, 0, v[132:133]
	s_mov_b32 m0, s97
	v_lshl_add_u64 v[218:219], s[62:63], 0, v[130:131]
	global_load_lds_dwordx4 v[216:217], off
	v_lshl_add_u64 v[216:217], vcc, 0, v[128:129]
	s_add_i32 m0, s97, 0x2000
	s_nop 0
	global_load_lds_dwordx4 v[216:217], off
	v_lshl_add_u64 v[216:217], s[62:63], 0, v[134:135]
	s_mov_b32 m0, s75
	s_nop 0
	global_load_lds_dwordx4 v[216:217], off
	s_mov_b32 m0, s76
	s_nop 0
	global_load_lds_dwordx4 v[218:219], off
	s_waitcnt vmcnt(8)
	s_waitcnt lgkmcnt(0)
	s_barrier
; #define PG8_STAGE(bufoff, gbase, voff) do { _Pragma("unroll") for (int _i = 0; _i < 2; ++_i) \
;         __builtin_amdgcn_global_load_lds((const unsigned*)((const char*)(gbase) + (voff)[_i]), (PG8_LAS unsigned*)(lds + (bufoff) + ldsw + _i * 8192), 16, 0, 0); } while (0)
; #define PG8_LDA(dst, b, h) do { _Pragma("unroll") for (int m = 0; m < 4; ++m) _Pragma("unroll") for (int k = 0; k < 2; ++k) dst[m][k] = *(const PG8_LAS bf16x8*)(lds + PG8_SA(b, h) + aoff + m * 2048 + k * 1024); } while (0)
; #define PG8_LDB(dst, b, h) do { _Pragma("unroll") for (int n = 0; n < 2; ++n) _Pragma("unroll") for (int k = 0; k < 2; ++k) dst[n][k] = *(const PG8_LAS bf16x8*)(lds + PG8_SB(b, h) + boff + n * 2048 + k * 1024); } while (0)
; #define PG8_MMA(ai, bj, At, Bt) do { __builtin_amdgcn_s_setprio(1); _Pragma("unroll") for (int m = 0; m < 4; ++m) _Pragma("unroll") for (int n = 0; n < 2; ++n) _Pragma("unroll") for (int k = 0; k < 2; ++k) \
;         acc[ai][bj][m][n] = __builtin_amdgcn_mfma_f32_16x16x32_bf16(Bt[n][k], At[m][k], acc[ai][bj][m][n], 0, 0, 0); __builtin_amdgcn_s_setprio(0); } while (0)
; #define PG8_WAIT_V(n) asm volatile("s_waitcnt vmcnt(" #n ")" ::: "memory")
; #define PG8_WAIT_L(n) asm volatile("s_waitcnt lgkmcnt(" #n ")" ::: "memory")
; #define PG8_BAR __builtin_amdgcn_s_barrier()
; #define PG8_SCHED __builtin_amdgcn_sched_barrier(0)
; template <class Epi, class Sched, bool ALIGN_EPI = false, bool SP2 = false>
; __device__ __forceinline__ void gemm_phase(PG8_LAS unsigned char* lds, const Gemm g, const Sched& S, const Epi& E, const int wv  ) {
;     ...
;             PG8_LDA(At, 0, 1); PG8_STAGE(PG8_SB(0, 0), b2, voffB); PG8_STAGE(PG8_SB(0, 1), b2 + hstepB, voffB); PG8_STAGE(PG8_SA(0, 0), a2, voffA);
;             PG8_WAIT_V(8); PG8_WAIT_L(0); PG8_BAR; PG8_MMA(1, 0, At, B0); PG8_MMA(1, 1, At, B1); PG8_BAR; PG8_SCHED;
;             PG8_LDB(B0, 1, 0); PG8_LDB(B1, 1, 1); PG8_SCHED; PG8_LDA(At, 1, 0); PG8_STAGE(PG8_SA(0, 1), a2 + hstepA, voffA);
;             PG8_WAIT_V(8); PG8_WAIT_L(0); PG8_BAR; PG8_MMA(0, 0, At, B0); PG8_MMA(0, 1, At, B1); PG8_BAR; PG8_SCHED;
	s_setprio 3
	s_waitcnt lgkmcnt(0)
	v_mfma_f32_16x16x32_bf16 v[28:31], v[142:145], v[180:183], v[28:31]
	v_mfma_f32_16x16x32_bf16 v[24:27], v[156:159], v[180:183], v[24:27]
	v_mfma_f32_16x16x32_bf16 v[20:23], v[142:145], v[188:191], v[20:23]
	v_mfma_f32_16x16x32_bf16 v[16:19], v[156:159], v[188:191], v[16:19]
	v_mfma_f32_16x16x32_bf16 v[12:15], v[142:145], v[196:199], v[12:15]
	v_mfma_f32_16x16x32_bf16 v[8:11], v[156:159], v[196:199], v[8:11]
	v_mfma_f32_16x16x32_bf16 v[4:7], v[142:145], v[204:207], v[4:7]
	v_mfma_f32_16x16x32_bf16 v[0:3], v[156:159], v[204:207], v[0:3]
	v_mfma_f32_16x16x32_bf16 v[28:31], v[152:155], v[184:187], v[28:31]
	v_mfma_f32_16x16x32_bf16 v[24:27], v[160:163], v[184:187], v[24:27]
	v_mfma_f32_16x16x32_bf16 v[20:23], v[152:155], v[192:195], v[20:23]
	v_mfma_f32_16x16x32_bf16 v[16:19], v[160:163], v[192:195], v[16:19]
	v_mfma_f32_16x16x32_bf16 v[12:15], v[152:155], v[200:203], v[12:15]
	v_mfma_f32_16x16x32_bf16 v[8:11], v[160:163], v[200:203], v[8:11]
	v_mfma_f32_16x16x32_bf16 v[4:7], v[152:155], v[208:211], v[4:7]
	v_mfma_f32_16x16x32_bf16 v[0:3], v[160:163], v[208:211], v[0:3]
	s_setprio 0
	s_setprio 3
	v_mfma_f32_16x16x32_bf16 v[92:95], v[164:167], v[180:183], v[92:95]
	v_mfma_f32_16x16x32_bf16 v[88:91], v[172:175], v[180:183], v[88:91]
	v_mfma_f32_16x16x32_bf16 v[84:87], v[164:167], v[188:191], v[84:87]
	v_mfma_f32_16x16x32_bf16 v[80:83], v[172:175], v[188:191], v[80:83]
	v_mfma_f32_16x16x32_bf16 v[60:63], v[164:167], v[196:199], v[60:63]
	v_mfma_f32_16x16x32_bf16 v[48:51], v[172:175], v[196:199], v[48:51]
	v_mfma_f32_16x16x32_bf16 v[36:39], v[164:167], v[204:207], v[36:39]
	v_mfma_f32_16x16x32_bf16 v[32:35], v[172:175], v[204:207], v[32:35]
	v_mfma_f32_16x16x32_bf16 v[92:95], v[168:171], v[184:187], v[92:95]
	v_mfma_f32_16x16x32_bf16 v[88:91], v[176:179], v[184:187], v[88:91]
	v_mfma_f32_16x16x32_bf16 v[84:87], v[168:171], v[192:195], v[84:87]
	v_mfma_f32_16x16x32_bf16 v[80:83], v[176:179], v[192:195], v[80:83]
	v_mfma_f32_16x16x32_bf16 v[60:63], v[168:171], v[200:203], v[60:63]
	v_mfma_f32_16x16x32_bf16 v[48:51], v[176:179], v[200:203], v[48:51]
	v_mfma_f32_16x16x32_bf16 v[36:39], v[168:171], v[208:211], v[36:39]
	s_setprio 3
	s_barrier
	v_mfma_f32_16x16x32_bf16 v[32:35], v[176:179], v[208:211], v[32:35]
	s_setprio 0
	s_add_i32 s97, 0, 0x18000
	v_add_u32_e32 v151, s97, v146
	s_add_i32 vcc_lo, 0, 0x1c000
	ds_read_b128 v[142:145], v151
	ds_read_b128 v[152:155], v151 offset:1024
	ds_read_b128 v[156:159], v151 offset:2048
	ds_read_b128 v[160:163], v151 offset:3072
	v_add_u32_e32 v151, vcc_lo, v146
	ds_read_b128 v[164:167], v151
	ds_read_b128 v[168:171], v151 offset:1024
	ds_read_b128 v[172:175], v151 offset:2048
	ds_read_b128 v[176:179], v151 offset:3072
	s_add_u32 s62, s62, 0x100000
	s_addc_u32 s63, s63, 0
	s_mov_b32 m0, s77
	v_lshl_add_u64 v[220:221], s[62:63], 0, v[134:135]
	ds_read_b128 v[180:183], v150 offset:32768
	ds_read_b128 v[184:187], v150 offset:33792
	ds_read_b128 v[188:191], v150 offset:34816
	ds_read_b128 v[192:195], v150 offset:35840
	ds_read_b128 v[196:199], v150 offset:36864
	ds_read_b128 v[200:203], v150 offset:37888
	ds_read_b128 v[204:207], v150 offset:38912
	ds_read_b128 v[208:211], v150 offset:39936
	global_load_lds_dwordx4 v[220:221], off
	v_lshl_add_u64 v[220:221], s[62:63], 0, v[130:131]
	s_mov_b32 m0, s78
	s_nop 0
	global_load_lds_dwordx4 v[220:221], off
	s_waitcnt vmcnt(8)
	s_waitcnt lgkmcnt(0)
	s_barrier
	s_setprio 3
	s_waitcnt lgkmcnt(0)
	v_mfma_f32_16x16x32_bf16 v[76:79], v[142:145], v[180:183], v[76:79]
	v_mfma_f32_16x16x32_bf16 v[72:75], v[156:159], v[180:183], v[72:75]
	v_mfma_f32_16x16x32_bf16 v[68:71], v[142:145], v[188:191], v[68:71]
	v_mfma_f32_16x16x32_bf16 v[64:67], v[156:159], v[188:191], v[64:67]
	v_mfma_f32_16x16x32_bf16 v[56:59], v[142:145], v[196:199], v[56:59]
	v_mfma_f32_16x16x32_bf16 v[52:55], v[156:159], v[196:199], v[52:55]
	v_mfma_f32_16x16x32_bf16 v[44:47], v[142:145], v[204:207], v[44:47]
	v_mfma_f32_16x16x32_bf16 v[40:43], v[156:159], v[204:207], v[40:43]
	v_mfma_f32_16x16x32_bf16 v[76:79], v[152:155], v[184:187], v[76:79]
	v_mfma_f32_16x16x32_bf16 v[72:75], v[160:163], v[184:187], v[72:75]
	v_mfma_f32_16x16x32_bf16 v[68:71], v[152:155], v[192:195], v[68:71]
	v_mfma_f32_16x16x32_bf16 v[64:67], v[160:163], v[192:195], v[64:67]
	v_mfma_f32_16x16x32_bf16 v[56:59], v[152:155], v[200:203], v[56:59]
	v_mfma_f32_16x16x32_bf16 v[52:55], v[160:163], v[200:203], v[52:55]
	v_mfma_f32_16x16x32_bf16 v[44:47], v[152:155], v[208:211], v[44:47]
	v_mfma_f32_16x16x32_bf16 v[40:43], v[160:163], v[208:211], v[40:43]
	s_setprio 0
	s_setprio 3
	v_mfma_f32_16x16x32_bf16 v[124:127], v[164:167], v[180:183], v[124:127]
	v_mfma_f32_16x16x32_bf16 v[120:123], v[172:175], v[180:183], v[120:123]
	v_mfma_f32_16x16x32_bf16 v[116:119], v[164:167], v[188:191], v[116:119]
	v_mfma_f32_16x16x32_bf16 v[112:115], v[172:175], v[188:191], v[112:115]
	v_mfma_f32_16x16x32_bf16 v[108:111], v[164:167], v[196:199], v[108:111]
	v_mfma_f32_16x16x32_bf16 v[104:107], v[172:175], v[196:199], v[104:107]
	v_mfma_f32_16x16x32_bf16 v[100:103], v[164:167], v[204:207], v[100:103]
	v_mfma_f32_16x16x32_bf16 v[96:99], v[172:175], v[204:207], v[96:99]
	v_mfma_f32_16x16x32_bf16 v[124:127], v[168:171], v[184:187], v[124:127]
	v_mfma_f32_16x16x32_bf16 v[120:123], v[176:179], v[184:187], v[120:123]
	v_mfma_f32_16x16x32_bf16 v[116:119], v[168:171], v[192:195], v[116:119]
	v_mfma_f32_16x16x32_bf16 v[112:115], v[176:179], v[192:195], v[112:115]
	v_mfma_f32_16x16x32_bf16 v[108:111], v[168:171], v[200:203], v[108:111]
	v_mfma_f32_16x16x32_bf16 v[104:107], v[176:179], v[200:203], v[104:107]
	v_mfma_f32_16x16x32_bf16 v[100:103], v[168:171], v[208:211], v[100:103]
	s_setprio 3
	s_barrier
; #define PG8_STAGE(bufoff, gbase, voff) do { _Pragma("unroll") for (int _i = 0; _i < 2; ++_i) \
;         __builtin_amdgcn_global_load_lds((const unsigned*)((const char*)(gbase) + (voff)[_i]), (PG8_LAS unsigned*)(lds + (bufoff) + ldsw + _i * 8192), 16, 0, 0); } while (0)
; #define PG8_LDA(dst, b, h) do { _Pragma("unroll") for (int m = 0; m < 4; ++m) _Pragma("unroll") for (int k = 0; k < 2; ++k) dst[m][k] = *(const PG8_LAS bf16x8*)(lds + PG8_SA(b, h) + aoff + m * 2048 + k * 1024); } while (0)
; #define PG8_MMA(ai, bj, At, Bt) do { __builtin_amdgcn_s_setprio(1); _Pragma("unroll") for (int m = 0; m < 4; ++m) _Pragma("unroll") for (int n = 0; n < 2; ++n) _Pragma("unroll") for (int k = 0; k < 2; ++k) \
;         acc[ai][bj][m][n] = __builtin_amdgcn_mfma_f32_16x16x32_bf16(Bt[n][k], At[m][k], acc[ai][bj][m][n], 0, 0, 0); __builtin_amdgcn_s_setprio(0); } while (0)
; #define PG8_WAIT_V(n) asm volatile("s_waitcnt vmcnt(" #n ")" ::: "memory")
; #define PG8_WAIT_L(n) asm volatile("s_waitcnt lgkmcnt(" #n ")" ::: "memory")
; #define PG8_BAR __builtin_amdgcn_s_barrier()
; #define PG8_SCHED __builtin_amdgcn_sched_barrier(0)
; template <class Epi, class Sched, bool ALIGN_EPI = false, bool SP2 = false>
; __device__ __forceinline__ void gemm_phase(PG8_LAS unsigned char* lds, const Gemm g, const Sched& S, const Epi& E, const int wv  ) {
;     ...
;             PG8_LDA(At, 1, 1); PG8_STAGE(PG8_SB(1, 0), b3, voffB); PG8_STAGE(PG8_SB(1, 1), b3 + hstepB, voffB); PG8_STAGE(PG8_SA(1, 0), a3, voffA);
;             PG8_WAIT_V(8); PG8_WAIT_L(0); PG8_BAR; PG8_MMA(1, 0, At, B0); PG8_MMA(1, 1, At, B1); PG8_BAR; PG8_SCHED;
;     ...
;         if constexpr (ALIGN_EPI) { if (wr == 0) PG8_BAR; }
	v_mfma_f32_16x16x32_bf16 v[96:99], v[176:179], v[208:211], v[96:99]
	s_setprio 0
	s_add_i32 s62, s97, s73
	v_lshl_add_u64 v[212:213], v[212:213], 0, s[8:9]
	s_mov_b32 m0, s62
	ds_read_b128 v[180:183], v150 offset:49152
	ds_read_b128 v[184:187], v150 offset:50176
	ds_read_b128 v[188:191], v150 offset:51200
	ds_read_b128 v[192:195], v150 offset:52224
	ds_read_b128 v[196:199], v150 offset:53248
	ds_read_b128 v[200:203], v150 offset:54272
	ds_read_b128 v[204:207], v150 offset:55296
	ds_read_b128 v[208:211], v150 offset:56320
	global_load_lds_dwordx4 v[212:213], off
	s_add_i32 m0, s62, 0x2000
	s_add_u32 s60, s60, 0x100080
	v_lshl_add_u64 v[212:213], v[214:215], 0, s[8:9]
	s_addc_u32 s61, s61, 0
	s_add_i32 s62, vcc_lo, s73
	global_load_lds_dwordx4 v[212:213], off
	v_lshl_add_u64 v[212:213], s[60:61], 0, v[132:133]
	s_mov_b32 m0, s62
	s_nop 0
	global_load_lds_dwordx4 v[212:213], off
	v_lshl_add_u64 v[212:213], s[60:61], 0, v[128:129]
	s_add_i32 m0, s62, 0x2000
	s_nop 0
	global_load_lds_dwordx4 v[212:213], off
	v_lshl_add_u64 v[212:213], v[216:217], 0, s[8:9]
	s_mov_b32 m0, s80
	s_nop 0
	global_load_lds_dwordx4 v[212:213], off
	v_lshl_add_u64 v[212:213], v[218:219], 0, s[8:9]
	s_mov_b32 m0, s81
	s_nop 0
	global_load_lds_dwordx4 v[212:213], off
	s_waitcnt vmcnt(8)
	s_waitcnt lgkmcnt(0)
	s_barrier
	s_setprio 3
	s_waitcnt lgkmcnt(0)
	v_mfma_f32_16x16x32_bf16 v[28:31], v[142:145], v[180:183], v[28:31]
	v_mfma_f32_16x16x32_bf16 v[24:27], v[156:159], v[180:183], v[24:27]
	v_mfma_f32_16x16x32_bf16 v[20:23], v[142:145], v[188:191], v[20:23]
	v_mfma_f32_16x16x32_bf16 v[16:19], v[156:159], v[188:191], v[16:19]
	v_mfma_f32_16x16x32_bf16 v[12:15], v[142:145], v[196:199], v[12:15]
	v_mfma_f32_16x16x32_bf16 v[8:11], v[156:159], v[196:199], v[8:11]
	v_mfma_f32_16x16x32_bf16 v[4:7], v[142:145], v[204:207], v[4:7]
	v_mfma_f32_16x16x32_bf16 v[0:3], v[156:159], v[204:207], v[0:3]
	v_mfma_f32_16x16x32_bf16 v[28:31], v[152:155], v[184:187], v[28:31]
	v_mfma_f32_16x16x32_bf16 v[24:27], v[160:163], v[184:187], v[24:27]
	v_mfma_f32_16x16x32_bf16 v[20:23], v[152:155], v[192:195], v[20:23]
	v_mfma_f32_16x16x32_bf16 v[16:19], v[160:163], v[192:195], v[16:19]
	v_mfma_f32_16x16x32_bf16 v[12:15], v[152:155], v[200:203], v[12:15]
	v_mfma_f32_16x16x32_bf16 v[8:11], v[160:163], v[200:203], v[8:11]
	v_mfma_f32_16x16x32_bf16 v[4:7], v[152:155], v[208:211], v[4:7]
	v_mfma_f32_16x16x32_bf16 v[0:3], v[160:163], v[208:211], v[0:3]
	s_setprio 0
	s_setprio 3
	v_mfma_f32_16x16x32_bf16 v[92:95], v[164:167], v[180:183], v[92:95]
	v_mfma_f32_16x16x32_bf16 v[88:91], v[172:175], v[180:183], v[88:91]
	v_mfma_f32_16x16x32_bf16 v[84:87], v[164:167], v[188:191], v[84:87]
	v_mfma_f32_16x16x32_bf16 v[80:83], v[172:175], v[188:191], v[80:83]
	v_mfma_f32_16x16x32_bf16 v[60:63], v[164:167], v[196:199], v[60:63]
	v_mfma_f32_16x16x32_bf16 v[48:51], v[172:175], v[196:199], v[48:51]
	v_mfma_f32_16x16x32_bf16 v[36:39], v[164:167], v[204:207], v[36:39]
	v_mfma_f32_16x16x32_bf16 v[32:35], v[172:175], v[204:207], v[32:35]
	v_mfma_f32_16x16x32_bf16 v[92:95], v[168:171], v[184:187], v[92:95]
	v_mfma_f32_16x16x32_bf16 v[88:91], v[176:179], v[184:187], v[88:91]
	v_mfma_f32_16x16x32_bf16 v[84:87], v[168:171], v[192:195], v[84:87]
	v_mfma_f32_16x16x32_bf16 v[80:83], v[176:179], v[192:195], v[80:83]
	v_mfma_f32_16x16x32_bf16 v[60:63], v[168:171], v[200:203], v[60:63]
	v_mfma_f32_16x16x32_bf16 v[48:51], v[176:179], v[200:203], v[48:51]
	v_mfma_f32_16x16x32_bf16 v[36:39], v[168:171], v[208:211], v[36:39]
	s_setprio 3
	s_barrier
	v_mfma_f32_16x16x32_bf16 v[32:35], v[176:179], v[208:211], v[32:35]
	s_setprio 0
	s_add_i32 s96, s96, 2
	s_add_u32 s58, s58, 0x100
	s_addc_u32 s59, s59, 0
	s_add_u32 s94, s94, 0x100
	s_addc_u32 s95, s95, 0
	s_cmp_gt_u32 s96, 61
	s_cbranch_scc0 .LBB0_871
	s_and_b64 vcc, exec, s[10:11]
	s_cbranch_vccz .LBB0_874
	s_barrier

; #define PG8_STAGE(bufoff, gbase, voff) do { _Pragma("unroll") for (int _i = 0; _i < 2; ++_i) \
;         __builtin_amdgcn_global_load_lds((const unsigned*)((const char*)(gbase) + (voff)[_i]), (PG8_LAS unsigned*)(lds + (bufoff) + ldsw + _i * 8192), 16, 0, 0); } while (0)
; #define PG8_LDA(dst, b, h) do { _Pragma("unroll") for (int m = 0; m < 4; ++m) _Pragma("unroll") for (int k = 0; k < 2; ++k) dst[m][k] = *(const PG8_LAS bf16x8*)(lds + PG8_SA(b, h) + aoff + m * 2048 + k * 1024); } while (0)
; #define PG8_LDB(dst, b, h) do { _Pragma("unroll") for (int n = 0; n < 2; ++n) _Pragma("unroll") for (int k = 0; k < 2; ++k) dst[n][k] = *(const PG8_LAS bf16x8*)(lds + PG8_SB(b, h) + boff + n * 2048 + k * 1024); } while (0)
; #define PG8_MMA(ai, bj, At, Bt) do { __builtin_amdgcn_s_setprio(1); _Pragma("unroll") for (int m = 0; m < 4; ++m) _Pragma("unroll") for (int n = 0; n < 2; ++n) _Pragma("unroll") for (int k = 0; k < 2; ++k) \
;         acc[ai][bj][m][n] = __builtin_amdgcn_mfma_f32_16x16x32_bf16(Bt[n][k], At[m][k], acc[ai][bj][m][n], 0, 0, 0); __builtin_amdgcn_s_setprio(0); } while (0)
; #define PG8_WAIT_V(n) asm volatile("s_waitcnt vmcnt(" #n ")" ::: "memory")
; #define PG8_WAIT_L(n) asm volatile("s_waitcnt lgkmcnt(" #n ")" ::: "memory")
; #define PG8_BAR __builtin_amdgcn_s_barrier()
; template <class Epi, class Sched, bool ALIGN_EPI = false, bool SP2 = false>
; __device__ __forceinline__ void gemm_phase(PG8_LAS unsigned char* lds, const Gemm g, const Sched& S, const Epi& E, const int wv  ) {
;     ...
;             const char* a1 = cA + (size_t)(t + 1) * kstep;
;             const char* a2 = last ? nA : cA + (size_t)(t + 2) * kstep; const char* b2 = last ? nB : cB + (size_t)(t + 2) * kstep;
;             const char* a3 = a2 + kstep; const char* b3 = b2 + kstep;
;             if (last && has_next) S.a_ready(nxt);
;             if constexpr (SP2) {
;             PG8_LDB(B0, 0, 0); PG8_LDB(B1, 0, 1); PG8_SCHED; PG8_LDA(At, 0, 0); PG8_STAGE(PG8_SA(1, 1), a1 + hstepA, voffA);
;             PG8_WAIT_V(8); PG8_WAIT_L(0); PG8_BAR; PG8_MMA(0, 0, At, B0); PG8_MMA(0, 1, At, B1); PG8_BAR; PG8_SCHED;
;             PG8_LDA(At, 0, 1); PG8_STAGE(PG8_SB(0, 0), b2, voffB); PG8_STAGE(PG8_SB(0, 1), b2 + hstepB, voffB); PG8_STAGE(PG8_SA(0, 0), a2, voffA);
;             PG8_WAIT_V(8); PG8_WAIT_L(0); PG8_BAR; PG8_MMA(1, 0, At, B0); PG8_MMA(1, 1, At, B1); PG8_BAR; PG8_SCHED;
.LBB0_892:
	ds_read_b128 v[142:145], v148
	ds_read_b128 v[152:155], v148 offset:1024
	ds_read_b128 v[156:159], v148 offset:2048
	ds_read_b128 v[160:163], v148 offset:3072
	ds_read_b128 v[164:167], v149
	ds_read_b128 v[168:171], v149 offset:1024
	ds_read_b128 v[172:175], v149 offset:2048
	ds_read_b128 v[176:179], v149 offset:3072
	s_add_u32 s60, s58, 0xfff00080
	s_addc_u32 s61, s59, -1
	s_cmp_eq_u32 s92, 60
	s_cselect_b32 s63, s49, s61
	s_cselect_b32 s62, s86, s60
	s_cselect_b32 s61, s47, s91
	s_cselect_b32 s60, s87, s90
	v_lshl_add_u64 v[212:213], s[58:59], 0, v[138:139]
	s_add_i32 m0, s71, 0xc000
	ds_read_b128 v[180:183], v150
	ds_read_b128 v[184:187], v150 offset:1024
	ds_read_b128 v[188:191], v150 offset:2048
	ds_read_b128 v[192:195], v150 offset:3072
	ds_read_b128 v[196:199], v150 offset:4096
	ds_read_b128 v[200:203], v150 offset:5120
	ds_read_b128 v[204:207], v150 offset:6144
	ds_read_b128 v[208:211], v150 offset:7168
	global_load_lds_dwordx4 v[212:213], off
	v_lshl_add_u64 v[212:213], s[58:59], 0, v[140:141]
	s_add_i32 m0, s71, 0xe000
	s_nop 0
	global_load_lds_dwordx4 v[212:213], off
	s_waitcnt vmcnt(8)
	s_waitcnt lgkmcnt(0)
	s_barrier
	s_setprio 3
	s_waitcnt lgkmcnt(0)
	v_mfma_f32_16x16x32_bf16 v[76:79], v[142:145], v[180:183], v[76:79]
	v_mfma_f32_16x16x32_bf16 v[72:75], v[156:159], v[180:183], v[72:75]
	v_mfma_f32_16x16x32_bf16 v[68:71], v[142:145], v[188:191], v[68:71]
	v_mfma_f32_16x16x32_bf16 v[64:67], v[156:159], v[188:191], v[64:67]
	v_mfma_f32_16x16x32_bf16 v[56:59], v[142:145], v[196:199], v[56:59]
	v_mfma_f32_16x16x32_bf16 v[52:55], v[156:159], v[196:199], v[52:55]
	v_mfma_f32_16x16x32_bf16 v[44:47], v[142:145], v[204:207], v[44:47]
	v_mfma_f32_16x16x32_bf16 v[40:43], v[156:159], v[204:207], v[40:43]
	v_mfma_f32_16x16x32_bf16 v[76:79], v[152:155], v[184:187], v[76:79]
	v_mfma_f32_16x16x32_bf16 v[72:75], v[160:163], v[184:187], v[72:75]
	v_mfma_f32_16x16x32_bf16 v[68:71], v[152:155], v[192:195], v[68:71]
	v_mfma_f32_16x16x32_bf16 v[64:67], v[160:163], v[192:195], v[64:67]
	v_mfma_f32_16x16x32_bf16 v[56:59], v[152:155], v[200:203], v[56:59]
	v_mfma_f32_16x16x32_bf16 v[52:55], v[160:163], v[200:203], v[52:55]
	v_mfma_f32_16x16x32_bf16 v[44:47], v[152:155], v[208:211], v[44:47]
	v_mfma_f32_16x16x32_bf16 v[40:43], v[160:163], v[208:211], v[40:43]
	s_setprio 0
	s_setprio 3
	v_mfma_f32_16x16x32_bf16 v[124:127], v[164:167], v[180:183], v[124:127]
	v_mfma_f32_16x16x32_bf16 v[120:123], v[172:175], v[180:183], v[120:123]
	v_mfma_f32_16x16x32_bf16 v[116:119], v[164:167], v[188:191], v[116:119]
	v_mfma_f32_16x16x32_bf16 v[112:115], v[172:175], v[188:191], v[112:115]
	v_mfma_f32_16x16x32_bf16 v[108:111], v[164:167], v[196:199], v[108:111]
	v_mfma_f32_16x16x32_bf16 v[104:107], v[172:175], v[196:199], v[104:107]
	v_mfma_f32_16x16x32_bf16 v[100:103], v[164:167], v[204:207], v[100:103]
	v_mfma_f32_16x16x32_bf16 v[96:99], v[172:175], v[204:207], v[96:99]
	v_mfma_f32_16x16x32_bf16 v[124:127], v[168:171], v[184:187], v[124:127]
	v_mfma_f32_16x16x32_bf16 v[120:123], v[176:179], v[184:187], v[120:123]
	v_mfma_f32_16x16x32_bf16 v[116:119], v[168:171], v[192:195], v[116:119]
	v_mfma_f32_16x16x32_bf16 v[112:115], v[176:179], v[192:195], v[112:115]
	v_mfma_f32_16x16x32_bf16 v[108:111], v[168:171], v[200:203], v[108:111]
	v_mfma_f32_16x16x32_bf16 v[104:107], v[176:179], v[200:203], v[104:107]
	v_mfma_f32_16x16x32_bf16 v[100:103], v[168:171], v[208:211], v[100:103]
	s_setprio 3
	s_barrier
	v_mfma_f32_16x16x32_bf16 v[96:99], v[176:179], v[208:211], v[96:99]
	s_setprio 0
	s_add_i32 s93, s84, s69
	v_lshl_add_u64 v[212:213], s[60:61], 0, v[132:133]
	s_mov_b32 m0, s93
	ds_read_b128 v[180:183], v150 offset:16384
	ds_read_b128 v[184:187], v150 offset:17408
	ds_read_b128 v[188:191], v150 offset:18432
	ds_read_b128 v[192:195], v150 offset:19456
	ds_read_b128 v[196:199], v150 offset:20480
	ds_read_b128 v[200:203], v150 offset:21504
	ds_read_b128 v[204:207], v150 offset:22528
	ds_read_b128 v[208:211], v150 offset:23552
	global_load_lds_dwordx4 v[212:213], off
	s_add_i32 m0, s93, 0x2000
	s_add_u32 s94, s60, 0x100000
	v_lshl_add_u64 v[214:215], s[60:61], 0, v[128:129]
	s_addc_u32 s95, s61, 0
	s_add_i32 s93, s85, s69
	global_load_lds_dwordx4 v[214:215], off
	v_lshl_add_u64 v[216:217], s[94:95], 0, v[132:133]
	s_mov_b32 m0, s93
	v_lshl_add_u64 v[218:219], s[62:63], 0, v[130:131]
	global_load_lds_dwordx4 v[216:217], off
	v_lshl_add_u64 v[216:217], s[94:95], 0, v[128:129]
	s_add_i32 m0, s93, 0x2000
	s_nop 0
	global_load_lds_dwordx4 v[216:217], off
	v_lshl_add_u64 v[216:217], s[62:63], 0, v[134:135]
	s_mov_b32 m0, s71
	s_nop 0
	global_load_lds_dwordx4 v[216:217], off
	s_mov_b32 m0, s72
	s_nop 0
	global_load_lds_dwordx4 v[218:219], off
	s_waitcnt vmcnt(8)
	s_waitcnt lgkmcnt(0)
	s_barrier
; #define PG8_STAGE(bufoff, gbase, voff) do { _Pragma("unroll") for (int _i = 0; _i < 2; ++_i) \
;         __builtin_amdgcn_global_load_lds((const unsigned*)((const char*)(gbase) + (voff)[_i]), (PG8_LAS unsigned*)(lds + (bufoff) + ldsw + _i * 8192), 16, 0, 0); } while (0)
; #define PG8_LDA(dst, b, h) do { _Pragma("unroll") for (int m = 0; m < 4; ++m) _Pragma("unroll") for (int k = 0; k < 2; ++k) dst[m][k] = *(const PG8_LAS bf16x8*)(lds + PG8_SA(b, h) + aoff + m * 2048 + k * 1024); } while (0)
; #define PG8_LDB(dst, b, h) do { _Pragma("unroll") for (int n = 0; n < 2; ++n) _Pragma("unroll") for (int k = 0; k < 2; ++k) dst[n][k] = *(const PG8_LAS bf16x8*)(lds + PG8_SB(b, h) + boff + n * 2048 + k * 1024); } while (0)
; #define PG8_MMA(ai, bj, At, Bt) do { __builtin_amdgcn_s_setprio(1); _Pragma("unroll") for (int m = 0; m < 4; ++m) _Pragma("unroll") for (int n = 0; n < 2; ++n) _Pragma("unroll") for (int k = 0; k < 2; ++k) \
;         acc[ai][bj][m][n] = __builtin_amdgcn_mfma_f32_16x16x32_bf16(Bt[n][k], At[m][k], acc[ai][bj][m][n], 0, 0, 0); __builtin_amdgcn_s_setprio(0); } while (0)
; #define PG8_WAIT_V(n) asm volatile("s_waitcnt vmcnt(" #n ")" ::: "memory")
; #define PG8_WAIT_L(n) asm volatile("s_waitcnt lgkmcnt(" #n ")" ::: "memory")
; #define PG8_BAR __builtin_amdgcn_s_barrier()
; #define PG8_SCHED __builtin_amdgcn_sched_barrier(0)
; template <class Epi, class Sched, bool ALIGN_EPI = false, bool SP2 = false>
; __device__ __forceinline__ void gemm_phase(PG8_LAS unsigned char* lds, const Gemm g, const Sched& S, const Epi& E, const int wv  ) {
;     ...
;             PG8_LDA(At, 0, 1); PG8_STAGE(PG8_SB(0, 0), b2, voffB); PG8_STAGE(PG8_SB(0, 1), b2 + hstepB, voffB); PG8_STAGE(PG8_SA(0, 0), a2, voffA);
;             PG8_WAIT_V(8); PG8_WAIT_L(0); PG8_BAR; PG8_MMA(1, 0, At, B0); PG8_MMA(1, 1, At, B1); PG8_BAR; PG8_SCHED;
;             PG8_LDB(B0, 1, 0); PG8_LDB(B1, 1, 1); PG8_SCHED; PG8_LDA(At, 1, 0); PG8_STAGE(PG8_SA(0, 1), a2 + hstepA, voffA);
;             PG8_WAIT_V(8); PG8_WAIT_L(0); PG8_BAR; PG8_MMA(0, 0, At, B0); PG8_MMA(0, 1, At, B1); PG8_BAR; PG8_SCHED;
	s_setprio 3
	s_waitcnt lgkmcnt(0)
	v_mfma_f32_16x16x32_bf16 v[28:31], v[142:145], v[180:183], v[28:31]
	v_mfma_f32_16x16x32_bf16 v[24:27], v[156:159], v[180:183], v[24:27]
	v_mfma_f32_16x16x32_bf16 v[20:23], v[142:145], v[188:191], v[20:23]
	v_mfma_f32_16x16x32_bf16 v[16:19], v[156:159], v[188:191], v[16:19]
	v_mfma_f32_16x16x32_bf16 v[12:15], v[142:145], v[196:199], v[12:15]
	v_mfma_f32_16x16x32_bf16 v[8:11], v[156:159], v[196:199], v[8:11]
	v_mfma_f32_16x16x32_bf16 v[4:7], v[142:145], v[204:207], v[4:7]
	v_mfma_f32_16x16x32_bf16 v[0:3], v[156:159], v[204:207], v[0:3]
	v_mfma_f32_16x16x32_bf16 v[28:31], v[152:155], v[184:187], v[28:31]
	v_mfma_f32_16x16x32_bf16 v[24:27], v[160:163], v[184:187], v[24:27]
	v_mfma_f32_16x16x32_bf16 v[20:23], v[152:155], v[192:195], v[20:23]
	v_mfma_f32_16x16x32_bf16 v[16:19], v[160:163], v[192:195], v[16:19]
	v_mfma_f32_16x16x32_bf16 v[12:15], v[152:155], v[200:203], v[12:15]
	v_mfma_f32_16x16x32_bf16 v[8:11], v[160:163], v[200:203], v[8:11]
	v_mfma_f32_16x16x32_bf16 v[4:7], v[152:155], v[208:211], v[4:7]
	v_mfma_f32_16x16x32_bf16 v[0:3], v[160:163], v[208:211], v[0:3]
	s_setprio 0
	s_setprio 3
	v_mfma_f32_16x16x32_bf16 v[92:95], v[164:167], v[180:183], v[92:95]
	v_mfma_f32_16x16x32_bf16 v[88:91], v[172:175], v[180:183], v[88:91]
	v_mfma_f32_16x16x32_bf16 v[84:87], v[164:167], v[188:191], v[84:87]
	v_mfma_f32_16x16x32_bf16 v[80:83], v[172:175], v[188:191], v[80:83]
	v_mfma_f32_16x16x32_bf16 v[60:63], v[164:167], v[196:199], v[60:63]
	v_mfma_f32_16x16x32_bf16 v[48:51], v[172:175], v[196:199], v[48:51]
	v_mfma_f32_16x16x32_bf16 v[36:39], v[164:167], v[204:207], v[36:39]
	v_mfma_f32_16x16x32_bf16 v[32:35], v[172:175], v[204:207], v[32:35]
	v_mfma_f32_16x16x32_bf16 v[92:95], v[168:171], v[184:187], v[92:95]
	v_mfma_f32_16x16x32_bf16 v[88:91], v[176:179], v[184:187], v[88:91]
	v_mfma_f32_16x16x32_bf16 v[84:87], v[168:171], v[192:195], v[84:87]
	v_mfma_f32_16x16x32_bf16 v[80:83], v[176:179], v[192:195], v[80:83]
	v_mfma_f32_16x16x32_bf16 v[60:63], v[168:171], v[200:203], v[60:63]
	v_mfma_f32_16x16x32_bf16 v[48:51], v[176:179], v[200:203], v[48:51]
	v_mfma_f32_16x16x32_bf16 v[36:39], v[168:171], v[208:211], v[36:39]
	s_setprio 3
	s_barrier
	v_mfma_f32_16x16x32_bf16 v[32:35], v[176:179], v[208:211], v[32:35]
	s_setprio 0
	s_add_i32 s93, 0, 0x18000
	v_add_u32_e32 v151, s93, v146
	s_add_i32 s94, 0, 0x1c000
	ds_read_b128 v[142:145], v151
	ds_read_b128 v[152:155], v151 offset:1024
	ds_read_b128 v[156:159], v151 offset:2048
	ds_read_b128 v[160:163], v151 offset:3072
	v_add_u32_e32 v151, s94, v146
	ds_read_b128 v[164:167], v151
	ds_read_b128 v[168:171], v151 offset:1024
	ds_read_b128 v[172:175], v151 offset:2048
	ds_read_b128 v[176:179], v151 offset:3072
	s_add_u32 s62, s62, 0x100000
	s_addc_u32 s63, s63, 0
	s_mov_b32 m0, s73
	v_lshl_add_u64 v[220:221], s[62:63], 0, v[134:135]
	ds_read_b128 v[180:183], v150 offset:32768
	ds_read_b128 v[184:187], v150 offset:33792
	ds_read_b128 v[188:191], v150 offset:34816
	ds_read_b128 v[192:195], v150 offset:35840
	ds_read_b128 v[196:199], v150 offset:36864
	ds_read_b128 v[200:203], v150 offset:37888
	ds_read_b128 v[204:207], v150 offset:38912
	ds_read_b128 v[208:211], v150 offset:39936
	global_load_lds_dwordx4 v[220:221], off
	v_lshl_add_u64 v[220:221], s[62:63], 0, v[130:131]
	s_mov_b32 m0, s74
	s_nop 0
	global_load_lds_dwordx4 v[220:221], off
	s_waitcnt vmcnt(8)
	s_waitcnt lgkmcnt(0)
	s_barrier
	s_setprio 3
	s_waitcnt lgkmcnt(0)
	v_mfma_f32_16x16x32_bf16 v[76:79], v[142:145], v[180:183], v[76:79]
	v_mfma_f32_16x16x32_bf16 v[72:75], v[156:159], v[180:183], v[72:75]
	v_mfma_f32_16x16x32_bf16 v[68:71], v[142:145], v[188:191], v[68:71]
	v_mfma_f32_16x16x32_bf16 v[64:67], v[156:159], v[188:191], v[64:67]
	v_mfma_f32_16x16x32_bf16 v[56:59], v[142:145], v[196:199], v[56:59]
	v_mfma_f32_16x16x32_bf16 v[52:55], v[156:159], v[196:199], v[52:55]
	v_mfma_f32_16x16x32_bf16 v[44:47], v[142:145], v[204:207], v[44:47]
	v_mfma_f32_16x16x32_bf16 v[40:43], v[156:159], v[204:207], v[40:43]
	v_mfma_f32_16x16x32_bf16 v[76:79], v[152:155], v[184:187], v[76:79]
	v_mfma_f32_16x16x32_bf16 v[72:75], v[160:163], v[184:187], v[72:75]
	v_mfma_f32_16x16x32_bf16 v[68:71], v[152:155], v[192:195], v[68:71]
	v_mfma_f32_16x16x32_bf16 v[64:67], v[160:163], v[192:195], v[64:67]
	v_mfma_f32_16x16x32_bf16 v[56:59], v[152:155], v[200:203], v[56:59]
	v_mfma_f32_16x16x32_bf16 v[52:55], v[160:163], v[200:203], v[52:55]
	v_mfma_f32_16x16x32_bf16 v[44:47], v[152:155], v[208:211], v[44:47]
	v_mfma_f32_16x16x32_bf16 v[40:43], v[160:163], v[208:211], v[40:43]
	s_setprio 0
	s_setprio 3
	v_mfma_f32_16x16x32_bf16 v[124:127], v[164:167], v[180:183], v[124:127]
	v_mfma_f32_16x16x32_bf16 v[120:123], v[172:175], v[180:183], v[120:123]
	v_mfma_f32_16x16x32_bf16 v[116:119], v[164:167], v[188:191], v[116:119]
	v_mfma_f32_16x16x32_bf16 v[112:115], v[172:175], v[188:191], v[112:115]
	v_mfma_f32_16x16x32_bf16 v[108:111], v[164:167], v[196:199], v[108:111]
	v_mfma_f32_16x16x32_bf16 v[104:107], v[172:175], v[196:199], v[104:107]
	v_mfma_f32_16x16x32_bf16 v[100:103], v[164:167], v[204:207], v[100:103]
	v_mfma_f32_16x16x32_bf16 v[96:99], v[172:175], v[204:207], v[96:99]
	v_mfma_f32_16x16x32_bf16 v[124:127], v[168:171], v[184:187], v[124:127]
	v_mfma_f32_16x16x32_bf16 v[120:123], v[176:179], v[184:187], v[120:123]
	v_mfma_f32_16x16x32_bf16 v[116:119], v[168:171], v[192:195], v[116:119]
	v_mfma_f32_16x16x32_bf16 v[112:115], v[176:179], v[192:195], v[112:115]
	v_mfma_f32_16x16x32_bf16 v[108:111], v[168:171], v[200:203], v[108:111]
	v_mfma_f32_16x16x32_bf16 v[104:107], v[176:179], v[200:203], v[104:107]
	v_mfma_f32_16x16x32_bf16 v[100:103], v[168:171], v[208:211], v[100:103]
	s_setprio 3
	s_barrier
; #define PG8_STAGE(bufoff, gbase, voff) do { _Pragma("unroll") for (int _i = 0; _i < 2; ++_i) \
;         __builtin_amdgcn_global_load_lds((const unsigned*)((const char*)(gbase) + (voff)[_i]), (PG8_LAS unsigned*)(lds + (bufoff) + ldsw + _i * 8192), 16, 0, 0); } while (0)
; #define PG8_LDA(dst, b, h) do { _Pragma("unroll") for (int m = 0; m < 4; ++m) _Pragma("unroll") for (int k = 0; k < 2; ++k) dst[m][k] = *(const PG8_LAS bf16x8*)(lds + PG8_SA(b, h) + aoff + m * 2048 + k * 1024); } while (0)
; #define PG8_MMA(ai, bj, At, Bt) do { __builtin_amdgcn_s_setprio(1); _Pragma("unroll") for (int m = 0; m < 4; ++m) _Pragma("unroll") for (int n = 0; n < 2; ++n) _Pragma("unroll") for (int k = 0; k < 2; ++k) \
;         acc[ai][bj][m][n] = __builtin_amdgcn_mfma_f32_16x16x32_bf16(Bt[n][k], At[m][k], acc[ai][bj][m][n], 0, 0, 0); __builtin_amdgcn_s_setprio(0); } while (0)
; #define PG8_WAIT_V(n) asm volatile("s_waitcnt vmcnt(" #n ")" ::: "memory")
; #define PG8_WAIT_L(n) asm volatile("s_waitcnt lgkmcnt(" #n ")" ::: "memory")
; #define PG8_BAR __builtin_amdgcn_s_barrier()
; #define PG8_SCHED __builtin_amdgcn_sched_barrier(0)
; template <class Epi, class Sched, bool ALIGN_EPI = false, bool SP2 = false>
; __device__ __forceinline__ void gemm_phase(PG8_LAS unsigned char* lds, const Gemm g, const Sched& S, const Epi& E, const int wv  ) {
;     ...
;             PG8_LDA(At, 1, 1); PG8_STAGE(PG8_SB(1, 0), b3, voffB); PG8_STAGE(PG8_SB(1, 1), b3 + hstepB, voffB); PG8_STAGE(PG8_SA(1, 0), a3, voffA);
;             PG8_WAIT_V(8); PG8_WAIT_L(0); PG8_BAR; PG8_MMA(1, 0, At, B0); PG8_MMA(1, 1, At, B1); PG8_BAR; PG8_SCHED;
;     ...
;         if constexpr (ALIGN_EPI) { if (wr == 0) PG8_BAR; }
	v_mfma_f32_16x16x32_bf16 v[96:99], v[176:179], v[208:211], v[96:99]
	s_setprio 0
	s_add_i32 s62, s93, s69
	v_lshl_add_u64 v[212:213], v[212:213], 0, s[8:9]
	s_mov_b32 m0, s62
	ds_read_b128 v[180:183], v150 offset:49152
	ds_read_b128 v[184:187], v150 offset:50176
	ds_read_b128 v[188:191], v150 offset:51200
	ds_read_b128 v[192:195], v150 offset:52224
	ds_read_b128 v[196:199], v150 offset:53248
	ds_read_b128 v[200:203], v150 offset:54272
	ds_read_b128 v[204:207], v150 offset:55296
	ds_read_b128 v[208:211], v150 offset:56320
	global_load_lds_dwordx4 v[212:213], off
	s_add_i32 m0, s62, 0x2000
	s_add_u32 s60, s60, 0x100080
	v_lshl_add_u64 v[212:213], v[214:215], 0, s[8:9]
	s_addc_u32 s61, s61, 0
	s_add_i32 s62, s94, s69
	global_load_lds_dwordx4 v[212:213], off
	v_lshl_add_u64 v[212:213], s[60:61], 0, v[132:133]
	s_mov_b32 m0, s62
	s_nop 0
	global_load_lds_dwordx4 v[212:213], off
	v_lshl_add_u64 v[212:213], s[60:61], 0, v[128:129]
	s_add_i32 m0, s62, 0x2000
	s_nop 0
	global_load_lds_dwordx4 v[212:213], off
	v_lshl_add_u64 v[212:213], v[216:217], 0, s[8:9]
	s_mov_b32 m0, s81
	s_nop 0
	global_load_lds_dwordx4 v[212:213], off
	v_lshl_add_u64 v[212:213], v[218:219], 0, s[8:9]
	s_mov_b32 m0, s82
	s_nop 0
	global_load_lds_dwordx4 v[212:213], off
	s_waitcnt vmcnt(8)
	s_waitcnt lgkmcnt(0)
	s_barrier
	s_setprio 3
	s_waitcnt lgkmcnt(0)
	v_mfma_f32_16x16x32_bf16 v[28:31], v[142:145], v[180:183], v[28:31]
	v_mfma_f32_16x16x32_bf16 v[24:27], v[156:159], v[180:183], v[24:27]
	v_mfma_f32_16x16x32_bf16 v[20:23], v[142:145], v[188:191], v[20:23]
	v_mfma_f32_16x16x32_bf16 v[16:19], v[156:159], v[188:191], v[16:19]
	v_mfma_f32_16x16x32_bf16 v[12:15], v[142:145], v[196:199], v[12:15]
	v_mfma_f32_16x16x32_bf16 v[8:11], v[156:159], v[196:199], v[8:11]
	v_mfma_f32_16x16x32_bf16 v[4:7], v[142:145], v[204:207], v[4:7]
	v_mfma_f32_16x16x32_bf16 v[0:3], v[156:159], v[204:207], v[0:3]
	v_mfma_f32_16x16x32_bf16 v[28:31], v[152:155], v[184:187], v[28:31]
	v_mfma_f32_16x16x32_bf16 v[24:27], v[160:163], v[184:187], v[24:27]
	v_mfma_f32_16x16x32_bf16 v[20:23], v[152:155], v[192:195], v[20:23]
	v_mfma_f32_16x16x32_bf16 v[16:19], v[160:163], v[192:195], v[16:19]
	v_mfma_f32_16x16x32_bf16 v[12:15], v[152:155], v[200:203], v[12:15]
	v_mfma_f32_16x16x32_bf16 v[8:11], v[160:163], v[200:203], v[8:11]
	v_mfma_f32_16x16x32_bf16 v[4:7], v[152:155], v[208:211], v[4:7]
	v_mfma_f32_16x16x32_bf16 v[0:3], v[160:163], v[208:211], v[0:3]
	s_setprio 0
	s_setprio 3
	v_mfma_f32_16x16x32_bf16 v[92:95], v[164:167], v[180:183], v[92:95]
	v_mfma_f32_16x16x32_bf16 v[88:91], v[172:175], v[180:183], v[88:91]
	v_mfma_f32_16x16x32_bf16 v[84:87], v[164:167], v[188:191], v[84:87]
	v_mfma_f32_16x16x32_bf16 v[80:83], v[172:175], v[188:191], v[80:83]
	v_mfma_f32_16x16x32_bf16 v[60:63], v[164:167], v[196:199], v[60:63]
	v_mfma_f32_16x16x32_bf16 v[48:51], v[172:175], v[196:199], v[48:51]
	v_mfma_f32_16x16x32_bf16 v[36:39], v[164:167], v[204:207], v[36:39]
	v_mfma_f32_16x16x32_bf16 v[32:35], v[172:175], v[204:207], v[32:35]
	v_mfma_f32_16x16x32_bf16 v[92:95], v[168:171], v[184:187], v[92:95]
	v_mfma_f32_16x16x32_bf16 v[88:91], v[176:179], v[184:187], v[88:91]
	v_mfma_f32_16x16x32_bf16 v[84:87], v[168:171], v[192:195], v[84:87]
	v_mfma_f32_16x16x32_bf16 v[80:83], v[176:179], v[192:195], v[80:83]
	v_mfma_f32_16x16x32_bf16 v[60:63], v[168:171], v[200:203], v[60:63]
	v_mfma_f32_16x16x32_bf16 v[48:51], v[176:179], v[200:203], v[48:51]
	v_mfma_f32_16x16x32_bf16 v[36:39], v[168:171], v[208:211], v[36:39]
	s_setprio 3
	s_barrier
	v_mfma_f32_16x16x32_bf16 v[32:35], v[176:179], v[208:211], v[32:35]
	s_setprio 0
	s_add_i32 s92, s92, 2
	s_add_u32 s58, s58, 0x100
	s_addc_u32 s59, s59, 0
	s_add_u32 s90, s90, 0x100
	s_addc_u32 s91, s91, 0
	s_cmp_gt_u32 s92, 61
	s_cbranch_scc0 .LBB0_892
	s_and_b64 vcc, exec, s[10:11]
	s_cbranch_vccz .LBB0_895
	s_barrier

; #define PG8_STAGE(bufoff, gbase, voff) do { _Pragma("unroll") for (int _i = 0; _i < 2; ++_i) \
;         __builtin_amdgcn_global_load_lds((const unsigned*)((const char*)(gbase) + (voff)[_i]), (PG8_LAS unsigned*)(lds + (bufoff) + ldsw + _i * 8192), 16, 0, 0); } while (0)
; #define PG8_LDA(dst, b, h) do { _Pragma("unroll") for (int m = 0; m < 4; ++m) _Pragma("unroll") for (int k = 0; k < 2; ++k) dst[m][k] = *(const PG8_LAS bf16x8*)(lds + PG8_SA(b, h) + aoff + m * 2048 + k * 1024); } while (0)
; #define PG8_LDB(dst, b, h) do { _Pragma("unroll") for (int n = 0; n < 2; ++n) _Pragma("unroll") for (int k = 0; k < 2; ++k) dst[n][k] = *(const PG8_LAS bf16x8*)(lds + PG8_SB(b, h) + boff + n * 2048 + k * 1024); } while (0)
; #define PG8_MMA(ai, bj, At, Bt) do { __builtin_amdgcn_s_setprio(1); _Pragma("unroll") for (int m = 0; m < 4; ++m) _Pragma("unroll") for (int n = 0; n < 2; ++n) _Pragma("unroll") for (int k = 0; k < 2; ++k) \
;         acc[ai][bj][m][n] = __builtin_amdgcn_mfma_f32_16x16x32_bf16(Bt[n][k], At[m][k], acc[ai][bj][m][n], 0, 0, 0); __builtin_amdgcn_s_setprio(0); } while (0)
; #define PG8_WAIT_V(n) asm volatile("s_waitcnt vmcnt(" #n ")" ::: "memory")
; #define PG8_WAIT_L(n) asm volatile("s_waitcnt lgkmcnt(" #n ")" ::: "memory")
; #define PG8_BAR __builtin_amdgcn_s_barrier()
; template <class Epi, class Sched, bool ALIGN_EPI = false, bool SP2 = false>
; __device__ __forceinline__ void gemm_phase(PG8_LAS unsigned char* lds, const Gemm g, const Sched& S, const Epi& E, const int wv  ) {
;     ...
;             const char* a1 = cA + (size_t)(t + 1) * kstep;
;             const char* a2 = last ? nA : cA + (size_t)(t + 2) * kstep; const char* b2 = last ? nB : cB + (size_t)(t + 2) * kstep;
;             const char* a3 = a2 + kstep; const char* b3 = b2 + kstep;
;             if (last && has_next) S.a_ready(nxt);
;             if constexpr (SP2) {
;             PG8_LDB(B0, 0, 0); PG8_LDB(B1, 0, 1); PG8_SCHED; PG8_LDA(At, 0, 0); PG8_STAGE(PG8_SA(1, 1), a1 + hstepA, voffA);
;             PG8_WAIT_V(8); PG8_WAIT_L(0); PG8_BAR; PG8_MMA(0, 0, At, B0); PG8_MMA(0, 1, At, B1); PG8_BAR; PG8_SCHED;
;             PG8_LDA(At, 0, 1); PG8_STAGE(PG8_SB(0, 0), b2, voffB); PG8_STAGE(PG8_SB(0, 1), b2 + hstepB, voffB); PG8_STAGE(PG8_SA(0, 0), a2, voffA);
;             PG8_WAIT_V(8); PG8_WAIT_L(0); PG8_BAR; PG8_MMA(1, 0, At, B0); PG8_MMA(1, 1, At, B1); PG8_BAR; PG8_SCHED;
.LBB0_1049:
	ds_read_b128 v[146:149], v152
	ds_read_b128 v[156:159], v152 offset:1024
	ds_read_b128 v[160:163], v152 offset:2048
	ds_read_b128 v[164:167], v152 offset:3072
	ds_read_b128 v[168:171], v153
	ds_read_b128 v[172:175], v153 offset:1024
	ds_read_b128 v[176:179], v153 offset:2048
	ds_read_b128 v[180:183], v153 offset:3072
	s_add_u32 s60, s58, 0xfffc0080
	s_addc_u32 s61, s59, -1
	s_cmp_eq_u32 s87, 12
	s_cselect_b32 s63, s51, s61
	s_cselect_b32 s62, s83, s60
	s_cselect_b32 s61, s49, s86
	s_cselect_b32 s60, s84, s85
	v_lshl_add_u64 v[216:217], s[58:59], 0, v[138:139]
	s_add_i32 m0, s68, 0xc000
	ds_read_b128 v[184:187], v154
	ds_read_b128 v[188:191], v154 offset:1024
	ds_read_b128 v[192:195], v154 offset:2048
	ds_read_b128 v[196:199], v154 offset:3072
	ds_read_b128 v[200:203], v154 offset:4096
	ds_read_b128 v[204:207], v154 offset:5120
	ds_read_b128 v[208:211], v154 offset:6144
	ds_read_b128 v[212:215], v154 offset:7168
	global_load_lds_dwordx4 v[216:217], off
	v_lshl_add_u64 v[216:217], s[58:59], 0, v[140:141]
	s_add_i32 m0, s68, 0xe000
	s_nop 0
	global_load_lds_dwordx4 v[216:217], off
	s_waitcnt vmcnt(8)
	s_waitcnt lgkmcnt(0)
	s_barrier
	s_setprio 3
	s_waitcnt lgkmcnt(0)
	v_mfma_f32_16x16x32_bf16 v[76:79], v[146:149], v[184:187], v[76:79]
	v_mfma_f32_16x16x32_bf16 v[72:75], v[160:163], v[184:187], v[72:75]
	v_mfma_f32_16x16x32_bf16 v[68:71], v[146:149], v[192:195], v[68:71]
	v_mfma_f32_16x16x32_bf16 v[64:67], v[160:163], v[192:195], v[64:67]
	v_mfma_f32_16x16x32_bf16 v[56:59], v[146:149], v[200:203], v[56:59]
	v_mfma_f32_16x16x32_bf16 v[52:55], v[160:163], v[200:203], v[52:55]
	v_mfma_f32_16x16x32_bf16 v[44:47], v[146:149], v[208:211], v[44:47]
	v_mfma_f32_16x16x32_bf16 v[40:43], v[160:163], v[208:211], v[40:43]
	v_mfma_f32_16x16x32_bf16 v[76:79], v[156:159], v[188:191], v[76:79]
	v_mfma_f32_16x16x32_bf16 v[72:75], v[164:167], v[188:191], v[72:75]
	v_mfma_f32_16x16x32_bf16 v[68:71], v[156:159], v[196:199], v[68:71]
	v_mfma_f32_16x16x32_bf16 v[64:67], v[164:167], v[196:199], v[64:67]
	v_mfma_f32_16x16x32_bf16 v[56:59], v[156:159], v[204:207], v[56:59]
	v_mfma_f32_16x16x32_bf16 v[52:55], v[164:167], v[204:207], v[52:55]
	v_mfma_f32_16x16x32_bf16 v[44:47], v[156:159], v[212:215], v[44:47]
	v_mfma_f32_16x16x32_bf16 v[40:43], v[164:167], v[212:215], v[40:43]
	s_setprio 0
	s_setprio 3
	v_mfma_f32_16x16x32_bf16 v[124:127], v[168:171], v[184:187], v[124:127]
	v_mfma_f32_16x16x32_bf16 v[120:123], v[176:179], v[184:187], v[120:123]
	v_mfma_f32_16x16x32_bf16 v[116:119], v[168:171], v[192:195], v[116:119]
	v_mfma_f32_16x16x32_bf16 v[112:115], v[176:179], v[192:195], v[112:115]
	v_mfma_f32_16x16x32_bf16 v[108:111], v[168:171], v[200:203], v[108:111]
	v_mfma_f32_16x16x32_bf16 v[104:107], v[176:179], v[200:203], v[104:107]
	v_mfma_f32_16x16x32_bf16 v[100:103], v[168:171], v[208:211], v[100:103]
	v_mfma_f32_16x16x32_bf16 v[96:99], v[176:179], v[208:211], v[96:99]
	v_mfma_f32_16x16x32_bf16 v[124:127], v[172:175], v[188:191], v[124:127]
	v_mfma_f32_16x16x32_bf16 v[120:123], v[180:183], v[188:191], v[120:123]
	v_mfma_f32_16x16x32_bf16 v[116:119], v[172:175], v[196:199], v[116:119]
	v_mfma_f32_16x16x32_bf16 v[112:115], v[180:183], v[196:199], v[112:115]
	v_mfma_f32_16x16x32_bf16 v[108:111], v[172:175], v[204:207], v[108:111]
	v_mfma_f32_16x16x32_bf16 v[104:107], v[180:183], v[204:207], v[104:107]
	v_mfma_f32_16x16x32_bf16 v[100:103], v[172:175], v[212:215], v[100:103]
	s_setprio 3
	s_barrier
	v_mfma_f32_16x16x32_bf16 v[96:99], v[180:183], v[212:215], v[96:99]
	s_setprio 0
	s_add_i32 s90, s77, s67
	v_lshl_add_u64 v[216:217], s[60:61], 0, v[130:131]
	s_mov_b32 m0, s90
	ds_read_b128 v[184:187], v154 offset:16384
	ds_read_b128 v[188:191], v154 offset:17408
	ds_read_b128 v[192:195], v154 offset:18432
	ds_read_b128 v[196:199], v154 offset:19456
	ds_read_b128 v[200:203], v154 offset:20480
	ds_read_b128 v[204:207], v154 offset:21504
	ds_read_b128 v[208:211], v154 offset:22528
	ds_read_b128 v[212:215], v154 offset:23552
	global_load_lds_dwordx4 v[216:217], off
	s_add_i32 m0, s90, 0x2000
	s_add_u32 s90, s60, 0x40000
	v_lshl_add_u64 v[218:219], s[60:61], 0, v[134:135]
	s_addc_u32 s91, s61, 0
	s_add_i32 s92, s78, s67
	global_load_lds_dwordx4 v[218:219], off
	v_lshl_add_u64 v[220:221], s[90:91], 0, v[130:131]
	s_mov_b32 m0, s92
	v_lshl_add_u64 v[222:223], s[62:63], 0, v[132:133]
	global_load_lds_dwordx4 v[220:221], off
	v_lshl_add_u64 v[220:221], s[90:91], 0, v[134:135]
	s_add_i32 m0, s92, 0x2000
	s_nop 0
	global_load_lds_dwordx4 v[220:221], off
	v_lshl_add_u64 v[220:221], s[62:63], 0, v[128:129]
	s_mov_b32 m0, s68
	s_nop 0
	global_load_lds_dwordx4 v[220:221], off
	s_mov_b32 m0, s69
	s_nop 0
	global_load_lds_dwordx4 v[222:223], off
	s_waitcnt vmcnt(8)
	s_waitcnt lgkmcnt(0)
	s_barrier
; #define PG8_STAGE(bufoff, gbase, voff) do { _Pragma("unroll") for (int _i = 0; _i < 2; ++_i) \
;         __builtin_amdgcn_global_load_lds((const unsigned*)((const char*)(gbase) + (voff)[_i]), (PG8_LAS unsigned*)(lds + (bufoff) + ldsw + _i * 8192), 16, 0, 0); } while (0)
; #define PG8_LDA(dst, b, h) do { _Pragma("unroll") for (int m = 0; m < 4; ++m) _Pragma("unroll") for (int k = 0; k < 2; ++k) dst[m][k] = *(const PG8_LAS bf16x8*)(lds + PG8_SA(b, h) + aoff + m * 2048 + k * 1024); } while (0)
; #define PG8_LDB(dst, b, h) do { _Pragma("unroll") for (int n = 0; n < 2; ++n) _Pragma("unroll") for (int k = 0; k < 2; ++k) dst[n][k] = *(const PG8_LAS bf16x8*)(lds + PG8_SB(b, h) + boff + n * 2048 + k * 1024); } while (0)
; #define PG8_MMA(ai, bj, At, Bt) do { __builtin_amdgcn_s_setprio(1); _Pragma("unroll") for (int m = 0; m < 4; ++m) _Pragma("unroll") for (int n = 0; n < 2; ++n) _Pragma("unroll") for (int k = 0; k < 2; ++k) \
;         acc[ai][bj][m][n] = __builtin_amdgcn_mfma_f32_16x16x32_bf16(Bt[n][k], At[m][k], acc[ai][bj][m][n], 0, 0, 0); __builtin_amdgcn_s_setprio(0); } while (0)
; #define PG8_WAIT_V(n) asm volatile("s_waitcnt vmcnt(" #n ")" ::: "memory")
; #define PG8_WAIT_L(n) asm volatile("s_waitcnt lgkmcnt(" #n ")" ::: "memory")
; #define PG8_BAR __builtin_amdgcn_s_barrier()
; #define PG8_SCHED __builtin_amdgcn_sched_barrier(0)
; template <class Epi, class Sched, bool ALIGN_EPI = false, bool SP2 = false>
; __device__ __forceinline__ void gemm_phase(PG8_LAS unsigned char* lds, const Gemm g, const Sched& S, const Epi& E, const int wv  ) {
;     ...
;             PG8_LDA(At, 0, 1); PG8_STAGE(PG8_SB(0, 0), b2, voffB); PG8_STAGE(PG8_SB(0, 1), b2 + hstepB, voffB); PG8_STAGE(PG8_SA(0, 0), a2, voffA);
;             PG8_WAIT_V(8); PG8_WAIT_L(0); PG8_BAR; PG8_MMA(1, 0, At, B0); PG8_MMA(1, 1, At, B1); PG8_BAR; PG8_SCHED;
;             PG8_LDB(B0, 1, 0); PG8_LDB(B1, 1, 1); PG8_SCHED; PG8_LDA(At, 1, 0); PG8_STAGE(PG8_SA(0, 1), a2 + hstepA, voffA);
;             PG8_WAIT_V(8); PG8_WAIT_L(0); PG8_BAR; PG8_MMA(0, 0, At, B0); PG8_MMA(0, 1, At, B1); PG8_BAR; PG8_SCHED;
	s_setprio 3
	s_waitcnt lgkmcnt(0)
	v_mfma_f32_16x16x32_bf16 v[28:31], v[146:149], v[184:187], v[28:31]
	v_mfma_f32_16x16x32_bf16 v[24:27], v[160:163], v[184:187], v[24:27]
	v_mfma_f32_16x16x32_bf16 v[20:23], v[146:149], v[192:195], v[20:23]
	v_mfma_f32_16x16x32_bf16 v[16:19], v[160:163], v[192:195], v[16:19]
	v_mfma_f32_16x16x32_bf16 v[12:15], v[146:149], v[200:203], v[12:15]
	v_mfma_f32_16x16x32_bf16 v[8:11], v[160:163], v[200:203], v[8:11]
	v_mfma_f32_16x16x32_bf16 v[4:7], v[146:149], v[208:211], v[4:7]
	v_mfma_f32_16x16x32_bf16 v[0:3], v[160:163], v[208:211], v[0:3]
	v_mfma_f32_16x16x32_bf16 v[28:31], v[156:159], v[188:191], v[28:31]
	v_mfma_f32_16x16x32_bf16 v[24:27], v[164:167], v[188:191], v[24:27]
	v_mfma_f32_16x16x32_bf16 v[20:23], v[156:159], v[196:199], v[20:23]
	v_mfma_f32_16x16x32_bf16 v[16:19], v[164:167], v[196:199], v[16:19]
	v_mfma_f32_16x16x32_bf16 v[12:15], v[156:159], v[204:207], v[12:15]
	v_mfma_f32_16x16x32_bf16 v[8:11], v[164:167], v[204:207], v[8:11]
	v_mfma_f32_16x16x32_bf16 v[4:7], v[156:159], v[212:215], v[4:7]
	v_mfma_f32_16x16x32_bf16 v[0:3], v[164:167], v[212:215], v[0:3]
	s_setprio 0
	s_setprio 3
	v_mfma_f32_16x16x32_bf16 v[92:95], v[168:171], v[184:187], v[92:95]
	v_mfma_f32_16x16x32_bf16 v[88:91], v[176:179], v[184:187], v[88:91]
	v_mfma_f32_16x16x32_bf16 v[84:87], v[168:171], v[192:195], v[84:87]
	v_mfma_f32_16x16x32_bf16 v[80:83], v[176:179], v[192:195], v[80:83]
	v_mfma_f32_16x16x32_bf16 v[60:63], v[168:171], v[200:203], v[60:63]
	v_mfma_f32_16x16x32_bf16 v[48:51], v[176:179], v[200:203], v[48:51]
	v_mfma_f32_16x16x32_bf16 v[36:39], v[168:171], v[208:211], v[36:39]
	v_mfma_f32_16x16x32_bf16 v[32:35], v[176:179], v[208:211], v[32:35]
	v_mfma_f32_16x16x32_bf16 v[92:95], v[172:175], v[188:191], v[92:95]
	v_mfma_f32_16x16x32_bf16 v[88:91], v[180:183], v[188:191], v[88:91]
	v_mfma_f32_16x16x32_bf16 v[84:87], v[172:175], v[196:199], v[84:87]
	v_mfma_f32_16x16x32_bf16 v[80:83], v[180:183], v[196:199], v[80:83]
	v_mfma_f32_16x16x32_bf16 v[60:63], v[172:175], v[204:207], v[60:63]
	v_mfma_f32_16x16x32_bf16 v[48:51], v[180:183], v[204:207], v[48:51]
	v_mfma_f32_16x16x32_bf16 v[36:39], v[172:175], v[212:215], v[36:39]
	s_setprio 3
	s_barrier
	v_mfma_f32_16x16x32_bf16 v[32:35], v[180:183], v[212:215], v[32:35]
	s_setprio 0
	s_add_i32 s90, 0, 0x18000
	v_add_u32_e32 v155, s90, v150
	s_add_i32 s91, 0, 0x1c000
	ds_read_b128 v[146:149], v155
	ds_read_b128 v[156:159], v155 offset:1024
	ds_read_b128 v[160:163], v155 offset:2048
	ds_read_b128 v[164:167], v155 offset:3072
	v_add_u32_e32 v155, s91, v150
	ds_read_b128 v[168:171], v155
	ds_read_b128 v[172:175], v155 offset:1024
	ds_read_b128 v[176:179], v155 offset:2048
	ds_read_b128 v[180:183], v155 offset:3072
	s_add_u32 s62, s62, 0x40000
	s_addc_u32 s63, s63, 0
	s_mov_b32 m0, s70
	v_lshl_add_u64 v[224:225], s[62:63], 0, v[128:129]
	ds_read_b128 v[184:187], v154 offset:32768
	ds_read_b128 v[188:191], v154 offset:33792
	ds_read_b128 v[192:195], v154 offset:34816
	ds_read_b128 v[196:199], v154 offset:35840
	ds_read_b128 v[200:203], v154 offset:36864
	ds_read_b128 v[204:207], v154 offset:37888
	ds_read_b128 v[208:211], v154 offset:38912
	ds_read_b128 v[212:215], v154 offset:39936
	global_load_lds_dwordx4 v[224:225], off
	v_lshl_add_u64 v[224:225], s[62:63], 0, v[132:133]
	s_mov_b32 m0, s71
	s_nop 0
	global_load_lds_dwordx4 v[224:225], off
	s_waitcnt vmcnt(8)
	s_waitcnt lgkmcnt(0)
	s_barrier
	s_setprio 3
	s_waitcnt lgkmcnt(0)
	v_mfma_f32_16x16x32_bf16 v[76:79], v[146:149], v[184:187], v[76:79]
	v_mfma_f32_16x16x32_bf16 v[72:75], v[160:163], v[184:187], v[72:75]
	v_mfma_f32_16x16x32_bf16 v[68:71], v[146:149], v[192:195], v[68:71]
	v_mfma_f32_16x16x32_bf16 v[64:67], v[160:163], v[192:195], v[64:67]
	v_mfma_f32_16x16x32_bf16 v[56:59], v[146:149], v[200:203], v[56:59]
	v_mfma_f32_16x16x32_bf16 v[52:55], v[160:163], v[200:203], v[52:55]
	v_mfma_f32_16x16x32_bf16 v[44:47], v[146:149], v[208:211], v[44:47]
	v_mfma_f32_16x16x32_bf16 v[40:43], v[160:163], v[208:211], v[40:43]
	v_mfma_f32_16x16x32_bf16 v[76:79], v[156:159], v[188:191], v[76:79]
	v_mfma_f32_16x16x32_bf16 v[72:75], v[164:167], v[188:191], v[72:75]
	v_mfma_f32_16x16x32_bf16 v[68:71], v[156:159], v[196:199], v[68:71]
	v_mfma_f32_16x16x32_bf16 v[64:67], v[164:167], v[196:199], v[64:67]
	v_mfma_f32_16x16x32_bf16 v[56:59], v[156:159], v[204:207], v[56:59]
	v_mfma_f32_16x16x32_bf16 v[52:55], v[164:167], v[204:207], v[52:55]
	v_mfma_f32_16x16x32_bf16 v[44:47], v[156:159], v[212:215], v[44:47]
	v_mfma_f32_16x16x32_bf16 v[40:43], v[164:167], v[212:215], v[40:43]
	s_setprio 0
	s_setprio 3
	v_mfma_f32_16x16x32_bf16 v[124:127], v[168:171], v[184:187], v[124:127]
	v_mfma_f32_16x16x32_bf16 v[120:123], v[176:179], v[184:187], v[120:123]
	v_mfma_f32_16x16x32_bf16 v[116:119], v[168:171], v[192:195], v[116:119]
	v_mfma_f32_16x16x32_bf16 v[112:115], v[176:179], v[192:195], v[112:115]
	v_mfma_f32_16x16x32_bf16 v[108:111], v[168:171], v[200:203], v[108:111]
	v_mfma_f32_16x16x32_bf16 v[104:107], v[176:179], v[200:203], v[104:107]
	v_mfma_f32_16x16x32_bf16 v[100:103], v[168:171], v[208:211], v[100:103]
	v_mfma_f32_16x16x32_bf16 v[96:99], v[176:179], v[208:211], v[96:99]
	v_mfma_f32_16x16x32_bf16 v[124:127], v[172:175], v[188:191], v[124:127]
	v_mfma_f32_16x16x32_bf16 v[120:123], v[180:183], v[188:191], v[120:123]
	v_mfma_f32_16x16x32_bf16 v[116:119], v[172:175], v[196:199], v[116:119]
	v_mfma_f32_16x16x32_bf16 v[112:115], v[180:183], v[196:199], v[112:115]
	v_mfma_f32_16x16x32_bf16 v[108:111], v[172:175], v[204:207], v[108:111]
	v_mfma_f32_16x16x32_bf16 v[104:107], v[180:183], v[204:207], v[104:107]
	v_mfma_f32_16x16x32_bf16 v[100:103], v[172:175], v[212:215], v[100:103]
	s_setprio 3
	s_barrier
; #define PG8_STAGE(bufoff, gbase, voff) do { _Pragma("unroll") for (int _i = 0; _i < 2; ++_i) \
;         __builtin_amdgcn_global_load_lds((const unsigned*)((const char*)(gbase) + (voff)[_i]), (PG8_LAS unsigned*)(lds + (bufoff) + ldsw + _i * 8192), 16, 0, 0); } while (0)
; #define PG8_LDA(dst, b, h) do { _Pragma("unroll") for (int m = 0; m < 4; ++m) _Pragma("unroll") for (int k = 0; k < 2; ++k) dst[m][k] = *(const PG8_LAS bf16x8*)(lds + PG8_SA(b, h) + aoff + m * 2048 + k * 1024); } while (0)
; #define PG8_MMA(ai, bj, At, Bt) do { __builtin_amdgcn_s_setprio(1); _Pragma("unroll") for (int m = 0; m < 4; ++m) _Pragma("unroll") for (int n = 0; n < 2; ++n) _Pragma("unroll") for (int k = 0; k < 2; ++k) \
;         acc[ai][bj][m][n] = __builtin_amdgcn_mfma_f32_16x16x32_bf16(Bt[n][k], At[m][k], acc[ai][bj][m][n], 0, 0, 0); __builtin_amdgcn_s_setprio(0); } while (0)
; #define PG8_WAIT_V(n) asm volatile("s_waitcnt vmcnt(" #n ")" ::: "memory")
; #define PG8_WAIT_L(n) asm volatile("s_waitcnt lgkmcnt(" #n ")" ::: "memory")
; #define PG8_BAR __builtin_amdgcn_s_barrier()
; #define PG8_SCHED __builtin_amdgcn_sched_barrier(0)
; template <class Epi, class Sched, bool ALIGN_EPI = false, bool SP2 = false>
; __device__ __forceinline__ void gemm_phase(PG8_LAS unsigned char* lds, const Gemm g, const Sched& S, const Epi& E, const int wv  ) {
;     ...
;             PG8_LDA(At, 1, 1); PG8_STAGE(PG8_SB(1, 0), b3, voffB); PG8_STAGE(PG8_SB(1, 1), b3 + hstepB, voffB); PG8_STAGE(PG8_SA(1, 0), a3, voffA);
;             PG8_WAIT_V(8); PG8_WAIT_L(0); PG8_BAR; PG8_MMA(1, 0, At, B0); PG8_MMA(1, 1, At, B1); PG8_BAR; PG8_SCHED;
;     ...
;         if constexpr (ALIGN_EPI) { if (wr == 0) PG8_BAR; }
	v_mfma_f32_16x16x32_bf16 v[96:99], v[180:183], v[212:215], v[96:99]
	s_setprio 0
	s_add_i32 s62, s90, s67
	v_lshl_add_u64 v[216:217], v[216:217], 0, s[10:11]
	s_mov_b32 m0, s62
	ds_read_b128 v[184:187], v154 offset:49152
	ds_read_b128 v[188:191], v154 offset:50176
	ds_read_b128 v[192:195], v154 offset:51200
	ds_read_b128 v[196:199], v154 offset:52224
	ds_read_b128 v[200:203], v154 offset:53248
	ds_read_b128 v[204:207], v154 offset:54272
	ds_read_b128 v[208:211], v154 offset:55296
	ds_read_b128 v[212:215], v154 offset:56320
	global_load_lds_dwordx4 v[216:217], off
	s_add_i32 m0, s62, 0x2000
	s_add_u32 s60, s60, 0x40080
	v_lshl_add_u64 v[216:217], v[218:219], 0, s[10:11]
	s_addc_u32 s61, s61, 0
	s_add_i32 s62, s91, s67
	global_load_lds_dwordx4 v[216:217], off
	v_lshl_add_u64 v[216:217], s[60:61], 0, v[130:131]
	s_mov_b32 m0, s62
	s_nop 0
	global_load_lds_dwordx4 v[216:217], off
	v_lshl_add_u64 v[216:217], s[60:61], 0, v[134:135]
	s_add_i32 m0, s62, 0x2000
	s_nop 0
	global_load_lds_dwordx4 v[216:217], off
	v_lshl_add_u64 v[216:217], v[220:221], 0, s[10:11]
	s_mov_b32 m0, s74
	s_nop 0
	global_load_lds_dwordx4 v[216:217], off
	v_lshl_add_u64 v[216:217], v[222:223], 0, s[10:11]
	s_mov_b32 m0, s75
	s_nop 0
	global_load_lds_dwordx4 v[216:217], off
	s_waitcnt vmcnt(8)
	s_waitcnt lgkmcnt(0)
	s_barrier
	s_setprio 3
	s_waitcnt lgkmcnt(0)
	v_mfma_f32_16x16x32_bf16 v[28:31], v[146:149], v[184:187], v[28:31]
	v_mfma_f32_16x16x32_bf16 v[24:27], v[160:163], v[184:187], v[24:27]
	v_mfma_f32_16x16x32_bf16 v[20:23], v[146:149], v[192:195], v[20:23]
	v_mfma_f32_16x16x32_bf16 v[16:19], v[160:163], v[192:195], v[16:19]
	v_mfma_f32_16x16x32_bf16 v[12:15], v[146:149], v[200:203], v[12:15]
	v_mfma_f32_16x16x32_bf16 v[8:11], v[160:163], v[200:203], v[8:11]
	v_mfma_f32_16x16x32_bf16 v[4:7], v[146:149], v[208:211], v[4:7]
	v_mfma_f32_16x16x32_bf16 v[0:3], v[160:163], v[208:211], v[0:3]
	v_mfma_f32_16x16x32_bf16 v[28:31], v[156:159], v[188:191], v[28:31]
	v_mfma_f32_16x16x32_bf16 v[24:27], v[164:167], v[188:191], v[24:27]
	v_mfma_f32_16x16x32_bf16 v[20:23], v[156:159], v[196:199], v[20:23]
	v_mfma_f32_16x16x32_bf16 v[16:19], v[164:167], v[196:199], v[16:19]
	v_mfma_f32_16x16x32_bf16 v[12:15], v[156:159], v[204:207], v[12:15]
	v_mfma_f32_16x16x32_bf16 v[8:11], v[164:167], v[204:207], v[8:11]
	v_mfma_f32_16x16x32_bf16 v[4:7], v[156:159], v[212:215], v[4:7]
	v_mfma_f32_16x16x32_bf16 v[0:3], v[164:167], v[212:215], v[0:3]
	s_setprio 0
	s_setprio 3
	v_mfma_f32_16x16x32_bf16 v[92:95], v[168:171], v[184:187], v[92:95]
	v_mfma_f32_16x16x32_bf16 v[88:91], v[176:179], v[184:187], v[88:91]
	v_mfma_f32_16x16x32_bf16 v[84:87], v[168:171], v[192:195], v[84:87]
	v_mfma_f32_16x16x32_bf16 v[80:83], v[176:179], v[192:195], v[80:83]
	v_mfma_f32_16x16x32_bf16 v[60:63], v[168:171], v[200:203], v[60:63]
	v_mfma_f32_16x16x32_bf16 v[48:51], v[176:179], v[200:203], v[48:51]
	v_mfma_f32_16x16x32_bf16 v[36:39], v[168:171], v[208:211], v[36:39]
	v_mfma_f32_16x16x32_bf16 v[32:35], v[176:179], v[208:211], v[32:35]
	v_mfma_f32_16x16x32_bf16 v[92:95], v[172:175], v[188:191], v[92:95]
	v_mfma_f32_16x16x32_bf16 v[88:91], v[180:183], v[188:191], v[88:91]
	v_mfma_f32_16x16x32_bf16 v[84:87], v[172:175], v[196:199], v[84:87]
	v_mfma_f32_16x16x32_bf16 v[80:83], v[180:183], v[196:199], v[80:83]
	v_mfma_f32_16x16x32_bf16 v[60:63], v[172:175], v[204:207], v[60:63]
	v_mfma_f32_16x16x32_bf16 v[48:51], v[180:183], v[204:207], v[48:51]
	v_mfma_f32_16x16x32_bf16 v[36:39], v[172:175], v[212:215], v[36:39]
	s_setprio 3
	s_barrier
	v_mfma_f32_16x16x32_bf16 v[32:35], v[180:183], v[212:215], v[32:35]
	s_setprio 0
	s_add_i32 s87, s87, 2
	s_add_u32 s58, s58, 0x100
	s_addc_u32 s59, s59, 0
	s_add_u32 s85, s85, 0x100
	s_addc_u32 s86, s86, 0
	s_cmp_gt_u32 s87, 13
	s_cbranch_scc0 .LBB0_1049
	s_and_b64 vcc, exec, s[12:13]
	s_cbranch_vccz .LBB0_1052
	s_barrier

; #define PG8_STAGE(bufoff, gbase, voff) do { _Pragma("unroll") for (int _i = 0; _i < 2; ++_i) \
;         __builtin_amdgcn_global_load_lds((const unsigned*)((const char*)(gbase) + (voff)[_i]), (PG8_LAS unsigned*)(lds + (bufoff) + ldsw + _i * 8192), 16, 0, 0); } while (0)
; #define PG8_LDA(dst, b, h) do { _Pragma("unroll") for (int m = 0; m < 4; ++m) _Pragma("unroll") for (int k = 0; k < 2; ++k) dst[m][k] = *(const PG8_LAS bf16x8*)(lds + PG8_SA(b, h) + aoff + m * 2048 + k * 1024); } while (0)
; #define PG8_LDB(dst, b, h) do { _Pragma("unroll") for (int n = 0; n < 2; ++n) _Pragma("unroll") for (int k = 0; k < 2; ++k) dst[n][k] = *(const PG8_LAS bf16x8*)(lds + PG8_SB(b, h) + boff + n * 2048 + k * 1024); } while (0)
; #define PG8_MMA(ai, bj, At, Bt) do { __builtin_amdgcn_s_setprio(1); _Pragma("unroll") for (int m = 0; m < 4; ++m) _Pragma("unroll") for (int n = 0; n < 2; ++n) _Pragma("unroll") for (int k = 0; k < 2; ++k) \
;         acc[ai][bj][m][n] = __builtin_amdgcn_mfma_f32_16x16x32_bf16(Bt[n][k], At[m][k], acc[ai][bj][m][n], 0, 0, 0); __builtin_amdgcn_s_setprio(0); } while (0)
; #define PG8_WAIT_V(n) asm volatile("s_waitcnt vmcnt(" #n ")" ::: "memory")
; #define PG8_WAIT_L(n) asm volatile("s_waitcnt lgkmcnt(" #n ")" ::: "memory")
; #define PG8_BAR __builtin_amdgcn_s_barrier()
; template <class Epi, class Sched, bool ALIGN_EPI = false, bool SP2 = false>
; __device__ __forceinline__ void gemm_phase(PG8_LAS unsigned char* lds, const Gemm g, const Sched& S, const Epi& E, const int wv  ) {
;     ...
;             const char* a1 = cA + (size_t)(t + 1) * kstep;
;             const char* a2 = last ? nA : cA + (size_t)(t + 2) * kstep; const char* b2 = last ? nB : cB + (size_t)(t + 2) * kstep;
;             const char* a3 = a2 + kstep; const char* b3 = b2 + kstep;
;             if (last && has_next) S.a_ready(nxt);
;             if constexpr (SP2) {
;             PG8_LDB(B0, 0, 0); PG8_LDB(B1, 0, 1); PG8_SCHED; PG8_LDA(At, 0, 0); PG8_STAGE(PG8_SA(1, 1), a1 + hstepA, voffA);
;             PG8_WAIT_V(8); PG8_WAIT_L(0); PG8_BAR; PG8_MMA(0, 0, At, B0); PG8_MMA(0, 1, At, B1); PG8_BAR; PG8_SCHED;
;             PG8_LDA(At, 0, 1); PG8_STAGE(PG8_SB(0, 0), b2, voffB); PG8_STAGE(PG8_SB(0, 1), b2 + hstepB, voffB); PG8_STAGE(PG8_SA(0, 0), a2, voffA);
;             PG8_WAIT_V(8); PG8_WAIT_L(0); PG8_BAR; PG8_MMA(1, 0, At, B0); PG8_MMA(1, 1, At, B1); PG8_BAR; PG8_SCHED;
.LBB0_1187:
	ds_read_b128 v[44:47], v196
	ds_read_b128 v[48:51], v196 offset:1024
	ds_read_b128 v[52:55], v196 offset:2048
	ds_read_b128 v[56:59], v196 offset:3072
	ds_read_b128 v[60:63], v197
	ds_read_b128 v[68:71], v197 offset:1024
	ds_read_b128 v[72:75], v197 offset:2048
	ds_read_b128 v[76:79], v197 offset:3072
	s_add_u32 s68, s66, 0xfff00080
	s_addc_u32 s69, s67, -1
	s_cmp_eq_u32 s94, 60
	s_cselect_b32 s71, s57, s69
	s_cselect_b32 s70, s63, s68
	s_cselect_b32 s69, s55, s93
	s_cselect_b32 s68, s65, s92
	v_lshl_add_u64 v[224:225], s[66:67], 0, v[172:173]
	s_add_i32 m0, s75, 0xc000
	ds_read_b128 v[180:183], v198
	ds_read_b128 v[184:187], v198 offset:1024
	ds_read_b128 v[200:203], v198 offset:2048
	ds_read_b128 v[204:207], v198 offset:3072
	ds_read_b128 v[208:211], v198 offset:4096
	ds_read_b128 v[212:215], v198 offset:5120
	ds_read_b128 v[216:219], v198 offset:6144
	ds_read_b128 v[220:223], v198 offset:7168
	global_load_lds_dwordx4 v[224:225], off
	v_lshl_add_u64 v[224:225], s[66:67], 0, v[174:175]
	s_add_i32 m0, s75, 0xe000
	s_nop 0
	global_load_lds_dwordx4 v[224:225], off
	s_waitcnt vmcnt(8)
	s_waitcnt lgkmcnt(0)
	s_barrier
	s_setprio 3
	s_waitcnt lgkmcnt(0)
	v_mfma_f32_16x16x32_bf16 v[104:107], v[44:47], v[180:183], v[104:107]
	v_mfma_f32_16x16x32_bf16 v[100:103], v[52:55], v[180:183], v[100:103]
	v_mfma_f32_16x16x32_bf16 v[156:159], v[44:47], v[200:203], v[156:159]
	v_mfma_f32_16x16x32_bf16 v[148:151], v[52:55], v[200:203], v[148:151]
	v_mfma_f32_16x16x32_bf16 v[140:143], v[44:47], v[208:211], v[140:143]
	v_mfma_f32_16x16x32_bf16 v[132:135], v[52:55], v[208:211], v[132:135]
	v_mfma_f32_16x16x32_bf16 v[124:127], v[44:47], v[216:219], v[124:127]
	v_mfma_f32_16x16x32_bf16 v[120:123], v[52:55], v[216:219], v[120:123]
	v_mfma_f32_16x16x32_bf16 v[104:107], v[48:51], v[184:187], v[104:107]
	v_mfma_f32_16x16x32_bf16 v[100:103], v[56:59], v[184:187], v[100:103]
	v_mfma_f32_16x16x32_bf16 v[156:159], v[48:51], v[204:207], v[156:159]
	v_mfma_f32_16x16x32_bf16 v[148:151], v[56:59], v[204:207], v[148:151]
	v_mfma_f32_16x16x32_bf16 v[140:143], v[48:51], v[212:215], v[140:143]
	v_mfma_f32_16x16x32_bf16 v[132:135], v[56:59], v[212:215], v[132:135]
	v_mfma_f32_16x16x32_bf16 v[124:127], v[48:51], v[220:223], v[124:127]
	v_mfma_f32_16x16x32_bf16 v[120:123], v[56:59], v[220:223], v[120:123]
	s_setprio 0
	s_setprio 3
	v_mfma_f32_16x16x32_bf16 v[92:95], v[60:63], v[180:183], v[92:95]
	v_mfma_f32_16x16x32_bf16 v[88:91], v[72:75], v[180:183], v[88:91]
	v_mfma_f32_16x16x32_bf16 v[152:155], v[60:63], v[200:203], v[152:155]
	v_mfma_f32_16x16x32_bf16 v[144:147], v[72:75], v[200:203], v[144:147]
	v_mfma_f32_16x16x32_bf16 v[136:139], v[60:63], v[208:211], v[136:139]
	v_mfma_f32_16x16x32_bf16 v[128:131], v[72:75], v[208:211], v[128:131]
	v_mfma_f32_16x16x32_bf16 v[116:119], v[60:63], v[216:219], v[116:119]
	v_mfma_f32_16x16x32_bf16 v[112:115], v[72:75], v[216:219], v[112:115]
	v_mfma_f32_16x16x32_bf16 v[92:95], v[68:71], v[184:187], v[92:95]
	v_mfma_f32_16x16x32_bf16 v[88:91], v[76:79], v[184:187], v[88:91]
	v_mfma_f32_16x16x32_bf16 v[152:155], v[68:71], v[204:207], v[152:155]
	v_mfma_f32_16x16x32_bf16 v[144:147], v[76:79], v[204:207], v[144:147]
	v_mfma_f32_16x16x32_bf16 v[136:139], v[68:71], v[212:215], v[136:139]
	v_mfma_f32_16x16x32_bf16 v[128:131], v[76:79], v[212:215], v[128:131]
	v_mfma_f32_16x16x32_bf16 v[116:119], v[68:71], v[220:223], v[116:119]
	s_setprio 3
	s_barrier
	v_mfma_f32_16x16x32_bf16 v[112:115], v[76:79], v[220:223], v[112:115]
	s_setprio 0
	s_add_i32 s95, s87, s74
	v_lshl_add_u64 v[228:229], s[68:69], 0, v[162:163]
	s_mov_b32 m0, s95
	ds_read_b128 v[180:183], v198 offset:16384
	ds_read_b128 v[184:187], v198 offset:17408
	ds_read_b128 v[200:203], v198 offset:18432
	ds_read_b128 v[204:207], v198 offset:19456
	ds_read_b128 v[208:211], v198 offset:20480
	ds_read_b128 v[212:215], v198 offset:21504
	ds_read_b128 v[216:219], v198 offset:22528
	ds_read_b128 v[220:223], v198 offset:23552
	global_load_lds_dwordx4 v[228:229], off
	s_add_i32 m0, s95, 0x2000
	s_add_u32 s96, s68, 0x100000
	v_lshl_add_u64 v[230:231], s[68:69], 0, v[166:167]
	s_addc_u32 s97, s69, 0
	s_add_i32 s95, s90, s74
	global_load_lds_dwordx4 v[230:231], off
	v_lshl_add_u64 v[224:225], s[96:97], 0, v[162:163]
	s_mov_b32 m0, s95
	v_lshl_add_u64 v[232:233], s[70:71], 0, v[160:161]
	global_load_lds_dwordx4 v[224:225], off
	v_lshl_add_u64 v[224:225], s[96:97], 0, v[166:167]
	s_add_i32 m0, s95, 0x2000
	v_lshl_add_u64 v[234:235], s[70:71], 0, v[164:165]
	global_load_lds_dwordx4 v[224:225], off
	s_mov_b32 m0, s75
	s_nop 0
	global_load_lds_dwordx4 v[232:233], off
	s_mov_b32 m0, s76
	s_nop 0
	global_load_lds_dwordx4 v[234:235], off
	s_waitcnt vmcnt(8)
	s_waitcnt lgkmcnt(0)
	s_barrier
; #define PG8_STAGE(bufoff, gbase, voff) do { _Pragma("unroll") for (int _i = 0; _i < 2; ++_i) \
;         __builtin_amdgcn_global_load_lds((const unsigned*)((const char*)(gbase) + (voff)[_i]), (PG8_LAS unsigned*)(lds + (bufoff) + ldsw + _i * 8192), 16, 0, 0); } while (0)
; #define PG8_LDA(dst, b, h) do { _Pragma("unroll") for (int m = 0; m < 4; ++m) _Pragma("unroll") for (int k = 0; k < 2; ++k) dst[m][k] = *(const PG8_LAS bf16x8*)(lds + PG8_SA(b, h) + aoff + m * 2048 + k * 1024); } while (0)
; #define PG8_LDB(dst, b, h) do { _Pragma("unroll") for (int n = 0; n < 2; ++n) _Pragma("unroll") for (int k = 0; k < 2; ++k) dst[n][k] = *(const PG8_LAS bf16x8*)(lds + PG8_SB(b, h) + boff + n * 2048 + k * 1024); } while (0)
; #define PG8_MMA(ai, bj, At, Bt) do { __builtin_amdgcn_s_setprio(1); _Pragma("unroll") for (int m = 0; m < 4; ++m) _Pragma("unroll") for (int n = 0; n < 2; ++n) _Pragma("unroll") for (int k = 0; k < 2; ++k) \
;         acc[ai][bj][m][n] = __builtin_amdgcn_mfma_f32_16x16x32_bf16(Bt[n][k], At[m][k], acc[ai][bj][m][n], 0, 0, 0); __builtin_amdgcn_s_setprio(0); } while (0)
; #define PG8_WAIT_V(n) asm volatile("s_waitcnt vmcnt(" #n ")" ::: "memory")
; #define PG8_WAIT_L(n) asm volatile("s_waitcnt lgkmcnt(" #n ")" ::: "memory")
; #define PG8_BAR __builtin_amdgcn_s_barrier()
; #define PG8_SCHED __builtin_amdgcn_sched_barrier(0)
; template <class Epi, class Sched, bool ALIGN_EPI = false, bool SP2 = false>
; __device__ __forceinline__ void gemm_phase(PG8_LAS unsigned char* lds, const Gemm g, const Sched& S, const Epi& E, const int wv  ) {
;     ...
;             PG8_LDA(At, 0, 1); PG8_STAGE(PG8_SB(0, 0), b2, voffB); PG8_STAGE(PG8_SB(0, 1), b2 + hstepB, voffB); PG8_STAGE(PG8_SA(0, 0), a2, voffA);
;             PG8_WAIT_V(8); PG8_WAIT_L(0); PG8_BAR; PG8_MMA(1, 0, At, B0); PG8_MMA(1, 1, At, B1); PG8_BAR; PG8_SCHED;
;             PG8_LDB(B0, 1, 0); PG8_LDB(B1, 1, 1); PG8_SCHED; PG8_LDA(At, 1, 0); PG8_STAGE(PG8_SA(0, 1), a2 + hstepA, voffA);
;             PG8_WAIT_V(8); PG8_WAIT_L(0); PG8_BAR; PG8_MMA(0, 0, At, B0); PG8_MMA(0, 1, At, B1); PG8_BAR; PG8_SCHED;
	s_setprio 3
	s_waitcnt lgkmcnt(0)
	v_mfma_f32_16x16x32_bf16 v[108:111], v[44:47], v[180:183], v[108:111]
	v_mfma_f32_16x16x32_bf16 v[96:99], v[52:55], v[180:183], v[96:99]
	v_mfma_f32_16x16x32_bf16 v[64:67], v[44:47], v[200:203], v[64:67]
	v_mfma_f32_16x16x32_bf16 v[36:39], v[52:55], v[200:203], v[36:39]
	v_mfma_f32_16x16x32_bf16 v[28:31], v[44:47], v[208:211], v[28:31]
	v_mfma_f32_16x16x32_bf16 v[20:23], v[52:55], v[208:211], v[20:23]
	v_mfma_f32_16x16x32_bf16 v[12:15], v[44:47], v[216:219], v[12:15]
	v_mfma_f32_16x16x32_bf16 v[4:7], v[52:55], v[216:219], v[4:7]
	v_mfma_f32_16x16x32_bf16 v[108:111], v[48:51], v[184:187], v[108:111]
	v_mfma_f32_16x16x32_bf16 v[96:99], v[56:59], v[184:187], v[96:99]
	v_mfma_f32_16x16x32_bf16 v[64:67], v[48:51], v[204:207], v[64:67]
	v_mfma_f32_16x16x32_bf16 v[36:39], v[56:59], v[204:207], v[36:39]
	v_mfma_f32_16x16x32_bf16 v[28:31], v[48:51], v[212:215], v[28:31]
	v_mfma_f32_16x16x32_bf16 v[20:23], v[56:59], v[212:215], v[20:23]
	v_mfma_f32_16x16x32_bf16 v[12:15], v[48:51], v[220:223], v[12:15]
	v_mfma_f32_16x16x32_bf16 v[4:7], v[56:59], v[220:223], v[4:7]
	s_setprio 0
	s_setprio 3
	v_mfma_f32_16x16x32_bf16 v[40:43], v[60:63], v[200:203], v[40:43]
	v_mfma_f32_16x16x32_bf16 v[32:35], v[72:75], v[200:203], v[32:35]
	v_mfma_f32_16x16x32_bf16 v[24:27], v[60:63], v[208:211], v[24:27]
	v_mfma_f32_16x16x32_bf16 v[16:19], v[72:75], v[208:211], v[16:19]
	v_mfma_f32_16x16x32_bf16 v[8:11], v[60:63], v[216:219], v[8:11]
	v_mfma_f32_16x16x32_bf16 v[0:3], v[72:75], v[216:219], v[0:3]
	v_mfma_f32_16x16x32_bf16 v[44:47], v[60:63], v[180:183], v[84:87]
	v_mfma_f32_16x16x32_bf16 v[48:51], v[72:75], v[180:183], v[80:83]
	v_mfma_f32_16x16x32_bf16 v[40:43], v[68:71], v[204:207], v[40:43]
	v_mfma_f32_16x16x32_bf16 v[32:35], v[76:79], v[204:207], v[32:35]
	v_mfma_f32_16x16x32_bf16 v[24:27], v[68:71], v[212:215], v[24:27]
	v_mfma_f32_16x16x32_bf16 v[16:19], v[76:79], v[212:215], v[16:19]
	v_mfma_f32_16x16x32_bf16 v[8:11], v[68:71], v[220:223], v[8:11]
	v_mfma_f32_16x16x32_bf16 v[0:3], v[76:79], v[220:223], v[0:3]
	v_mfma_f32_16x16x32_bf16 v[44:47], v[68:71], v[184:187], v[44:47]
	s_setprio 3
	s_barrier
	v_mfma_f32_16x16x32_bf16 v[48:51], v[76:79], v[184:187], v[48:51]
	s_setprio 0
	s_add_i32 s95, 0, 0x18000
	s_add_i32 s96, 0, 0x1c000
	v_add_u32_e32 v68, s95, v190
	v_add_u32_e32 v80, s96, v190
	ds_read_b128 v[52:55], v68
	ds_read_b128 v[56:59], v68 offset:1024
	ds_read_b128 v[60:63], v68 offset:2048
	ds_read_b128 v[68:71], v68 offset:3072
	ds_read_b128 v[72:75], v80
	ds_read_b128 v[76:79], v80 offset:1024
	ds_read_b128 v[180:183], v80 offset:2048
	ds_read_b128 v[184:187], v80 offset:3072
	s_add_u32 s70, s70, 0x100000
	s_addc_u32 s71, s71, 0
	s_mov_b32 m0, s77
	v_lshl_add_u64 v[224:225], s[70:71], 0, v[160:161]
	ds_read_b128 v[80:83], v198 offset:32768
	ds_read_b128 v[84:87], v198 offset:33792
	ds_read_b128 v[200:203], v198 offset:34816
	ds_read_b128 v[204:207], v198 offset:35840
	ds_read_b128 v[208:211], v198 offset:36864
	ds_read_b128 v[212:215], v198 offset:37888
	ds_read_b128 v[216:219], v198 offset:38912
	ds_read_b128 v[220:223], v198 offset:39936
	global_load_lds_dwordx4 v[224:225], off
	v_lshl_add_u64 v[224:225], s[70:71], 0, v[164:165]
	s_mov_b32 m0, s78
	s_nop 0
	global_load_lds_dwordx4 v[224:225], off
	s_waitcnt vmcnt(8)
	s_waitcnt lgkmcnt(0)
	s_barrier
	s_setprio 3
	s_waitcnt lgkmcnt(0)
	v_mfma_f32_16x16x32_bf16 v[104:107], v[52:55], v[80:83], v[104:107]
	v_mfma_f32_16x16x32_bf16 v[100:103], v[60:63], v[80:83], v[100:103]
	v_mfma_f32_16x16x32_bf16 v[156:159], v[52:55], v[200:203], v[156:159]
	v_mfma_f32_16x16x32_bf16 v[148:151], v[60:63], v[200:203], v[148:151]
	v_mfma_f32_16x16x32_bf16 v[140:143], v[52:55], v[208:211], v[140:143]
	v_mfma_f32_16x16x32_bf16 v[132:135], v[60:63], v[208:211], v[132:135]
	v_mfma_f32_16x16x32_bf16 v[124:127], v[52:55], v[216:219], v[124:127]
	v_mfma_f32_16x16x32_bf16 v[120:123], v[60:63], v[216:219], v[120:123]
	v_mfma_f32_16x16x32_bf16 v[104:107], v[56:59], v[84:87], v[104:107]
	v_mfma_f32_16x16x32_bf16 v[100:103], v[68:71], v[84:87], v[100:103]
	v_mfma_f32_16x16x32_bf16 v[156:159], v[56:59], v[204:207], v[156:159]
	v_mfma_f32_16x16x32_bf16 v[148:151], v[68:71], v[204:207], v[148:151]
	v_mfma_f32_16x16x32_bf16 v[140:143], v[56:59], v[212:215], v[140:143]
	v_mfma_f32_16x16x32_bf16 v[132:135], v[68:71], v[212:215], v[132:135]
	v_mfma_f32_16x16x32_bf16 v[124:127], v[56:59], v[220:223], v[124:127]
	v_mfma_f32_16x16x32_bf16 v[120:123], v[68:71], v[220:223], v[120:123]
	s_setprio 0
	s_setprio 3
	v_mfma_f32_16x16x32_bf16 v[92:95], v[72:75], v[80:83], v[92:95]
	v_mfma_f32_16x16x32_bf16 v[80:83], v[180:183], v[80:83], v[88:91]
	v_mfma_f32_16x16x32_bf16 v[88:91], v[184:187], v[84:87], v[80:83]
	v_mfma_f32_16x16x32_bf16 v[80:83], v[72:75], v[200:203], v[152:155]
	v_mfma_f32_16x16x32_bf16 v[152:155], v[76:79], v[204:207], v[80:83]
	v_mfma_f32_16x16x32_bf16 v[80:83], v[180:183], v[200:203], v[144:147]
	v_mfma_f32_16x16x32_bf16 v[144:147], v[184:187], v[204:207], v[80:83]
	v_mfma_f32_16x16x32_bf16 v[80:83], v[72:75], v[208:211], v[136:139]
	v_mfma_f32_16x16x32_bf16 v[136:139], v[76:79], v[212:215], v[80:83]
	v_mfma_f32_16x16x32_bf16 v[80:83], v[180:183], v[208:211], v[128:131]
	v_mfma_f32_16x16x32_bf16 v[128:131], v[184:187], v[212:215], v[80:83]
	v_mfma_f32_16x16x32_bf16 v[80:83], v[72:75], v[216:219], v[116:119]
	v_mfma_f32_16x16x32_bf16 v[116:119], v[76:79], v[220:223], v[80:83]
	v_mfma_f32_16x16x32_bf16 v[80:83], v[180:183], v[216:219], v[112:115]
	v_mfma_f32_16x16x32_bf16 v[92:95], v[76:79], v[84:87], v[92:95]
	s_setprio 3
	s_barrier
; #define PG8_STAGE(bufoff, gbase, voff) do { _Pragma("unroll") for (int _i = 0; _i < 2; ++_i) \
;         __builtin_amdgcn_global_load_lds((const unsigned*)((const char*)(gbase) + (voff)[_i]), (PG8_LAS unsigned*)(lds + (bufoff) + ldsw + _i * 8192), 16, 0, 0); } while (0)
; #define PG8_LDA(dst, b, h) do { _Pragma("unroll") for (int m = 0; m < 4; ++m) _Pragma("unroll") for (int k = 0; k < 2; ++k) dst[m][k] = *(const PG8_LAS bf16x8*)(lds + PG8_SA(b, h) + aoff + m * 2048 + k * 1024); } while (0)
; #define PG8_MMA(ai, bj, At, Bt) do { __builtin_amdgcn_s_setprio(1); _Pragma("unroll") for (int m = 0; m < 4; ++m) _Pragma("unroll") for (int n = 0; n < 2; ++n) _Pragma("unroll") for (int k = 0; k < 2; ++k) \
;         acc[ai][bj][m][n] = __builtin_amdgcn_mfma_f32_16x16x32_bf16(Bt[n][k], At[m][k], acc[ai][bj][m][n], 0, 0, 0); __builtin_amdgcn_s_setprio(0); } while (0)
; #define PG8_WAIT_V(n) asm volatile("s_waitcnt vmcnt(" #n ")" ::: "memory")
; #define PG8_WAIT_L(n) asm volatile("s_waitcnt lgkmcnt(" #n ")" ::: "memory")
; #define PG8_BAR __builtin_amdgcn_s_barrier()
; #define PG8_SCHED __builtin_amdgcn_sched_barrier(0)
; template <class Epi, class Sched, bool ALIGN_EPI = false, bool SP2 = false>
; __device__ __forceinline__ void gemm_phase(PG8_LAS unsigned char* lds, const Gemm g, const Sched& S, const Epi& E, const int wv  ) {
;     ...
;             PG8_LDA(At, 1, 1); PG8_STAGE(PG8_SB(1, 0), b3, voffB); PG8_STAGE(PG8_SB(1, 1), b3 + hstepB, voffB); PG8_STAGE(PG8_SA(1, 0), a3, voffA);
;             PG8_WAIT_V(8); PG8_WAIT_L(0); PG8_BAR; PG8_MMA(1, 0, At, B0); PG8_MMA(1, 1, At, B1); PG8_BAR; PG8_SCHED;
;     ...
;         if constexpr (ALIGN_EPI) { if (wr == 0) PG8_BAR; }
	v_mfma_f32_16x16x32_bf16 v[112:115], v[184:187], v[220:223], v[80:83]
	s_setprio 0
	s_add_i32 s70, s95, s74
	v_lshl_add_u64 v[84:85], v[228:229], 0, s[18:19]
	s_mov_b32 m0, s70
	s_nop 0
	ds_read_b128 v[80:83], v198 offset:49152
	ds_read_b128 v[200:203], v198 offset:50176
	ds_read_b128 v[204:207], v198 offset:51200
	ds_read_b128 v[208:211], v198 offset:52224
	ds_read_b128 v[212:215], v198 offset:53248
	ds_read_b128 v[216:219], v198 offset:54272
	ds_read_b128 v[220:223], v198 offset:55296
	ds_read_b128 v[224:227], v198 offset:56320
	global_load_lds_dwordx4 v[84:85], off
	s_add_i32 m0, s70, 0x2000
	s_add_u32 s68, s68, 0x100080
	v_lshl_add_u64 v[84:85], v[230:231], 0, s[18:19]
	s_addc_u32 s69, s69, 0
	s_add_i32 s70, s96, s74
	global_load_lds_dwordx4 v[84:85], off
	v_lshl_add_u64 v[84:85], s[68:69], 0, v[162:163]
	s_mov_b32 m0, s70
	s_nop 0
	global_load_lds_dwordx4 v[84:85], off
	v_lshl_add_u64 v[84:85], s[68:69], 0, v[166:167]
	s_add_i32 m0, s70, 0x2000
	s_nop 0
	global_load_lds_dwordx4 v[84:85], off
	v_lshl_add_u64 v[84:85], v[232:233], 0, s[18:19]
	s_mov_b32 m0, s82
	s_nop 0
	global_load_lds_dwordx4 v[84:85], off
	v_lshl_add_u64 v[84:85], v[234:235], 0, s[18:19]
	s_mov_b32 m0, s83
	s_nop 0
	global_load_lds_dwordx4 v[84:85], off
	s_waitcnt vmcnt(8)
	s_waitcnt lgkmcnt(0)
	s_barrier
	s_setprio 3
	s_waitcnt lgkmcnt(0)
	v_mfma_f32_16x16x32_bf16 v[84:87], v[52:55], v[80:83], v[108:111]
	v_mfma_f32_16x16x32_bf16 v[108:111], v[56:59], v[200:203], v[84:87]
	v_mfma_f32_16x16x32_bf16 v[84:87], v[60:63], v[80:83], v[96:99]
	v_mfma_f32_16x16x32_bf16 v[64:67], v[52:55], v[204:207], v[64:67]
	v_mfma_f32_16x16x32_bf16 v[36:39], v[60:63], v[204:207], v[36:39]
	v_mfma_f32_16x16x32_bf16 v[28:31], v[52:55], v[212:215], v[28:31]
	v_mfma_f32_16x16x32_bf16 v[20:23], v[60:63], v[212:215], v[20:23]
	v_mfma_f32_16x16x32_bf16 v[12:15], v[52:55], v[220:223], v[12:15]
	v_mfma_f32_16x16x32_bf16 v[4:7], v[60:63], v[220:223], v[4:7]
	v_mfma_f32_16x16x32_bf16 v[96:99], v[68:71], v[200:203], v[84:87]
	v_mfma_f32_16x16x32_bf16 v[64:67], v[56:59], v[208:211], v[64:67]
	v_mfma_f32_16x16x32_bf16 v[36:39], v[68:71], v[208:211], v[36:39]
	v_mfma_f32_16x16x32_bf16 v[28:31], v[56:59], v[216:219], v[28:31]
	v_mfma_f32_16x16x32_bf16 v[20:23], v[68:71], v[216:219], v[20:23]
	v_mfma_f32_16x16x32_bf16 v[12:15], v[56:59], v[224:227], v[12:15]
	v_mfma_f32_16x16x32_bf16 v[4:7], v[68:71], v[224:227], v[4:7]
	s_setprio 0
	s_setprio 3
	v_mfma_f32_16x16x32_bf16 v[44:47], v[72:75], v[80:83], v[44:47]
	v_mfma_f32_16x16x32_bf16 v[84:87], v[76:79], v[200:203], v[44:47]
	v_mfma_f32_16x16x32_bf16 v[44:47], v[180:183], v[80:83], v[48:51]
	v_mfma_f32_16x16x32_bf16 v[40:43], v[72:75], v[204:207], v[40:43]
	v_mfma_f32_16x16x32_bf16 v[32:35], v[180:183], v[204:207], v[32:35]
	v_mfma_f32_16x16x32_bf16 v[24:27], v[72:75], v[212:215], v[24:27]
	v_mfma_f32_16x16x32_bf16 v[16:19], v[180:183], v[212:215], v[16:19]
	v_mfma_f32_16x16x32_bf16 v[8:11], v[72:75], v[220:223], v[8:11]
	v_mfma_f32_16x16x32_bf16 v[0:3], v[180:183], v[220:223], v[0:3]
	v_mfma_f32_16x16x32_bf16 v[80:83], v[184:187], v[200:203], v[44:47]
	v_mfma_f32_16x16x32_bf16 v[40:43], v[76:79], v[208:211], v[40:43]
	v_mfma_f32_16x16x32_bf16 v[32:35], v[184:187], v[208:211], v[32:35]
	v_mfma_f32_16x16x32_bf16 v[24:27], v[76:79], v[216:219], v[24:27]
	v_mfma_f32_16x16x32_bf16 v[16:19], v[184:187], v[216:219], v[16:19]
	v_mfma_f32_16x16x32_bf16 v[8:11], v[76:79], v[224:227], v[8:11]
	s_setprio 3
	s_barrier
	v_mfma_f32_16x16x32_bf16 v[0:3], v[184:187], v[224:227], v[0:3]
	s_setprio 0
	s_add_i32 s94, s94, 2
	s_add_u32 s66, s66, 0x100
	s_addc_u32 s67, s67, 0
	s_add_u32 s92, s92, 0x100
	s_addc_u32 s93, s93, 0
	s_cmp_gt_u32 s94, 61
	s_cbranch_scc0 .LBB0_1187
	s_and_b64 vcc, exec, s[20:21]
	s_cbranch_vccz .LBB0_1190
	s_barrier

; #define PG8_STAGE(bufoff, gbase, voff) do { _Pragma("unroll") for (int _i = 0; _i < 2; ++_i) \
;         __builtin_amdgcn_global_load_lds((const unsigned*)((const char*)(gbase) + (voff)[_i]), (PG8_LAS unsigned*)(lds + (bufoff) + ldsw + _i * 8192), 16, 0, 0); } while (0)
; #define PG8_LDA(dst, b, h) do { _Pragma("unroll") for (int m = 0; m < 4; ++m) _Pragma("unroll") for (int k = 0; k < 2; ++k) dst[m][k] = *(const PG8_LAS bf16x8*)(lds + PG8_SA(b, h) + aoff + m * 2048 + k * 1024); } while (0)
; #define PG8_LDB(dst, b, h) do { _Pragma("unroll") for (int n = 0; n < 2; ++n) _Pragma("unroll") for (int k = 0; k < 2; ++k) dst[n][k] = *(const PG8_LAS bf16x8*)(lds + PG8_SB(b, h) + boff + n * 2048 + k * 1024); } while (0)
; #define PG8_MMA(ai, bj, At, Bt) do { __builtin_amdgcn_s_setprio(1); _Pragma("unroll") for (int m = 0; m < 4; ++m) _Pragma("unroll") for (int n = 0; n < 2; ++n) _Pragma("unroll") for (int k = 0; k < 2; ++k) \
;         acc[ai][bj][m][n] = __builtin_amdgcn_mfma_f32_16x16x32_bf16(Bt[n][k], At[m][k], acc[ai][bj][m][n], 0, 0, 0); __builtin_amdgcn_s_setprio(0); } while (0)
; #define PG8_WAIT_V(n) asm volatile("s_waitcnt vmcnt(" #n ")" ::: "memory")
; #define PG8_WAIT_L(n) asm volatile("s_waitcnt lgkmcnt(" #n ")" ::: "memory")
; #define PG8_BAR __builtin_amdgcn_s_barrier()
; template <class Epi, class Sched, bool ALIGN_EPI = false, bool SP2 = false>
; __device__ __forceinline__ void gemm_phase(PG8_LAS unsigned char* lds, const Gemm g, const Sched& S, const Epi& E, const int wv  ) {
;     ...
;             const char* a1 = cA + (size_t)(t + 1) * kstep;
;             const char* a2 = last ? nA : cA + (size_t)(t + 2) * kstep; const char* b2 = last ? nB : cB + (size_t)(t + 2) * kstep;
;             const char* a3 = a2 + kstep; const char* b3 = b2 + kstep;
;             if (last && has_next) S.a_ready(nxt);
;             if constexpr (SP2) {
;             PG8_LDB(B0, 0, 0); PG8_LDB(B1, 0, 1); PG8_SCHED; PG8_LDA(At, 0, 0); PG8_STAGE(PG8_SA(1, 1), a1 + hstepA, voffA);
;             PG8_WAIT_V(8); PG8_WAIT_L(0); PG8_BAR; PG8_MMA(0, 0, At, B0); PG8_MMA(0, 1, At, B1); PG8_BAR; PG8_SCHED;
;             PG8_LDA(At, 0, 1); PG8_STAGE(PG8_SB(0, 0), b2, voffB); PG8_STAGE(PG8_SB(0, 1), b2 + hstepB, voffB); PG8_STAGE(PG8_SA(0, 0), a2, voffA);
;             PG8_WAIT_V(8); PG8_WAIT_L(0); PG8_BAR; PG8_MMA(1, 0, At, B0); PG8_MMA(1, 1, At, B1); PG8_BAR; PG8_SCHED;
.LBB0_1544:
	ds_read_b128 v[146:149], v152
	ds_read_b128 v[156:159], v152 offset:1024
	ds_read_b128 v[160:163], v152 offset:2048
	ds_read_b128 v[164:167], v152 offset:3072
	ds_read_b128 v[168:171], v153
	ds_read_b128 v[172:175], v153 offset:1024
	ds_read_b128 v[176:179], v153 offset:2048
	ds_read_b128 v[180:183], v153 offset:3072
	s_add_u32 s54, s52, 0x100
	s_addc_u32 s55, s53, 0
	s_cmpk_eq_i32 s85, 0xa8
	s_cselect_b32 s59, s7, s55
	s_cselect_b32 s58, s6, s54
	s_cselect_b32 s57, s51, s84
	s_cselect_b32 s56, s50, s83
	v_lshl_add_u64 v[216:217], s[52:53], 0, v[138:139]
	s_add_i32 m0, s64, 0xc000
	ds_read_b128 v[184:187], v154
	ds_read_b128 v[188:191], v154 offset:1024
	ds_read_b128 v[192:195], v154 offset:2048
	ds_read_b128 v[196:199], v154 offset:3072
	ds_read_b128 v[200:203], v154 offset:4096
	ds_read_b128 v[204:207], v154 offset:5120
	ds_read_b128 v[208:211], v154 offset:6144
	ds_read_b128 v[212:215], v154 offset:7168
	global_load_lds_dwordx4 v[216:217], off
	v_lshl_add_u64 v[216:217], s[52:53], 0, v[140:141]
	s_add_i32 m0, s64, 0xe000
	s_nop 0
	global_load_lds_dwordx4 v[216:217], off
	s_waitcnt vmcnt(8)
	s_waitcnt lgkmcnt(0)
	s_barrier
	s_setprio 3
	s_waitcnt lgkmcnt(0)
	v_mfma_f32_16x16x32_bf16 v[76:79], v[146:149], v[184:187], v[76:79]
	v_mfma_f32_16x16x32_bf16 v[72:75], v[160:163], v[184:187], v[72:75]
	v_mfma_f32_16x16x32_bf16 v[68:71], v[146:149], v[192:195], v[68:71]
	v_mfma_f32_16x16x32_bf16 v[64:67], v[160:163], v[192:195], v[64:67]
	v_mfma_f32_16x16x32_bf16 v[56:59], v[146:149], v[200:203], v[56:59]
	v_mfma_f32_16x16x32_bf16 v[52:55], v[160:163], v[200:203], v[52:55]
	v_mfma_f32_16x16x32_bf16 v[44:47], v[146:149], v[208:211], v[44:47]
	v_mfma_f32_16x16x32_bf16 v[40:43], v[160:163], v[208:211], v[40:43]
	v_mfma_f32_16x16x32_bf16 v[76:79], v[156:159], v[188:191], v[76:79]
	v_mfma_f32_16x16x32_bf16 v[72:75], v[164:167], v[188:191], v[72:75]
	v_mfma_f32_16x16x32_bf16 v[68:71], v[156:159], v[196:199], v[68:71]
	v_mfma_f32_16x16x32_bf16 v[64:67], v[164:167], v[196:199], v[64:67]
	v_mfma_f32_16x16x32_bf16 v[56:59], v[156:159], v[204:207], v[56:59]
	v_mfma_f32_16x16x32_bf16 v[52:55], v[164:167], v[204:207], v[52:55]
	v_mfma_f32_16x16x32_bf16 v[44:47], v[156:159], v[212:215], v[44:47]
	v_mfma_f32_16x16x32_bf16 v[40:43], v[164:167], v[212:215], v[40:43]
	s_setprio 0
	s_setprio 3
	v_mfma_f32_16x16x32_bf16 v[124:127], v[168:171], v[184:187], v[124:127]
	v_mfma_f32_16x16x32_bf16 v[120:123], v[176:179], v[184:187], v[120:123]
	v_mfma_f32_16x16x32_bf16 v[116:119], v[168:171], v[192:195], v[116:119]
	v_mfma_f32_16x16x32_bf16 v[112:115], v[176:179], v[192:195], v[112:115]
	v_mfma_f32_16x16x32_bf16 v[108:111], v[168:171], v[200:203], v[108:111]
	v_mfma_f32_16x16x32_bf16 v[104:107], v[176:179], v[200:203], v[104:107]
	v_mfma_f32_16x16x32_bf16 v[100:103], v[168:171], v[208:211], v[100:103]
	v_mfma_f32_16x16x32_bf16 v[96:99], v[176:179], v[208:211], v[96:99]
	v_mfma_f32_16x16x32_bf16 v[124:127], v[172:175], v[188:191], v[124:127]
	v_mfma_f32_16x16x32_bf16 v[120:123], v[180:183], v[188:191], v[120:123]
	v_mfma_f32_16x16x32_bf16 v[116:119], v[172:175], v[196:199], v[116:119]
	v_mfma_f32_16x16x32_bf16 v[112:115], v[180:183], v[196:199], v[112:115]
	v_mfma_f32_16x16x32_bf16 v[108:111], v[172:175], v[204:207], v[108:111]
	v_mfma_f32_16x16x32_bf16 v[104:107], v[180:183], v[204:207], v[104:107]
	v_mfma_f32_16x16x32_bf16 v[100:103], v[172:175], v[212:215], v[100:103]
	s_setprio 3
	s_barrier
	v_mfma_f32_16x16x32_bf16 v[96:99], v[180:183], v[212:215], v[96:99]
	s_setprio 0
	s_add_i32 s52, s73, s63
	v_lshl_add_u64 v[216:217], s[56:57], 0, v[130:131]
	s_mov_b32 m0, s52
	ds_read_b128 v[184:187], v154 offset:16384
	ds_read_b128 v[188:191], v154 offset:17408
	ds_read_b128 v[192:195], v154 offset:18432
	ds_read_b128 v[196:199], v154 offset:19456
	ds_read_b128 v[200:203], v154 offset:20480
	ds_read_b128 v[204:207], v154 offset:21504
	ds_read_b128 v[208:211], v154 offset:22528
	ds_read_b128 v[212:215], v154 offset:23552
	global_load_lds_dwordx4 v[216:217], off
	s_add_i32 m0, s52, 0x2000
	s_add_u32 s52, s56, 0x2b0000
	v_lshl_add_u64 v[218:219], s[56:57], 0, v[134:135]
	s_addc_u32 s53, s57, 0
	s_add_i32 s86, s74, s63
	global_load_lds_dwordx4 v[218:219], off
	v_lshl_add_u64 v[220:221], s[52:53], 0, v[130:131]
	s_mov_b32 m0, s86
	v_lshl_add_u64 v[222:223], s[58:59], 0, v[132:133]
	global_load_lds_dwordx4 v[220:221], off
	v_lshl_add_u64 v[220:221], s[52:53], 0, v[134:135]
	s_add_i32 m0, s86, 0x2000
	s_nop 0
	global_load_lds_dwordx4 v[220:221], off
	v_lshl_add_u64 v[220:221], s[58:59], 0, v[128:129]
	s_mov_b32 m0, s64
	s_nop 0
	global_load_lds_dwordx4 v[220:221], off
	s_mov_b32 m0, s65
	s_nop 0
	global_load_lds_dwordx4 v[222:223], off
	s_waitcnt vmcnt(8)
	s_waitcnt lgkmcnt(0)
	s_barrier
; #define PG8_STAGE(bufoff, gbase, voff) do { _Pragma("unroll") for (int _i = 0; _i < 2; ++_i) \
;         __builtin_amdgcn_global_load_lds((const unsigned*)((const char*)(gbase) + (voff)[_i]), (PG8_LAS unsigned*)(lds + (bufoff) + ldsw + _i * 8192), 16, 0, 0); } while (0)
; #define PG8_LDA(dst, b, h) do { _Pragma("unroll") for (int m = 0; m < 4; ++m) _Pragma("unroll") for (int k = 0; k < 2; ++k) dst[m][k] = *(const PG8_LAS bf16x8*)(lds + PG8_SA(b, h) + aoff + m * 2048 + k * 1024); } while (0)
; #define PG8_LDB(dst, b, h) do { _Pragma("unroll") for (int n = 0; n < 2; ++n) _Pragma("unroll") for (int k = 0; k < 2; ++k) dst[n][k] = *(const PG8_LAS bf16x8*)(lds + PG8_SB(b, h) + boff + n * 2048 + k * 1024); } while (0)
; #define PG8_MMA(ai, bj, At, Bt) do { __builtin_amdgcn_s_setprio(1); _Pragma("unroll") for (int m = 0; m < 4; ++m) _Pragma("unroll") for (int n = 0; n < 2; ++n) _Pragma("unroll") for (int k = 0; k < 2; ++k) \
;         acc[ai][bj][m][n] = __builtin_amdgcn_mfma_f32_16x16x32_bf16(Bt[n][k], At[m][k], acc[ai][bj][m][n], 0, 0, 0); __builtin_amdgcn_s_setprio(0); } while (0)
; #define PG8_WAIT_V(n) asm volatile("s_waitcnt vmcnt(" #n ")" ::: "memory")
; #define PG8_WAIT_L(n) asm volatile("s_waitcnt lgkmcnt(" #n ")" ::: "memory")
; #define PG8_BAR __builtin_amdgcn_s_barrier()
; #define PG8_SCHED __builtin_amdgcn_sched_barrier(0)
; template <class Epi, class Sched, bool ALIGN_EPI = false, bool SP2 = false>
; __device__ __forceinline__ void gemm_phase(PG8_LAS unsigned char* lds, const Gemm g, const Sched& S, const Epi& E, const int wv  ) {
;     ...
;             PG8_LDA(At, 0, 1); PG8_STAGE(PG8_SB(0, 0), b2, voffB); PG8_STAGE(PG8_SB(0, 1), b2 + hstepB, voffB); PG8_STAGE(PG8_SA(0, 0), a2, voffA);
;             PG8_WAIT_V(8); PG8_WAIT_L(0); PG8_BAR; PG8_MMA(1, 0, At, B0); PG8_MMA(1, 1, At, B1); PG8_BAR; PG8_SCHED;
;             PG8_LDB(B0, 1, 0); PG8_LDB(B1, 1, 1); PG8_SCHED; PG8_LDA(At, 1, 0); PG8_STAGE(PG8_SA(0, 1), a2 + hstepA, voffA);
;             PG8_WAIT_V(8); PG8_WAIT_L(0); PG8_BAR; PG8_MMA(0, 0, At, B0); PG8_MMA(0, 1, At, B1); PG8_BAR; PG8_SCHED;
	s_setprio 3
	s_waitcnt lgkmcnt(0)
	v_mfma_f32_16x16x32_bf16 v[28:31], v[146:149], v[184:187], v[28:31]
	v_mfma_f32_16x16x32_bf16 v[24:27], v[160:163], v[184:187], v[24:27]
	v_mfma_f32_16x16x32_bf16 v[20:23], v[146:149], v[192:195], v[20:23]
	v_mfma_f32_16x16x32_bf16 v[16:19], v[160:163], v[192:195], v[16:19]
	v_mfma_f32_16x16x32_bf16 v[12:15], v[146:149], v[200:203], v[12:15]
	v_mfma_f32_16x16x32_bf16 v[8:11], v[160:163], v[200:203], v[8:11]
	v_mfma_f32_16x16x32_bf16 v[4:7], v[146:149], v[208:211], v[4:7]
	v_mfma_f32_16x16x32_bf16 v[0:3], v[160:163], v[208:211], v[0:3]
	v_mfma_f32_16x16x32_bf16 v[28:31], v[156:159], v[188:191], v[28:31]
	v_mfma_f32_16x16x32_bf16 v[24:27], v[164:167], v[188:191], v[24:27]
	v_mfma_f32_16x16x32_bf16 v[20:23], v[156:159], v[196:199], v[20:23]
	v_mfma_f32_16x16x32_bf16 v[16:19], v[164:167], v[196:199], v[16:19]
	v_mfma_f32_16x16x32_bf16 v[12:15], v[156:159], v[204:207], v[12:15]
	v_mfma_f32_16x16x32_bf16 v[8:11], v[164:167], v[204:207], v[8:11]
	v_mfma_f32_16x16x32_bf16 v[4:7], v[156:159], v[212:215], v[4:7]
	v_mfma_f32_16x16x32_bf16 v[0:3], v[164:167], v[212:215], v[0:3]
	s_setprio 0
	s_setprio 3
	v_mfma_f32_16x16x32_bf16 v[92:95], v[168:171], v[184:187], v[92:95]
	v_mfma_f32_16x16x32_bf16 v[88:91], v[176:179], v[184:187], v[88:91]
	v_mfma_f32_16x16x32_bf16 v[84:87], v[168:171], v[192:195], v[84:87]
	v_mfma_f32_16x16x32_bf16 v[80:83], v[176:179], v[192:195], v[80:83]
	v_mfma_f32_16x16x32_bf16 v[60:63], v[168:171], v[200:203], v[60:63]
	v_mfma_f32_16x16x32_bf16 v[48:51], v[176:179], v[200:203], v[48:51]
	v_mfma_f32_16x16x32_bf16 v[36:39], v[168:171], v[208:211], v[36:39]
	v_mfma_f32_16x16x32_bf16 v[32:35], v[176:179], v[208:211], v[32:35]
	v_mfma_f32_16x16x32_bf16 v[92:95], v[172:175], v[188:191], v[92:95]
	v_mfma_f32_16x16x32_bf16 v[88:91], v[180:183], v[188:191], v[88:91]
	v_mfma_f32_16x16x32_bf16 v[84:87], v[172:175], v[196:199], v[84:87]
	v_mfma_f32_16x16x32_bf16 v[80:83], v[180:183], v[196:199], v[80:83]
	v_mfma_f32_16x16x32_bf16 v[60:63], v[172:175], v[204:207], v[60:63]
	v_mfma_f32_16x16x32_bf16 v[48:51], v[180:183], v[204:207], v[48:51]
	v_mfma_f32_16x16x32_bf16 v[36:39], v[172:175], v[212:215], v[36:39]
	s_setprio 3
	s_barrier
	v_mfma_f32_16x16x32_bf16 v[32:35], v[180:183], v[212:215], v[32:35]
	s_setprio 0
	s_add_i32 s86, 0, 0x18000
	v_add_u32_e32 v155, s86, v150
	s_add_i32 s87, 0, 0x1c000
	ds_read_b128 v[146:149], v155
	ds_read_b128 v[156:159], v155 offset:1024
	ds_read_b128 v[160:163], v155 offset:2048
	ds_read_b128 v[164:167], v155 offset:3072
	v_add_u32_e32 v155, s87, v150
	ds_read_b128 v[168:171], v155
	ds_read_b128 v[172:175], v155 offset:1024
	ds_read_b128 v[176:179], v155 offset:2048
	ds_read_b128 v[180:183], v155 offset:3072
	s_add_u32 s52, s58, 0x2b0000
	s_addc_u32 s53, s59, 0
	s_mov_b32 m0, s66
	v_lshl_add_u64 v[224:225], s[52:53], 0, v[128:129]
	ds_read_b128 v[184:187], v154 offset:32768
	ds_read_b128 v[188:191], v154 offset:33792
	ds_read_b128 v[192:195], v154 offset:34816
	ds_read_b128 v[196:199], v154 offset:35840
	ds_read_b128 v[200:203], v154 offset:36864
	ds_read_b128 v[204:207], v154 offset:37888
	ds_read_b128 v[208:211], v154 offset:38912
	ds_read_b128 v[212:215], v154 offset:39936
	global_load_lds_dwordx4 v[224:225], off
	v_lshl_add_u64 v[224:225], s[52:53], 0, v[132:133]
	s_mov_b32 m0, s67
	s_nop 0
	global_load_lds_dwordx4 v[224:225], off
	s_waitcnt vmcnt(8)
	s_waitcnt lgkmcnt(0)
	s_barrier
	s_setprio 3
	s_waitcnt lgkmcnt(0)
	v_mfma_f32_16x16x32_bf16 v[76:79], v[146:149], v[184:187], v[76:79]
	v_mfma_f32_16x16x32_bf16 v[72:75], v[160:163], v[184:187], v[72:75]
	v_mfma_f32_16x16x32_bf16 v[68:71], v[146:149], v[192:195], v[68:71]
	v_mfma_f32_16x16x32_bf16 v[64:67], v[160:163], v[192:195], v[64:67]
	v_mfma_f32_16x16x32_bf16 v[56:59], v[146:149], v[200:203], v[56:59]
	v_mfma_f32_16x16x32_bf16 v[52:55], v[160:163], v[200:203], v[52:55]
	v_mfma_f32_16x16x32_bf16 v[44:47], v[146:149], v[208:211], v[44:47]
	v_mfma_f32_16x16x32_bf16 v[40:43], v[160:163], v[208:211], v[40:43]
	v_mfma_f32_16x16x32_bf16 v[76:79], v[156:159], v[188:191], v[76:79]
	v_mfma_f32_16x16x32_bf16 v[72:75], v[164:167], v[188:191], v[72:75]
	v_mfma_f32_16x16x32_bf16 v[68:71], v[156:159], v[196:199], v[68:71]
	v_mfma_f32_16x16x32_bf16 v[64:67], v[164:167], v[196:199], v[64:67]
	v_mfma_f32_16x16x32_bf16 v[56:59], v[156:159], v[204:207], v[56:59]
	v_mfma_f32_16x16x32_bf16 v[52:55], v[164:167], v[204:207], v[52:55]
	v_mfma_f32_16x16x32_bf16 v[44:47], v[156:159], v[212:215], v[44:47]
	v_mfma_f32_16x16x32_bf16 v[40:43], v[164:167], v[212:215], v[40:43]
	s_setprio 0
	s_setprio 3
	v_mfma_f32_16x16x32_bf16 v[124:127], v[168:171], v[184:187], v[124:127]
	v_mfma_f32_16x16x32_bf16 v[120:123], v[176:179], v[184:187], v[120:123]
	v_mfma_f32_16x16x32_bf16 v[116:119], v[168:171], v[192:195], v[116:119]
	v_mfma_f32_16x16x32_bf16 v[112:115], v[176:179], v[192:195], v[112:115]
	v_mfma_f32_16x16x32_bf16 v[108:111], v[168:171], v[200:203], v[108:111]
	v_mfma_f32_16x16x32_bf16 v[104:107], v[176:179], v[200:203], v[104:107]
	v_mfma_f32_16x16x32_bf16 v[100:103], v[168:171], v[208:211], v[100:103]
	v_mfma_f32_16x16x32_bf16 v[96:99], v[176:179], v[208:211], v[96:99]
	v_mfma_f32_16x16x32_bf16 v[124:127], v[172:175], v[188:191], v[124:127]
	v_mfma_f32_16x16x32_bf16 v[120:123], v[180:183], v[188:191], v[120:123]
	v_mfma_f32_16x16x32_bf16 v[116:119], v[172:175], v[196:199], v[116:119]
	v_mfma_f32_16x16x32_bf16 v[112:115], v[180:183], v[196:199], v[112:115]
	v_mfma_f32_16x16x32_bf16 v[108:111], v[172:175], v[204:207], v[108:111]
	v_mfma_f32_16x16x32_bf16 v[104:107], v[180:183], v[204:207], v[104:107]
	v_mfma_f32_16x16x32_bf16 v[100:103], v[172:175], v[212:215], v[100:103]
	s_setprio 3
	s_barrier
; #define PG8_STAGE(bufoff, gbase, voff) do { _Pragma("unroll") for (int _i = 0; _i < 2; ++_i) \
;         __builtin_amdgcn_global_load_lds((const unsigned*)((const char*)(gbase) + (voff)[_i]), (PG8_LAS unsigned*)(lds + (bufoff) + ldsw + _i * 8192), 16, 0, 0); } while (0)
; #define PG8_LDA(dst, b, h) do { _Pragma("unroll") for (int m = 0; m < 4; ++m) _Pragma("unroll") for (int k = 0; k < 2; ++k) dst[m][k] = *(const PG8_LAS bf16x8*)(lds + PG8_SA(b, h) + aoff + m * 2048 + k * 1024); } while (0)
; #define PG8_MMA(ai, bj, At, Bt) do { __builtin_amdgcn_s_setprio(1); _Pragma("unroll") for (int m = 0; m < 4; ++m) _Pragma("unroll") for (int n = 0; n < 2; ++n) _Pragma("unroll") for (int k = 0; k < 2; ++k) \
;         acc[ai][bj][m][n] = __builtin_amdgcn_mfma_f32_16x16x32_bf16(Bt[n][k], At[m][k], acc[ai][bj][m][n], 0, 0, 0); __builtin_amdgcn_s_setprio(0); } while (0)
; #define PG8_WAIT_V(n) asm volatile("s_waitcnt vmcnt(" #n ")" ::: "memory")
; #define PG8_WAIT_L(n) asm volatile("s_waitcnt lgkmcnt(" #n ")" ::: "memory")
; #define PG8_BAR __builtin_amdgcn_s_barrier()
; #define PG8_SCHED __builtin_amdgcn_sched_barrier(0)
; template <class Epi, class Sched, bool ALIGN_EPI = false, bool SP2 = false>
; __device__ __forceinline__ void gemm_phase(PG8_LAS unsigned char* lds, const Gemm g, const Sched& S, const Epi& E, const int wv  ) {
;     ...
;             PG8_LDA(At, 1, 1); PG8_STAGE(PG8_SB(1, 0), b3, voffB); PG8_STAGE(PG8_SB(1, 1), b3 + hstepB, voffB); PG8_STAGE(PG8_SA(1, 0), a3, voffA);
;             PG8_WAIT_V(8); PG8_WAIT_L(0); PG8_BAR; PG8_MMA(1, 0, At, B0); PG8_MMA(1, 1, At, B1); PG8_BAR; PG8_SCHED;
;     ...
;         if constexpr (ALIGN_EPI) { if (wr == 0) PG8_BAR; }
	v_mfma_f32_16x16x32_bf16 v[96:99], v[180:183], v[212:215], v[96:99]
	s_setprio 0
	s_add_i32 s52, s86, s63
	v_lshl_add_u64 v[216:217], v[216:217], 0, s[12:13]
	s_mov_b32 m0, s52
	ds_read_b128 v[184:187], v154 offset:49152
	ds_read_b128 v[188:191], v154 offset:50176
	ds_read_b128 v[192:195], v154 offset:51200
	ds_read_b128 v[196:199], v154 offset:52224
	ds_read_b128 v[200:203], v154 offset:53248
	ds_read_b128 v[204:207], v154 offset:54272
	ds_read_b128 v[208:211], v154 offset:55296
	ds_read_b128 v[212:215], v154 offset:56320
	global_load_lds_dwordx4 v[216:217], off
	s_add_i32 m0, s52, 0x2000
	s_add_u32 s52, s56, 0x2b0080
	v_lshl_add_u64 v[216:217], v[218:219], 0, s[12:13]
	s_addc_u32 s53, s57, 0
	s_add_i32 s56, s87, s63
	global_load_lds_dwordx4 v[216:217], off
	v_lshl_add_u64 v[216:217], s[52:53], 0, v[130:131]
	s_mov_b32 m0, s56
	s_nop 0
	global_load_lds_dwordx4 v[216:217], off
	v_lshl_add_u64 v[216:217], s[52:53], 0, v[134:135]
	s_add_i32 m0, s56, 0x2000
	s_nop 0
	global_load_lds_dwordx4 v[216:217], off
	v_lshl_add_u64 v[216:217], v[220:221], 0, s[12:13]
	s_mov_b32 m0, s70
	s_nop 0
	global_load_lds_dwordx4 v[216:217], off
	v_lshl_add_u64 v[216:217], v[222:223], 0, s[12:13]
	s_mov_b32 m0, s71
	s_nop 0
	global_load_lds_dwordx4 v[216:217], off
	s_waitcnt vmcnt(8)
	s_waitcnt lgkmcnt(0)
	s_barrier
	s_setprio 3
	s_waitcnt lgkmcnt(0)
	v_mfma_f32_16x16x32_bf16 v[28:31], v[146:149], v[184:187], v[28:31]
	v_mfma_f32_16x16x32_bf16 v[24:27], v[160:163], v[184:187], v[24:27]
	v_mfma_f32_16x16x32_bf16 v[20:23], v[146:149], v[192:195], v[20:23]
	v_mfma_f32_16x16x32_bf16 v[16:19], v[160:163], v[192:195], v[16:19]
	v_mfma_f32_16x16x32_bf16 v[12:15], v[146:149], v[200:203], v[12:15]
	v_mfma_f32_16x16x32_bf16 v[8:11], v[160:163], v[200:203], v[8:11]
	v_mfma_f32_16x16x32_bf16 v[4:7], v[146:149], v[208:211], v[4:7]
	v_mfma_f32_16x16x32_bf16 v[0:3], v[160:163], v[208:211], v[0:3]
	v_mfma_f32_16x16x32_bf16 v[28:31], v[156:159], v[188:191], v[28:31]
	v_mfma_f32_16x16x32_bf16 v[24:27], v[164:167], v[188:191], v[24:27]
	v_mfma_f32_16x16x32_bf16 v[20:23], v[156:159], v[196:199], v[20:23]
	v_mfma_f32_16x16x32_bf16 v[16:19], v[164:167], v[196:199], v[16:19]
	v_mfma_f32_16x16x32_bf16 v[12:15], v[156:159], v[204:207], v[12:15]
	v_mfma_f32_16x16x32_bf16 v[8:11], v[164:167], v[204:207], v[8:11]
	v_mfma_f32_16x16x32_bf16 v[4:7], v[156:159], v[212:215], v[4:7]
	v_mfma_f32_16x16x32_bf16 v[0:3], v[164:167], v[212:215], v[0:3]
	s_setprio 0
	s_setprio 3
	v_mfma_f32_16x16x32_bf16 v[92:95], v[168:171], v[184:187], v[92:95]
	v_mfma_f32_16x16x32_bf16 v[88:91], v[176:179], v[184:187], v[88:91]
	v_mfma_f32_16x16x32_bf16 v[84:87], v[168:171], v[192:195], v[84:87]
	v_mfma_f32_16x16x32_bf16 v[80:83], v[176:179], v[192:195], v[80:83]
	v_mfma_f32_16x16x32_bf16 v[60:63], v[168:171], v[200:203], v[60:63]
	v_mfma_f32_16x16x32_bf16 v[48:51], v[176:179], v[200:203], v[48:51]
	v_mfma_f32_16x16x32_bf16 v[36:39], v[168:171], v[208:211], v[36:39]
	v_mfma_f32_16x16x32_bf16 v[32:35], v[176:179], v[208:211], v[32:35]
	v_mfma_f32_16x16x32_bf16 v[92:95], v[172:175], v[188:191], v[92:95]
	v_mfma_f32_16x16x32_bf16 v[88:91], v[180:183], v[188:191], v[88:91]
	v_mfma_f32_16x16x32_bf16 v[84:87], v[172:175], v[196:199], v[84:87]
	v_mfma_f32_16x16x32_bf16 v[80:83], v[180:183], v[196:199], v[80:83]
	v_mfma_f32_16x16x32_bf16 v[60:63], v[172:175], v[204:207], v[60:63]
	v_mfma_f32_16x16x32_bf16 v[48:51], v[180:183], v[204:207], v[48:51]
	v_mfma_f32_16x16x32_bf16 v[36:39], v[172:175], v[212:215], v[36:39]
	s_setprio 3
	s_barrier
	v_mfma_f32_16x16x32_bf16 v[32:35], v[180:183], v[212:215], v[32:35]
	s_setprio 0
	s_add_i32 s85, s85, 2
	s_add_u32 s83, s83, 0x100
	s_addc_u32 s84, s84, 0
	s_cmpk_gt_u32 s85, 0xa9
	s_mov_b64 s[52:53], s[54:55]
	s_cbranch_scc0 .LBB0_1544
	s_and_b64 vcc, exec, s[14:15]
	s_cbranch_vccz .LBB0_1547
	s_barrier

; #define PG8_STAGE(bufoff, gbase, voff) do { _Pragma("unroll") for (int _i = 0; _i < 2; ++_i) \
;         __builtin_amdgcn_global_load_lds((const unsigned*)((const char*)(gbase) + (voff)[_i]), (PG8_LAS unsigned*)(lds + (bufoff) + ldsw + _i * 8192), 16, 0, 0); } while (0)
; #define PG8_LDA(dst, b, h) do { _Pragma("unroll") for (int m = 0; m < 4; ++m) _Pragma("unroll") for (int k = 0; k < 2; ++k) dst[m][k] = *(const PG8_LAS bf16x8*)(lds + PG8_SA(b, h) + aoff + m * 2048 + k * 1024); } while (0)
; #define PG8_LDB(dst, b, h) do { _Pragma("unroll") for (int n = 0; n < 2; ++n) _Pragma("unroll") for (int k = 0; k < 2; ++k) dst[n][k] = *(const PG8_LAS bf16x8*)(lds + PG8_SB(b, h) + boff + n * 2048 + k * 1024); } while (0)
; #define PG8_MMA(ai, bj, At, Bt) do { __builtin_amdgcn_s_setprio(1); _Pragma("unroll") for (int m = 0; m < 4; ++m) _Pragma("unroll") for (int n = 0; n < 2; ++n) _Pragma("unroll") for (int k = 0; k < 2; ++k) \
;         acc[ai][bj][m][n] = __builtin_amdgcn_mfma_f32_16x16x32_bf16(Bt[n][k], At[m][k], acc[ai][bj][m][n], 0, 0, 0); __builtin_amdgcn_s_setprio(0); } while (0)
; #define PG8_WAIT_V(n) asm volatile("s_waitcnt vmcnt(" #n ")" ::: "memory")
; #define PG8_WAIT_L(n) asm volatile("s_waitcnt lgkmcnt(" #n ")" ::: "memory")
; #define PG8_BAR __builtin_amdgcn_s_barrier()
; template <class Epi, class Sched, bool ALIGN_EPI = false, bool SP2 = false>
; __device__ __forceinline__ void gemm_phase(PG8_LAS unsigned char* lds, const Gemm g, const Sched& S, const Epi& E, const int wv  ) {
;     ...
;             const char* a1 = cA + (size_t)(t + 1) * kstep;
;             const char* a2 = last ? nA : cA + (size_t)(t + 2) * kstep; const char* b2 = last ? nB : cB + (size_t)(t + 2) * kstep;
;             const char* a3 = a2 + kstep; const char* b3 = b2 + kstep;
;             if (last && has_next) S.a_ready(nxt);
;             if constexpr (SP2) {
;             PG8_LDB(B0, 0, 0); PG8_LDB(B1, 0, 1); PG8_SCHED; PG8_LDA(At, 0, 0); PG8_STAGE(PG8_SA(1, 1), a1 + hstepA, voffA);
;             PG8_WAIT_V(8); PG8_WAIT_L(0); PG8_BAR; PG8_MMA(0, 0, At, B0); PG8_MMA(0, 1, At, B1); PG8_BAR; PG8_SCHED;
;             PG8_LDA(At, 0, 1); PG8_STAGE(PG8_SB(0, 0), b2, voffB); PG8_STAGE(PG8_SB(0, 1), b2 + hstepB, voffB); PG8_STAGE(PG8_SA(0, 0), a2, voffA);
;             PG8_WAIT_V(8); PG8_WAIT_L(0); PG8_BAR; PG8_MMA(1, 0, At, B0); PG8_MMA(1, 1, At, B1); PG8_BAR; PG8_SCHED;
.LBB0_1717:
	ds_read_b128 v[146:149], v152
	ds_read_b128 v[156:159], v152 offset:1024
	ds_read_b128 v[160:163], v152 offset:2048
	ds_read_b128 v[164:167], v152 offset:3072
	ds_read_b128 v[168:171], v153
	ds_read_b128 v[172:175], v153 offset:1024
	ds_read_b128 v[176:179], v153 offset:2048
	ds_read_b128 v[180:183], v153 offset:3072
	s_add_u32 s60, s58, 0xfff00080
	s_addc_u32 s61, s59, -1
	s_cmp_eq_u32 s87, 60
	s_cselect_b32 s63, s51, s61
	s_cselect_b32 s62, s83, s60
	s_cselect_b32 s61, s49, s86
	s_cselect_b32 s60, s84, s85
	v_lshl_add_u64 v[216:217], s[58:59], 0, v[138:139]
	s_add_i32 m0, s70, 0xc000
	ds_read_b128 v[184:187], v154
	ds_read_b128 v[188:191], v154 offset:1024
	ds_read_b128 v[192:195], v154 offset:2048
	ds_read_b128 v[196:199], v154 offset:3072
	ds_read_b128 v[200:203], v154 offset:4096
	ds_read_b128 v[204:207], v154 offset:5120
	ds_read_b128 v[208:211], v154 offset:6144
	ds_read_b128 v[212:215], v154 offset:7168
	global_load_lds_dwordx4 v[216:217], off
	v_lshl_add_u64 v[216:217], s[58:59], 0, v[140:141]
	s_add_i32 m0, s70, 0xe000
	s_nop 0
	global_load_lds_dwordx4 v[216:217], off
	s_waitcnt vmcnt(8)
	s_waitcnt lgkmcnt(0)
	s_barrier
	s_setprio 3
	s_waitcnt lgkmcnt(0)
	v_mfma_f32_16x16x32_bf16 v[76:79], v[146:149], v[184:187], v[76:79]
	v_mfma_f32_16x16x32_bf16 v[72:75], v[160:163], v[184:187], v[72:75]
	v_mfma_f32_16x16x32_bf16 v[68:71], v[146:149], v[192:195], v[68:71]
	v_mfma_f32_16x16x32_bf16 v[64:67], v[160:163], v[192:195], v[64:67]
	v_mfma_f32_16x16x32_bf16 v[56:59], v[146:149], v[200:203], v[56:59]
	v_mfma_f32_16x16x32_bf16 v[52:55], v[160:163], v[200:203], v[52:55]
	v_mfma_f32_16x16x32_bf16 v[44:47], v[146:149], v[208:211], v[44:47]
	v_mfma_f32_16x16x32_bf16 v[40:43], v[160:163], v[208:211], v[40:43]
	v_mfma_f32_16x16x32_bf16 v[76:79], v[156:159], v[188:191], v[76:79]
	v_mfma_f32_16x16x32_bf16 v[72:75], v[164:167], v[188:191], v[72:75]
	v_mfma_f32_16x16x32_bf16 v[68:71], v[156:159], v[196:199], v[68:71]
	v_mfma_f32_16x16x32_bf16 v[64:67], v[164:167], v[196:199], v[64:67]
	v_mfma_f32_16x16x32_bf16 v[56:59], v[156:159], v[204:207], v[56:59]
	v_mfma_f32_16x16x32_bf16 v[52:55], v[164:167], v[204:207], v[52:55]
	v_mfma_f32_16x16x32_bf16 v[44:47], v[156:159], v[212:215], v[44:47]
	v_mfma_f32_16x16x32_bf16 v[40:43], v[164:167], v[212:215], v[40:43]
	s_setprio 0
	s_setprio 3
	v_mfma_f32_16x16x32_bf16 v[124:127], v[168:171], v[184:187], v[124:127]
	v_mfma_f32_16x16x32_bf16 v[120:123], v[176:179], v[184:187], v[120:123]
	v_mfma_f32_16x16x32_bf16 v[116:119], v[168:171], v[192:195], v[116:119]
	v_mfma_f32_16x16x32_bf16 v[112:115], v[176:179], v[192:195], v[112:115]
	v_mfma_f32_16x16x32_bf16 v[108:111], v[168:171], v[200:203], v[108:111]
	v_mfma_f32_16x16x32_bf16 v[104:107], v[176:179], v[200:203], v[104:107]
	v_mfma_f32_16x16x32_bf16 v[100:103], v[168:171], v[208:211], v[100:103]
	v_mfma_f32_16x16x32_bf16 v[96:99], v[176:179], v[208:211], v[96:99]
	v_mfma_f32_16x16x32_bf16 v[124:127], v[172:175], v[188:191], v[124:127]
	v_mfma_f32_16x16x32_bf16 v[120:123], v[180:183], v[188:191], v[120:123]
	v_mfma_f32_16x16x32_bf16 v[116:119], v[172:175], v[196:199], v[116:119]
	v_mfma_f32_16x16x32_bf16 v[112:115], v[180:183], v[196:199], v[112:115]
	v_mfma_f32_16x16x32_bf16 v[108:111], v[172:175], v[204:207], v[108:111]
	v_mfma_f32_16x16x32_bf16 v[104:107], v[180:183], v[204:207], v[104:107]
	v_mfma_f32_16x16x32_bf16 v[100:103], v[172:175], v[212:215], v[100:103]
	s_setprio 3
	s_barrier
	v_mfma_f32_16x16x32_bf16 v[96:99], v[180:183], v[212:215], v[96:99]
	s_setprio 0
	s_add_i32 s90, s77, s69
	v_lshl_add_u64 v[216:217], s[60:61], 0, v[130:131]
	s_mov_b32 m0, s90
	ds_read_b128 v[184:187], v154 offset:16384
	ds_read_b128 v[188:191], v154 offset:17408
	ds_read_b128 v[192:195], v154 offset:18432
	ds_read_b128 v[196:199], v154 offset:19456
	ds_read_b128 v[200:203], v154 offset:20480
	ds_read_b128 v[204:207], v154 offset:21504
	ds_read_b128 v[208:211], v154 offset:22528
	ds_read_b128 v[212:215], v154 offset:23552
	global_load_lds_dwordx4 v[216:217], off
	s_add_i32 m0, s90, 0x2000
	s_add_u32 s90, s60, 0x100000
	v_lshl_add_u64 v[218:219], s[60:61], 0, v[134:135]
	s_addc_u32 s91, s61, 0
	s_add_i32 s92, s78, s69
	global_load_lds_dwordx4 v[218:219], off
	v_lshl_add_u64 v[220:221], s[90:91], 0, v[130:131]
	s_mov_b32 m0, s92
	v_lshl_add_u64 v[222:223], s[62:63], 0, v[132:133]
	global_load_lds_dwordx4 v[220:221], off
	v_lshl_add_u64 v[220:221], s[90:91], 0, v[134:135]
	s_add_i32 m0, s92, 0x2000
	s_nop 0
	global_load_lds_dwordx4 v[220:221], off
	v_lshl_add_u64 v[220:221], s[62:63], 0, v[128:129]
	s_mov_b32 m0, s70
	s_nop 0
	global_load_lds_dwordx4 v[220:221], off
	s_mov_b32 m0, s71
	s_nop 0
	global_load_lds_dwordx4 v[222:223], off
	s_waitcnt vmcnt(8)
	s_waitcnt lgkmcnt(0)
	s_barrier
; #define PG8_STAGE(bufoff, gbase, voff) do { _Pragma("unroll") for (int _i = 0; _i < 2; ++_i) \
;         __builtin_amdgcn_global_load_lds((const unsigned*)((const char*)(gbase) + (voff)[_i]), (PG8_LAS unsigned*)(lds + (bufoff) + ldsw + _i * 8192), 16, 0, 0); } while (0)
; #define PG8_LDA(dst, b, h) do { _Pragma("unroll") for (int m = 0; m < 4; ++m) _Pragma("unroll") for (int k = 0; k < 2; ++k) dst[m][k] = *(const PG8_LAS bf16x8*)(lds + PG8_SA(b, h) + aoff + m * 2048 + k * 1024); } while (0)
; #define PG8_LDB(dst, b, h) do { _Pragma("unroll") for (int n = 0; n < 2; ++n) _Pragma("unroll") for (int k = 0; k < 2; ++k) dst[n][k] = *(const PG8_LAS bf16x8*)(lds + PG8_SB(b, h) + boff + n * 2048 + k * 1024); } while (0)
; #define PG8_MMA(ai, bj, At, Bt) do { __builtin_amdgcn_s_setprio(1); _Pragma("unroll") for (int m = 0; m < 4; ++m) _Pragma("unroll") for (int n = 0; n < 2; ++n) _Pragma("unroll") for (int k = 0; k < 2; ++k) \
;         acc[ai][bj][m][n] = __builtin_amdgcn_mfma_f32_16x16x32_bf16(Bt[n][k], At[m][k], acc[ai][bj][m][n], 0, 0, 0); __builtin_amdgcn_s_setprio(0); } while (0)
; #define PG8_WAIT_V(n) asm volatile("s_waitcnt vmcnt(" #n ")" ::: "memory")
; #define PG8_WAIT_L(n) asm volatile("s_waitcnt lgkmcnt(" #n ")" ::: "memory")
; #define PG8_BAR __builtin_amdgcn_s_barrier()
; #define PG8_SCHED __builtin_amdgcn_sched_barrier(0)
; template <class Epi, class Sched, bool ALIGN_EPI = false, bool SP2 = false>
; __device__ __forceinline__ void gemm_phase(PG8_LAS unsigned char* lds, const Gemm g, const Sched& S, const Epi& E, const int wv  ) {
;     ...
;             PG8_LDA(At, 0, 1); PG8_STAGE(PG8_SB(0, 0), b2, voffB); PG8_STAGE(PG8_SB(0, 1), b2 + hstepB, voffB); PG8_STAGE(PG8_SA(0, 0), a2, voffA);
;             PG8_WAIT_V(8); PG8_WAIT_L(0); PG8_BAR; PG8_MMA(1, 0, At, B0); PG8_MMA(1, 1, At, B1); PG8_BAR; PG8_SCHED;
;             PG8_LDB(B0, 1, 0); PG8_LDB(B1, 1, 1); PG8_SCHED; PG8_LDA(At, 1, 0); PG8_STAGE(PG8_SA(0, 1), a2 + hstepA, voffA);
;             PG8_WAIT_V(8); PG8_WAIT_L(0); PG8_BAR; PG8_MMA(0, 0, At, B0); PG8_MMA(0, 1, At, B1); PG8_BAR; PG8_SCHED;
	s_setprio 3
	s_waitcnt lgkmcnt(0)
	v_mfma_f32_16x16x32_bf16 v[28:31], v[146:149], v[184:187], v[28:31]
	v_mfma_f32_16x16x32_bf16 v[24:27], v[160:163], v[184:187], v[24:27]
	v_mfma_f32_16x16x32_bf16 v[20:23], v[146:149], v[192:195], v[20:23]
	v_mfma_f32_16x16x32_bf16 v[16:19], v[160:163], v[192:195], v[16:19]
	v_mfma_f32_16x16x32_bf16 v[12:15], v[146:149], v[200:203], v[12:15]
	v_mfma_f32_16x16x32_bf16 v[8:11], v[160:163], v[200:203], v[8:11]
	v_mfma_f32_16x16x32_bf16 v[4:7], v[146:149], v[208:211], v[4:7]
	v_mfma_f32_16x16x32_bf16 v[0:3], v[160:163], v[208:211], v[0:3]
	v_mfma_f32_16x16x32_bf16 v[28:31], v[156:159], v[188:191], v[28:31]
	v_mfma_f32_16x16x32_bf16 v[24:27], v[164:167], v[188:191], v[24:27]
	v_mfma_f32_16x16x32_bf16 v[20:23], v[156:159], v[196:199], v[20:23]
	v_mfma_f32_16x16x32_bf16 v[16:19], v[164:167], v[196:199], v[16:19]
	v_mfma_f32_16x16x32_bf16 v[12:15], v[156:159], v[204:207], v[12:15]
	v_mfma_f32_16x16x32_bf16 v[8:11], v[164:167], v[204:207], v[8:11]
	v_mfma_f32_16x16x32_bf16 v[4:7], v[156:159], v[212:215], v[4:7]
	v_mfma_f32_16x16x32_bf16 v[0:3], v[164:167], v[212:215], v[0:3]
	s_setprio 0
	s_setprio 3
	v_mfma_f32_16x16x32_bf16 v[92:95], v[168:171], v[184:187], v[92:95]
	v_mfma_f32_16x16x32_bf16 v[88:91], v[176:179], v[184:187], v[88:91]
	v_mfma_f32_16x16x32_bf16 v[84:87], v[168:171], v[192:195], v[84:87]
	v_mfma_f32_16x16x32_bf16 v[80:83], v[176:179], v[192:195], v[80:83]
	v_mfma_f32_16x16x32_bf16 v[60:63], v[168:171], v[200:203], v[60:63]
	v_mfma_f32_16x16x32_bf16 v[48:51], v[176:179], v[200:203], v[48:51]
	v_mfma_f32_16x16x32_bf16 v[36:39], v[168:171], v[208:211], v[36:39]
	v_mfma_f32_16x16x32_bf16 v[32:35], v[176:179], v[208:211], v[32:35]
	v_mfma_f32_16x16x32_bf16 v[92:95], v[172:175], v[188:191], v[92:95]
	v_mfma_f32_16x16x32_bf16 v[88:91], v[180:183], v[188:191], v[88:91]
	v_mfma_f32_16x16x32_bf16 v[84:87], v[172:175], v[196:199], v[84:87]
	v_mfma_f32_16x16x32_bf16 v[80:83], v[180:183], v[196:199], v[80:83]
	v_mfma_f32_16x16x32_bf16 v[60:63], v[172:175], v[204:207], v[60:63]
	v_mfma_f32_16x16x32_bf16 v[48:51], v[180:183], v[204:207], v[48:51]
	v_mfma_f32_16x16x32_bf16 v[36:39], v[172:175], v[212:215], v[36:39]
	s_setprio 3
	s_barrier
	v_mfma_f32_16x16x32_bf16 v[32:35], v[180:183], v[212:215], v[32:35]
	s_setprio 0
	s_add_i32 s90, 0, 0x18000
	v_add_u32_e32 v155, s90, v150
	s_add_i32 s91, 0, 0x1c000
	ds_read_b128 v[146:149], v155
	ds_read_b128 v[156:159], v155 offset:1024
	ds_read_b128 v[160:163], v155 offset:2048
	ds_read_b128 v[164:167], v155 offset:3072
	v_add_u32_e32 v155, s91, v150
	ds_read_b128 v[168:171], v155
	ds_read_b128 v[172:175], v155 offset:1024
	ds_read_b128 v[176:179], v155 offset:2048
	ds_read_b128 v[180:183], v155 offset:3072
	s_add_u32 s62, s62, 0x100000
	s_addc_u32 s63, s63, 0
	s_mov_b32 m0, s72
	v_lshl_add_u64 v[224:225], s[62:63], 0, v[128:129]
	ds_read_b128 v[184:187], v154 offset:32768
	ds_read_b128 v[188:191], v154 offset:33792
	ds_read_b128 v[192:195], v154 offset:34816
	ds_read_b128 v[196:199], v154 offset:35840
	ds_read_b128 v[200:203], v154 offset:36864
	ds_read_b128 v[204:207], v154 offset:37888
	ds_read_b128 v[208:211], v154 offset:38912
	ds_read_b128 v[212:215], v154 offset:39936
	global_load_lds_dwordx4 v[224:225], off
	v_lshl_add_u64 v[224:225], s[62:63], 0, v[132:133]
	s_mov_b32 m0, s73
	s_nop 0
	global_load_lds_dwordx4 v[224:225], off
	s_waitcnt vmcnt(8)
	s_waitcnt lgkmcnt(0)
	s_barrier
	s_setprio 3
	s_waitcnt lgkmcnt(0)
	v_mfma_f32_16x16x32_bf16 v[76:79], v[146:149], v[184:187], v[76:79]
	v_mfma_f32_16x16x32_bf16 v[72:75], v[160:163], v[184:187], v[72:75]
	v_mfma_f32_16x16x32_bf16 v[68:71], v[146:149], v[192:195], v[68:71]
	v_mfma_f32_16x16x32_bf16 v[64:67], v[160:163], v[192:195], v[64:67]
	v_mfma_f32_16x16x32_bf16 v[56:59], v[146:149], v[200:203], v[56:59]
	v_mfma_f32_16x16x32_bf16 v[52:55], v[160:163], v[200:203], v[52:55]
	v_mfma_f32_16x16x32_bf16 v[44:47], v[146:149], v[208:211], v[44:47]
	v_mfma_f32_16x16x32_bf16 v[40:43], v[160:163], v[208:211], v[40:43]
	v_mfma_f32_16x16x32_bf16 v[76:79], v[156:159], v[188:191], v[76:79]
	v_mfma_f32_16x16x32_bf16 v[72:75], v[164:167], v[188:191], v[72:75]
	v_mfma_f32_16x16x32_bf16 v[68:71], v[156:159], v[196:199], v[68:71]
	v_mfma_f32_16x16x32_bf16 v[64:67], v[164:167], v[196:199], v[64:67]
	v_mfma_f32_16x16x32_bf16 v[56:59], v[156:159], v[204:207], v[56:59]
	v_mfma_f32_16x16x32_bf16 v[52:55], v[164:167], v[204:207], v[52:55]
	v_mfma_f32_16x16x32_bf16 v[44:47], v[156:159], v[212:215], v[44:47]
	v_mfma_f32_16x16x32_bf16 v[40:43], v[164:167], v[212:215], v[40:43]
	s_setprio 0
	s_setprio 3
	v_mfma_f32_16x16x32_bf16 v[124:127], v[168:171], v[184:187], v[124:127]
	v_mfma_f32_16x16x32_bf16 v[120:123], v[176:179], v[184:187], v[120:123]
	v_mfma_f32_16x16x32_bf16 v[116:119], v[168:171], v[192:195], v[116:119]
	v_mfma_f32_16x16x32_bf16 v[112:115], v[176:179], v[192:195], v[112:115]
	v_mfma_f32_16x16x32_bf16 v[108:111], v[168:171], v[200:203], v[108:111]
	v_mfma_f32_16x16x32_bf16 v[104:107], v[176:179], v[200:203], v[104:107]
	v_mfma_f32_16x16x32_bf16 v[100:103], v[168:171], v[208:211], v[100:103]
	v_mfma_f32_16x16x32_bf16 v[96:99], v[176:179], v[208:211], v[96:99]
	v_mfma_f32_16x16x32_bf16 v[124:127], v[172:175], v[188:191], v[124:127]
	v_mfma_f32_16x16x32_bf16 v[120:123], v[180:183], v[188:191], v[120:123]
	v_mfma_f32_16x16x32_bf16 v[116:119], v[172:175], v[196:199], v[116:119]
	v_mfma_f32_16x16x32_bf16 v[112:115], v[180:183], v[196:199], v[112:115]
	v_mfma_f32_16x16x32_bf16 v[108:111], v[172:175], v[204:207], v[108:111]
	v_mfma_f32_16x16x32_bf16 v[104:107], v[180:183], v[204:207], v[104:107]
	v_mfma_f32_16x16x32_bf16 v[100:103], v[172:175], v[212:215], v[100:103]
	s_setprio 3
	s_barrier
; #define PG8_STAGE(bufoff, gbase, voff) do { _Pragma("unroll") for (int _i = 0; _i < 2; ++_i) \
;         __builtin_amdgcn_global_load_lds((const unsigned*)((const char*)(gbase) + (voff)[_i]), (PG8_LAS unsigned*)(lds + (bufoff) + ldsw + _i * 8192), 16, 0, 0); } while (0)
; #define PG8_LDA(dst, b, h) do { _Pragma("unroll") for (int m = 0; m < 4; ++m) _Pragma("unroll") for (int k = 0; k < 2; ++k) dst[m][k] = *(const PG8_LAS bf16x8*)(lds + PG8_SA(b, h) + aoff + m * 2048 + k * 1024); } while (0)
; #define PG8_MMA(ai, bj, At, Bt) do { __builtin_amdgcn_s_setprio(1); _Pragma("unroll") for (int m = 0; m < 4; ++m) _Pragma("unroll") for (int n = 0; n < 2; ++n) _Pragma("unroll") for (int k = 0; k < 2; ++k) \
;         acc[ai][bj][m][n] = __builtin_amdgcn_mfma_f32_16x16x32_bf16(Bt[n][k], At[m][k], acc[ai][bj][m][n], 0, 0, 0); __builtin_amdgcn_s_setprio(0); } while (0)
; #define PG8_WAIT_V(n) asm volatile("s_waitcnt vmcnt(" #n ")" ::: "memory")
; #define PG8_WAIT_L(n) asm volatile("s_waitcnt lgkmcnt(" #n ")" ::: "memory")
; #define PG8_BAR __builtin_amdgcn_s_barrier()
; #define PG8_SCHED __builtin_amdgcn_sched_barrier(0)
; template <class Epi, class Sched, bool ALIGN_EPI = false, bool SP2 = false>
; __device__ __forceinline__ void gemm_phase(PG8_LAS unsigned char* lds, const Gemm g, const Sched& S, const Epi& E, const int wv  ) {
;     ...
;             PG8_LDA(At, 1, 1); PG8_STAGE(PG8_SB(1, 0), b3, voffB); PG8_STAGE(PG8_SB(1, 1), b3 + hstepB, voffB); PG8_STAGE(PG8_SA(1, 0), a3, voffA);
;             PG8_WAIT_V(8); PG8_WAIT_L(0); PG8_BAR; PG8_MMA(1, 0, At, B0); PG8_MMA(1, 1, At, B1); PG8_BAR; PG8_SCHED;
;     ...
;         if constexpr (ALIGN_EPI) { if (wr == 0) PG8_BAR; }
	v_mfma_f32_16x16x32_bf16 v[96:99], v[180:183], v[212:215], v[96:99]
	s_setprio 0
	s_add_i32 s62, s90, s69
	v_lshl_add_u64 v[216:217], v[216:217], 0, s[10:11]
	s_mov_b32 m0, s62
	ds_read_b128 v[184:187], v154 offset:49152
	ds_read_b128 v[188:191], v154 offset:50176
	ds_read_b128 v[192:195], v154 offset:51200
	ds_read_b128 v[196:199], v154 offset:52224
	ds_read_b128 v[200:203], v154 offset:53248
	ds_read_b128 v[204:207], v154 offset:54272
	ds_read_b128 v[208:211], v154 offset:55296
	ds_read_b128 v[212:215], v154 offset:56320
	global_load_lds_dwordx4 v[216:217], off
	s_add_i32 m0, s62, 0x2000
	s_add_u32 s60, s60, 0x100080
	v_lshl_add_u64 v[216:217], v[218:219], 0, s[10:11]
	s_addc_u32 s61, s61, 0
	s_add_i32 s62, s91, s69
	global_load_lds_dwordx4 v[216:217], off
	v_lshl_add_u64 v[216:217], s[60:61], 0, v[130:131]
	s_mov_b32 m0, s62
	s_nop 0
	global_load_lds_dwordx4 v[216:217], off
	v_lshl_add_u64 v[216:217], s[60:61], 0, v[134:135]
	s_add_i32 m0, s62, 0x2000
	s_nop 0
	global_load_lds_dwordx4 v[216:217], off
	v_lshl_add_u64 v[216:217], v[220:221], 0, s[10:11]
	s_mov_b32 m0, s64
	s_nop 0
	global_load_lds_dwordx4 v[216:217], off
	v_lshl_add_u64 v[216:217], v[222:223], 0, s[10:11]
	s_mov_b32 m0, s65
	s_nop 0
	global_load_lds_dwordx4 v[216:217], off
	s_waitcnt vmcnt(8)
	s_waitcnt lgkmcnt(0)
	s_barrier
	s_setprio 3
	s_waitcnt lgkmcnt(0)
	v_mfma_f32_16x16x32_bf16 v[28:31], v[146:149], v[184:187], v[28:31]
	v_mfma_f32_16x16x32_bf16 v[24:27], v[160:163], v[184:187], v[24:27]
	v_mfma_f32_16x16x32_bf16 v[20:23], v[146:149], v[192:195], v[20:23]
	v_mfma_f32_16x16x32_bf16 v[16:19], v[160:163], v[192:195], v[16:19]
	v_mfma_f32_16x16x32_bf16 v[12:15], v[146:149], v[200:203], v[12:15]
	v_mfma_f32_16x16x32_bf16 v[8:11], v[160:163], v[200:203], v[8:11]
	v_mfma_f32_16x16x32_bf16 v[4:7], v[146:149], v[208:211], v[4:7]
	v_mfma_f32_16x16x32_bf16 v[0:3], v[160:163], v[208:211], v[0:3]
	v_mfma_f32_16x16x32_bf16 v[28:31], v[156:159], v[188:191], v[28:31]
	v_mfma_f32_16x16x32_bf16 v[24:27], v[164:167], v[188:191], v[24:27]
	v_mfma_f32_16x16x32_bf16 v[20:23], v[156:159], v[196:199], v[20:23]
	v_mfma_f32_16x16x32_bf16 v[16:19], v[164:167], v[196:199], v[16:19]
	v_mfma_f32_16x16x32_bf16 v[12:15], v[156:159], v[204:207], v[12:15]
	v_mfma_f32_16x16x32_bf16 v[8:11], v[164:167], v[204:207], v[8:11]
	v_mfma_f32_16x16x32_bf16 v[4:7], v[156:159], v[212:215], v[4:7]
	v_mfma_f32_16x16x32_bf16 v[0:3], v[164:167], v[212:215], v[0:3]
	s_setprio 0
	s_setprio 3
	v_mfma_f32_16x16x32_bf16 v[92:95], v[168:171], v[184:187], v[92:95]
	v_mfma_f32_16x16x32_bf16 v[88:91], v[176:179], v[184:187], v[88:91]
	v_mfma_f32_16x16x32_bf16 v[84:87], v[168:171], v[192:195], v[84:87]
	v_mfma_f32_16x16x32_bf16 v[80:83], v[176:179], v[192:195], v[80:83]
	v_mfma_f32_16x16x32_bf16 v[60:63], v[168:171], v[200:203], v[60:63]
	v_mfma_f32_16x16x32_bf16 v[48:51], v[176:179], v[200:203], v[48:51]
	v_mfma_f32_16x16x32_bf16 v[36:39], v[168:171], v[208:211], v[36:39]
	v_mfma_f32_16x16x32_bf16 v[32:35], v[176:179], v[208:211], v[32:35]
	v_mfma_f32_16x16x32_bf16 v[92:95], v[172:175], v[188:191], v[92:95]
	v_mfma_f32_16x16x32_bf16 v[88:91], v[180:183], v[188:191], v[88:91]
	v_mfma_f32_16x16x32_bf16 v[84:87], v[172:175], v[196:199], v[84:87]
	v_mfma_f32_16x16x32_bf16 v[80:83], v[180:183], v[196:199], v[80:83]
	v_mfma_f32_16x16x32_bf16 v[60:63], v[172:175], v[204:207], v[60:63]
	v_mfma_f32_16x16x32_bf16 v[48:51], v[180:183], v[204:207], v[48:51]
	v_mfma_f32_16x16x32_bf16 v[36:39], v[172:175], v[212:215], v[36:39]
	s_setprio 3
	s_barrier
	v_mfma_f32_16x16x32_bf16 v[32:35], v[180:183], v[212:215], v[32:35]
	s_setprio 0
	s_add_i32 s87, s87, 2
	s_add_u32 s58, s58, 0x100
	s_addc_u32 s59, s59, 0
	s_add_u32 s85, s85, 0x100
	s_addc_u32 s86, s86, 0
	s_cmp_gt_u32 s87, 61
	s_cbranch_scc0 .LBB0_1717
	s_and_b64 vcc, exec, s[12:13]
	s_cbranch_vccz .LBB0_1720
	s_barrier

; #define PG8_STAGE(bufoff, gbase, voff) do { _Pragma("unroll") for (int _i = 0; _i < 2; ++_i) \
;         __builtin_amdgcn_global_load_lds((const unsigned*)((const char*)(gbase) + (voff)[_i]), (PG8_LAS unsigned*)(lds + (bufoff) + ldsw + _i * 8192), 16, 0, 0); } while (0)
; #define PG8_LDA(dst, b, h) do { _Pragma("unroll") for (int m = 0; m < 4; ++m) _Pragma("unroll") for (int k = 0; k < 2; ++k) dst[m][k] = *(const PG8_LAS bf16x8*)(lds + PG8_SA(b, h) + aoff + m * 2048 + k * 1024); } while (0)
; #define PG8_LDB(dst, b, h) do { _Pragma("unroll") for (int n = 0; n < 2; ++n) _Pragma("unroll") for (int k = 0; k < 2; ++k) dst[n][k] = *(const PG8_LAS bf16x8*)(lds + PG8_SB(b, h) + boff + n * 2048 + k * 1024); } while (0)
; #define PG8_MMA(ai, bj, At, Bt) do { __builtin_amdgcn_s_setprio(1); _Pragma("unroll") for (int m = 0; m < 4; ++m) _Pragma("unroll") for (int n = 0; n < 2; ++n) _Pragma("unroll") for (int k = 0; k < 2; ++k) \
;         acc[ai][bj][m][n] = __builtin_amdgcn_mfma_f32_16x16x32_bf16(Bt[n][k], At[m][k], acc[ai][bj][m][n], 0, 0, 0); __builtin_amdgcn_s_setprio(0); } while (0)
; #define PG8_WAIT_V(n) asm volatile("s_waitcnt vmcnt(" #n ")" ::: "memory")
; #define PG8_WAIT_L(n) asm volatile("s_waitcnt lgkmcnt(" #n ")" ::: "memory")
; #define PG8_BAR __builtin_amdgcn_s_barrier()
; #define PG8_SCHED __builtin_amdgcn_sched_barrier(0)
; template <class Epi, class Sched, bool ALIGN_EPI = false, bool SP2 = false>
; __device__ __forceinline__ void gemm_phase(PG8_LAS unsigned char* lds, const Gemm g, const Sched& S, const Epi& E, const int wv  ) {
;     ...
;             const bool last = (t == nt - 2);
;             const char* a1 = cA + (size_t)(t + 1) * kstep;
;             const char* a2 = last ? nA : cA + (size_t)(t + 2) * kstep; const char* b2 = last ? nB : cB + (size_t)(t + 2) * kstep;
;             const char* a3 = a2 + kstep; const char* b3 = b2 + kstep;
;             if (last && has_next) S.a_ready(nxt);
;             if constexpr (SP2) {
;             PG8_LDB(B0, 0, 0); PG8_LDB(B1, 0, 1); PG8_SCHED; PG8_LDA(At, 0, 0); PG8_STAGE(PG8_SA(1, 1), a1 + hstepA, voffA);
;             PG8_WAIT_V(8); PG8_WAIT_L(0); PG8_BAR; PG8_MMA(0, 0, At, B0); PG8_MMA(0, 1, At, B1); PG8_BAR; PG8_SCHED;
;             PG8_LDA(At, 0, 1); PG8_STAGE(PG8_SB(0, 0), b2, voffB); PG8_STAGE(PG8_SB(0, 1), b2 + hstepB, voffB); PG8_STAGE(PG8_SA(0, 0), a2, voffA);
.LBB0_2399:
	ds_read_b128 v[44:47], v196
	ds_read_b128 v[48:51], v196 offset:1024
	ds_read_b128 v[52:55], v196 offset:2048
	ds_read_b128 v[56:59], v196 offset:3072
	ds_read_b128 v[60:63], v197
	ds_read_b128 v[68:71], v197 offset:1024
	ds_read_b128 v[72:75], v197 offset:2048
	ds_read_b128 v[76:79], v197 offset:3072
	s_add_u32 s68, s66, 0xfff00080
	s_addc_u32 s69, s67, -1
	s_cmp_eq_u32 s94, 60
	s_cselect_b32 s71, s57, s69
	s_cselect_b32 s70, s63, s68
	s_cselect_b32 s69, s55, s93
	s_cselect_b32 s68, s65, s92
	v_lshl_add_u64 v[224:225], s[66:67], 0, v[172:173]
	s_add_i32 m0, s75, 0xc000
	ds_read_b128 v[180:183], v198
	ds_read_b128 v[184:187], v198 offset:1024
	ds_read_b128 v[200:203], v198 offset:2048
	ds_read_b128 v[204:207], v198 offset:3072
	ds_read_b128 v[208:211], v198 offset:4096
	ds_read_b128 v[212:215], v198 offset:5120
	ds_read_b128 v[216:219], v198 offset:6144
	ds_read_b128 v[220:223], v198 offset:7168
	global_load_lds_dwordx4 v[224:225], off
	v_lshl_add_u64 v[224:225], s[66:67], 0, v[174:175]
	s_add_i32 m0, s75, 0xe000
	s_nop 0
	global_load_lds_dwordx4 v[224:225], off
	s_waitcnt vmcnt(8)
	s_waitcnt lgkmcnt(0)
	s_barrier
	s_setprio 3
	s_waitcnt lgkmcnt(0)
	v_mfma_f32_16x16x32_bf16 v[104:107], v[44:47], v[180:183], v[104:107]
	v_mfma_f32_16x16x32_bf16 v[100:103], v[52:55], v[180:183], v[100:103]
	v_mfma_f32_16x16x32_bf16 v[156:159], v[44:47], v[200:203], v[156:159]
	v_mfma_f32_16x16x32_bf16 v[148:151], v[52:55], v[200:203], v[148:151]
	v_mfma_f32_16x16x32_bf16 v[140:143], v[44:47], v[208:211], v[140:143]
	v_mfma_f32_16x16x32_bf16 v[132:135], v[52:55], v[208:211], v[132:135]
	v_mfma_f32_16x16x32_bf16 v[124:127], v[44:47], v[216:219], v[124:127]
	v_mfma_f32_16x16x32_bf16 v[120:123], v[52:55], v[216:219], v[120:123]
	v_mfma_f32_16x16x32_bf16 v[104:107], v[48:51], v[184:187], v[104:107]
	v_mfma_f32_16x16x32_bf16 v[100:103], v[56:59], v[184:187], v[100:103]
	v_mfma_f32_16x16x32_bf16 v[156:159], v[48:51], v[204:207], v[156:159]
	v_mfma_f32_16x16x32_bf16 v[148:151], v[56:59], v[204:207], v[148:151]
	v_mfma_f32_16x16x32_bf16 v[140:143], v[48:51], v[212:215], v[140:143]
	v_mfma_f32_16x16x32_bf16 v[132:135], v[56:59], v[212:215], v[132:135]
	v_mfma_f32_16x16x32_bf16 v[124:127], v[48:51], v[220:223], v[124:127]
	v_mfma_f32_16x16x32_bf16 v[120:123], v[56:59], v[220:223], v[120:123]
	s_setprio 0
	s_setprio 3
	v_mfma_f32_16x16x32_bf16 v[92:95], v[60:63], v[180:183], v[92:95]
	v_mfma_f32_16x16x32_bf16 v[88:91], v[72:75], v[180:183], v[88:91]
	v_mfma_f32_16x16x32_bf16 v[152:155], v[60:63], v[200:203], v[152:155]
	v_mfma_f32_16x16x32_bf16 v[144:147], v[72:75], v[200:203], v[144:147]
	v_mfma_f32_16x16x32_bf16 v[136:139], v[60:63], v[208:211], v[136:139]
	v_mfma_f32_16x16x32_bf16 v[128:131], v[72:75], v[208:211], v[128:131]
	v_mfma_f32_16x16x32_bf16 v[116:119], v[60:63], v[216:219], v[116:119]
	v_mfma_f32_16x16x32_bf16 v[112:115], v[72:75], v[216:219], v[112:115]
	v_mfma_f32_16x16x32_bf16 v[92:95], v[68:71], v[184:187], v[92:95]
	v_mfma_f32_16x16x32_bf16 v[88:91], v[76:79], v[184:187], v[88:91]
	v_mfma_f32_16x16x32_bf16 v[152:155], v[68:71], v[204:207], v[152:155]
	v_mfma_f32_16x16x32_bf16 v[144:147], v[76:79], v[204:207], v[144:147]
	v_mfma_f32_16x16x32_bf16 v[136:139], v[68:71], v[212:215], v[136:139]
	v_mfma_f32_16x16x32_bf16 v[128:131], v[76:79], v[212:215], v[128:131]
	v_mfma_f32_16x16x32_bf16 v[116:119], v[68:71], v[220:223], v[116:119]
	s_setprio 3
	s_barrier
	v_mfma_f32_16x16x32_bf16 v[112:115], v[76:79], v[220:223], v[112:115]
	s_setprio 0
	s_add_i32 s95, s87, s74
	v_lshl_add_u64 v[228:229], s[68:69], 0, v[162:163]
	s_mov_b32 m0, s95
	ds_read_b128 v[180:183], v198 offset:16384
	ds_read_b128 v[184:187], v198 offset:17408
	ds_read_b128 v[200:203], v198 offset:18432
	ds_read_b128 v[204:207], v198 offset:19456
	ds_read_b128 v[208:211], v198 offset:20480
	ds_read_b128 v[212:215], v198 offset:21504
	ds_read_b128 v[216:219], v198 offset:22528
	ds_read_b128 v[220:223], v198 offset:23552
	global_load_lds_dwordx4 v[228:229], off
	s_add_i32 m0, s95, 0x2000
	s_add_u32 s96, s68, 0x100000
	v_lshl_add_u64 v[230:231], s[68:69], 0, v[166:167]
	s_addc_u32 s97, s69, 0
	s_add_i32 s95, s90, s74
	global_load_lds_dwordx4 v[230:231], off
	v_lshl_add_u64 v[224:225], s[96:97], 0, v[162:163]
	s_mov_b32 m0, s95
	v_lshl_add_u64 v[232:233], s[70:71], 0, v[160:161]
	global_load_lds_dwordx4 v[224:225], off
	v_lshl_add_u64 v[224:225], s[96:97], 0, v[166:167]
	s_add_i32 m0, s95, 0x2000
	v_lshl_add_u64 v[234:235], s[70:71], 0, v[164:165]
	global_load_lds_dwordx4 v[224:225], off
	s_mov_b32 m0, s75
	s_nop 0
	global_load_lds_dwordx4 v[232:233], off
	s_mov_b32 m0, s76
	s_nop 0
	global_load_lds_dwordx4 v[234:235], off
	s_waitcnt vmcnt(8)
	s_waitcnt lgkmcnt(0)
	s_barrier
; #define PG8_STAGE(bufoff, gbase, voff) do { _Pragma("unroll") for (int _i = 0; _i < 2; ++_i) \
;         __builtin_amdgcn_global_load_lds((const unsigned*)((const char*)(gbase) + (voff)[_i]), (PG8_LAS unsigned*)(lds + (bufoff) + ldsw + _i * 8192), 16, 0, 0); } while (0)
; #define PG8_LDA(dst, b, h) do { _Pragma("unroll") for (int m = 0; m < 4; ++m) _Pragma("unroll") for (int k = 0; k < 2; ++k) dst[m][k] = *(const PG8_LAS bf16x8*)(lds + PG8_SA(b, h) + aoff + m * 2048 + k * 1024); } while (0)
; #define PG8_LDB(dst, b, h) do { _Pragma("unroll") for (int n = 0; n < 2; ++n) _Pragma("unroll") for (int k = 0; k < 2; ++k) dst[n][k] = *(const PG8_LAS bf16x8*)(lds + PG8_SB(b, h) + boff + n * 2048 + k * 1024); } while (0)
; #define PG8_MMA(ai, bj, At, Bt) do { __builtin_amdgcn_s_setprio(1); _Pragma("unroll") for (int m = 0; m < 4; ++m) _Pragma("unroll") for (int n = 0; n < 2; ++n) _Pragma("unroll") for (int k = 0; k < 2; ++k) \
;         acc[ai][bj][m][n] = __builtin_amdgcn_mfma_f32_16x16x32_bf16(Bt[n][k], At[m][k], acc[ai][bj][m][n], 0, 0, 0); __builtin_amdgcn_s_setprio(0); } while (0)
; #define PG8_WAIT_V(n) asm volatile("s_waitcnt vmcnt(" #n ")" ::: "memory")
; #define PG8_WAIT_L(n) asm volatile("s_waitcnt lgkmcnt(" #n ")" ::: "memory")
; #define PG8_BAR __builtin_amdgcn_s_barrier()
; #define PG8_SCHED __builtin_amdgcn_sched_barrier(0)
; template <class Epi, class Sched, bool ALIGN_EPI = false, bool SP2 = false>
; __device__ __forceinline__ void gemm_phase(PG8_LAS unsigned char* lds, const Gemm g, const Sched& S, const Epi& E, const int wv  ) {
;     ...
;             PG8_WAIT_V(8); PG8_WAIT_L(0); PG8_BAR; PG8_MMA(1, 0, At, B0); PG8_MMA(1, 1, At, B1); PG8_BAR; PG8_SCHED;
;             PG8_LDB(B0, 1, 0); PG8_LDB(B1, 1, 1); PG8_SCHED; PG8_LDA(At, 1, 0); PG8_STAGE(PG8_SA(0, 1), a2 + hstepA, voffA);
;             PG8_WAIT_V(8); PG8_WAIT_L(0); PG8_BAR; PG8_MMA(0, 0, At, B0); PG8_MMA(0, 1, At, B1); PG8_BAR; PG8_SCHED;
	s_setprio 3
	s_waitcnt lgkmcnt(0)
	v_mfma_f32_16x16x32_bf16 v[108:111], v[44:47], v[180:183], v[108:111]
	v_mfma_f32_16x16x32_bf16 v[96:99], v[52:55], v[180:183], v[96:99]
	v_mfma_f32_16x16x32_bf16 v[64:67], v[44:47], v[200:203], v[64:67]
	v_mfma_f32_16x16x32_bf16 v[36:39], v[52:55], v[200:203], v[36:39]
	v_mfma_f32_16x16x32_bf16 v[28:31], v[44:47], v[208:211], v[28:31]
	v_mfma_f32_16x16x32_bf16 v[20:23], v[52:55], v[208:211], v[20:23]
	v_mfma_f32_16x16x32_bf16 v[12:15], v[44:47], v[216:219], v[12:15]
	v_mfma_f32_16x16x32_bf16 v[4:7], v[52:55], v[216:219], v[4:7]
	v_mfma_f32_16x16x32_bf16 v[108:111], v[48:51], v[184:187], v[108:111]
	v_mfma_f32_16x16x32_bf16 v[96:99], v[56:59], v[184:187], v[96:99]
	v_mfma_f32_16x16x32_bf16 v[64:67], v[48:51], v[204:207], v[64:67]
	v_mfma_f32_16x16x32_bf16 v[36:39], v[56:59], v[204:207], v[36:39]
	v_mfma_f32_16x16x32_bf16 v[28:31], v[48:51], v[212:215], v[28:31]
	v_mfma_f32_16x16x32_bf16 v[20:23], v[56:59], v[212:215], v[20:23]
	v_mfma_f32_16x16x32_bf16 v[12:15], v[48:51], v[220:223], v[12:15]
	v_mfma_f32_16x16x32_bf16 v[4:7], v[56:59], v[220:223], v[4:7]
	s_setprio 0
	s_setprio 3
	v_mfma_f32_16x16x32_bf16 v[40:43], v[60:63], v[200:203], v[40:43]
	v_mfma_f32_16x16x32_bf16 v[32:35], v[72:75], v[200:203], v[32:35]
	v_mfma_f32_16x16x32_bf16 v[24:27], v[60:63], v[208:211], v[24:27]
	v_mfma_f32_16x16x32_bf16 v[16:19], v[72:75], v[208:211], v[16:19]
	v_mfma_f32_16x16x32_bf16 v[8:11], v[60:63], v[216:219], v[8:11]
	v_mfma_f32_16x16x32_bf16 v[0:3], v[72:75], v[216:219], v[0:3]
	v_mfma_f32_16x16x32_bf16 v[44:47], v[60:63], v[180:183], v[84:87]
	v_mfma_f32_16x16x32_bf16 v[48:51], v[72:75], v[180:183], v[80:83]
	v_mfma_f32_16x16x32_bf16 v[40:43], v[68:71], v[204:207], v[40:43]
	v_mfma_f32_16x16x32_bf16 v[32:35], v[76:79], v[204:207], v[32:35]
	v_mfma_f32_16x16x32_bf16 v[24:27], v[68:71], v[212:215], v[24:27]
	v_mfma_f32_16x16x32_bf16 v[16:19], v[76:79], v[212:215], v[16:19]
	v_mfma_f32_16x16x32_bf16 v[8:11], v[68:71], v[220:223], v[8:11]
	v_mfma_f32_16x16x32_bf16 v[0:3], v[76:79], v[220:223], v[0:3]
	v_mfma_f32_16x16x32_bf16 v[44:47], v[68:71], v[184:187], v[44:47]
	s_setprio 3
	s_barrier
	v_mfma_f32_16x16x32_bf16 v[48:51], v[76:79], v[184:187], v[48:51]
	s_setprio 0
	s_add_i32 s95, 0, 0x18000
	s_add_i32 s96, 0, 0x1c000
	v_add_u32_e32 v68, s95, v190
	v_add_u32_e32 v80, s96, v190
	ds_read_b128 v[52:55], v68
	ds_read_b128 v[56:59], v68 offset:1024
	ds_read_b128 v[60:63], v68 offset:2048
	ds_read_b128 v[68:71], v68 offset:3072
	ds_read_b128 v[72:75], v80
	ds_read_b128 v[76:79], v80 offset:1024
	ds_read_b128 v[180:183], v80 offset:2048
	ds_read_b128 v[184:187], v80 offset:3072
	s_add_u32 s70, s70, 0x100000
	s_addc_u32 s71, s71, 0
	s_mov_b32 m0, s77
	v_lshl_add_u64 v[224:225], s[70:71], 0, v[160:161]
	ds_read_b128 v[80:83], v198 offset:32768
	ds_read_b128 v[84:87], v198 offset:33792
	ds_read_b128 v[200:203], v198 offset:34816
	ds_read_b128 v[204:207], v198 offset:35840
	ds_read_b128 v[208:211], v198 offset:36864
	ds_read_b128 v[212:215], v198 offset:37888
	ds_read_b128 v[216:219], v198 offset:38912
	ds_read_b128 v[220:223], v198 offset:39936
	global_load_lds_dwordx4 v[224:225], off
	v_lshl_add_u64 v[224:225], s[70:71], 0, v[164:165]
	s_mov_b32 m0, s78
	s_nop 0
	global_load_lds_dwordx4 v[224:225], off
	s_waitcnt vmcnt(8)
	s_waitcnt lgkmcnt(0)
	s_barrier
	s_setprio 3
	s_waitcnt lgkmcnt(0)
	v_mfma_f32_16x16x32_bf16 v[104:107], v[52:55], v[80:83], v[104:107]
	v_mfma_f32_16x16x32_bf16 v[100:103], v[60:63], v[80:83], v[100:103]
	v_mfma_f32_16x16x32_bf16 v[156:159], v[52:55], v[200:203], v[156:159]
	v_mfma_f32_16x16x32_bf16 v[148:151], v[60:63], v[200:203], v[148:151]
	v_mfma_f32_16x16x32_bf16 v[140:143], v[52:55], v[208:211], v[140:143]
	v_mfma_f32_16x16x32_bf16 v[132:135], v[60:63], v[208:211], v[132:135]
	v_mfma_f32_16x16x32_bf16 v[124:127], v[52:55], v[216:219], v[124:127]
	v_mfma_f32_16x16x32_bf16 v[120:123], v[60:63], v[216:219], v[120:123]
	v_mfma_f32_16x16x32_bf16 v[104:107], v[56:59], v[84:87], v[104:107]
	v_mfma_f32_16x16x32_bf16 v[100:103], v[68:71], v[84:87], v[100:103]
	v_mfma_f32_16x16x32_bf16 v[156:159], v[56:59], v[204:207], v[156:159]
	v_mfma_f32_16x16x32_bf16 v[148:151], v[68:71], v[204:207], v[148:151]
	v_mfma_f32_16x16x32_bf16 v[140:143], v[56:59], v[212:215], v[140:143]
	v_mfma_f32_16x16x32_bf16 v[132:135], v[68:71], v[212:215], v[132:135]
	v_mfma_f32_16x16x32_bf16 v[124:127], v[56:59], v[220:223], v[124:127]
	v_mfma_f32_16x16x32_bf16 v[120:123], v[68:71], v[220:223], v[120:123]
	s_setprio 0
	s_setprio 3
	v_mfma_f32_16x16x32_bf16 v[92:95], v[72:75], v[80:83], v[92:95]
	v_mfma_f32_16x16x32_bf16 v[80:83], v[180:183], v[80:83], v[88:91]
	v_mfma_f32_16x16x32_bf16 v[88:91], v[184:187], v[84:87], v[80:83]
	v_mfma_f32_16x16x32_bf16 v[80:83], v[72:75], v[200:203], v[152:155]
	v_mfma_f32_16x16x32_bf16 v[152:155], v[76:79], v[204:207], v[80:83]
	v_mfma_f32_16x16x32_bf16 v[80:83], v[180:183], v[200:203], v[144:147]
	v_mfma_f32_16x16x32_bf16 v[144:147], v[184:187], v[204:207], v[80:83]
	v_mfma_f32_16x16x32_bf16 v[80:83], v[72:75], v[208:211], v[136:139]
	v_mfma_f32_16x16x32_bf16 v[136:139], v[76:79], v[212:215], v[80:83]
	v_mfma_f32_16x16x32_bf16 v[80:83], v[180:183], v[208:211], v[128:131]
	v_mfma_f32_16x16x32_bf16 v[128:131], v[184:187], v[212:215], v[80:83]
	v_mfma_f32_16x16x32_bf16 v[80:83], v[72:75], v[216:219], v[116:119]
	v_mfma_f32_16x16x32_bf16 v[116:119], v[76:79], v[220:223], v[80:83]
	v_mfma_f32_16x16x32_bf16 v[80:83], v[180:183], v[216:219], v[112:115]
	v_mfma_f32_16x16x32_bf16 v[92:95], v[76:79], v[84:87], v[92:95]
	s_setprio 3
	s_barrier
; #define PG8_STAGE(bufoff, gbase, voff) do { _Pragma("unroll") for (int _i = 0; _i < 2; ++_i) \
;         __builtin_amdgcn_global_load_lds((const unsigned*)((const char*)(gbase) + (voff)[_i]), (PG8_LAS unsigned*)(lds + (bufoff) + ldsw + _i * 8192), 16, 0, 0); } while (0)
; #define PG8_LDA(dst, b, h) do { _Pragma("unroll") for (int m = 0; m < 4; ++m) _Pragma("unroll") for (int k = 0; k < 2; ++k) dst[m][k] = *(const PG8_LAS bf16x8*)(lds + PG8_SA(b, h) + aoff + m * 2048 + k * 1024); } while (0)
; #define PG8_MMA(ai, bj, At, Bt) do { __builtin_amdgcn_s_setprio(1); _Pragma("unroll") for (int m = 0; m < 4; ++m) _Pragma("unroll") for (int n = 0; n < 2; ++n) _Pragma("unroll") for (int k = 0; k < 2; ++k) \
;         acc[ai][bj][m][n] = __builtin_amdgcn_mfma_f32_16x16x32_bf16(Bt[n][k], At[m][k], acc[ai][bj][m][n], 0, 0, 0); __builtin_amdgcn_s_setprio(0); } while (0)
; #define PG8_WAIT_V(n) asm volatile("s_waitcnt vmcnt(" #n ")" ::: "memory")
; #define PG8_WAIT_L(n) asm volatile("s_waitcnt lgkmcnt(" #n ")" ::: "memory")
; #define PG8_BAR __builtin_amdgcn_s_barrier()
; #define PG8_SCHED __builtin_amdgcn_sched_barrier(0)
; template <class Epi, class Sched, bool ALIGN_EPI = false, bool SP2 = false>
; __device__ __forceinline__ void gemm_phase(PG8_LAS unsigned char* lds, const Gemm g, const Sched& S, const Epi& E, const int wv  ) {
;     ...
;             PG8_LDA(At, 1, 1); PG8_STAGE(PG8_SB(1, 0), b3, voffB); PG8_STAGE(PG8_SB(1, 1), b3 + hstepB, voffB); PG8_STAGE(PG8_SA(1, 0), a3, voffA);
;             PG8_WAIT_V(8); PG8_WAIT_L(0); PG8_BAR; PG8_MMA(1, 0, At, B0); PG8_MMA(1, 1, At, B1); PG8_BAR; PG8_SCHED;
	v_mfma_f32_16x16x32_bf16 v[112:115], v[184:187], v[220:223], v[80:83]
	s_setprio 0
	s_add_i32 s70, s95, s74
	v_lshl_add_u64 v[84:85], v[228:229], 0, s[20:21]
	s_mov_b32 m0, s70
	s_nop 0
	ds_read_b128 v[80:83], v198 offset:49152
	ds_read_b128 v[200:203], v198 offset:50176
	ds_read_b128 v[204:207], v198 offset:51200
	ds_read_b128 v[208:211], v198 offset:52224
	ds_read_b128 v[212:215], v198 offset:53248
	ds_read_b128 v[216:219], v198 offset:54272
	ds_read_b128 v[220:223], v198 offset:55296
	ds_read_b128 v[224:227], v198 offset:56320
	global_load_lds_dwordx4 v[84:85], off
	s_add_i32 m0, s70, 0x2000
	s_add_u32 s68, s68, 0x100080
	v_lshl_add_u64 v[84:85], v[230:231], 0, s[20:21]
	s_addc_u32 s69, s69, 0
	s_add_i32 s70, s96, s74
	global_load_lds_dwordx4 v[84:85], off
	v_lshl_add_u64 v[84:85], s[68:69], 0, v[162:163]
	s_mov_b32 m0, s70
	s_nop 0
	global_load_lds_dwordx4 v[84:85], off
	v_lshl_add_u64 v[84:85], s[68:69], 0, v[166:167]
	s_add_i32 m0, s70, 0x2000
	s_nop 0
	global_load_lds_dwordx4 v[84:85], off
	v_lshl_add_u64 v[84:85], v[232:233], 0, s[20:21]
	s_mov_b32 m0, s82
	s_nop 0
	global_load_lds_dwordx4 v[84:85], off
	v_lshl_add_u64 v[84:85], v[234:235], 0, s[20:21]
	s_mov_b32 m0, s83
	s_nop 0
	global_load_lds_dwordx4 v[84:85], off
	s_waitcnt vmcnt(8)
	s_waitcnt lgkmcnt(0)
	s_barrier
	s_setprio 3
	s_waitcnt lgkmcnt(0)
	v_mfma_f32_16x16x32_bf16 v[84:87], v[52:55], v[80:83], v[108:111]
	v_mfma_f32_16x16x32_bf16 v[108:111], v[56:59], v[200:203], v[84:87]
	v_mfma_f32_16x16x32_bf16 v[84:87], v[60:63], v[80:83], v[96:99]
	v_mfma_f32_16x16x32_bf16 v[64:67], v[52:55], v[204:207], v[64:67]
	v_mfma_f32_16x16x32_bf16 v[36:39], v[60:63], v[204:207], v[36:39]
	v_mfma_f32_16x16x32_bf16 v[28:31], v[52:55], v[212:215], v[28:31]
	v_mfma_f32_16x16x32_bf16 v[20:23], v[60:63], v[212:215], v[20:23]
	v_mfma_f32_16x16x32_bf16 v[12:15], v[52:55], v[220:223], v[12:15]
	v_mfma_f32_16x16x32_bf16 v[4:7], v[60:63], v[220:223], v[4:7]
	v_mfma_f32_16x16x32_bf16 v[96:99], v[68:71], v[200:203], v[84:87]
	v_mfma_f32_16x16x32_bf16 v[64:67], v[56:59], v[208:211], v[64:67]
	v_mfma_f32_16x16x32_bf16 v[36:39], v[68:71], v[208:211], v[36:39]
	v_mfma_f32_16x16x32_bf16 v[28:31], v[56:59], v[216:219], v[28:31]
	v_mfma_f32_16x16x32_bf16 v[20:23], v[68:71], v[216:219], v[20:23]
	v_mfma_f32_16x16x32_bf16 v[12:15], v[56:59], v[224:227], v[12:15]
	v_mfma_f32_16x16x32_bf16 v[4:7], v[68:71], v[224:227], v[4:7]
	s_setprio 0
	s_setprio 3
	v_mfma_f32_16x16x32_bf16 v[44:47], v[72:75], v[80:83], v[44:47]
	v_mfma_f32_16x16x32_bf16 v[84:87], v[76:79], v[200:203], v[44:47]
	v_mfma_f32_16x16x32_bf16 v[44:47], v[180:183], v[80:83], v[48:51]
	v_mfma_f32_16x16x32_bf16 v[40:43], v[72:75], v[204:207], v[40:43]
	v_mfma_f32_16x16x32_bf16 v[32:35], v[180:183], v[204:207], v[32:35]
	v_mfma_f32_16x16x32_bf16 v[24:27], v[72:75], v[212:215], v[24:27]
	v_mfma_f32_16x16x32_bf16 v[16:19], v[180:183], v[212:215], v[16:19]
	v_mfma_f32_16x16x32_bf16 v[8:11], v[72:75], v[220:223], v[8:11]
	v_mfma_f32_16x16x32_bf16 v[0:3], v[180:183], v[220:223], v[0:3]
	v_mfma_f32_16x16x32_bf16 v[80:83], v[184:187], v[200:203], v[44:47]
	v_mfma_f32_16x16x32_bf16 v[40:43], v[76:79], v[208:211], v[40:43]
	v_mfma_f32_16x16x32_bf16 v[32:35], v[184:187], v[208:211], v[32:35]
	v_mfma_f32_16x16x32_bf16 v[24:27], v[76:79], v[216:219], v[24:27]
	v_mfma_f32_16x16x32_bf16 v[16:19], v[184:187], v[216:219], v[16:19]
	v_mfma_f32_16x16x32_bf16 v[8:11], v[76:79], v[224:227], v[8:11]
	s_setprio 3
	s_barrier
	v_mfma_f32_16x16x32_bf16 v[0:3], v[184:187], v[224:227], v[0:3]
	s_setprio 0
	s_add_i32 s94, s94, 2
	s_add_u32 s66, s66, 0x100
	s_addc_u32 s67, s67, 0
	s_add_u32 s92, s92, 0x100
	s_addc_u32 s93, s93, 0
	s_cmp_gt_u32 s94, 61
	s_cbranch_scc0 .LBB0_2399
	s_and_b64 vcc, exec, s[22:23]
	s_cbranch_vccz .LBB0_2402
	s_barrier

; #define PG8_STAGE(bufoff, gbase, voff) do { _Pragma("unroll") for (int _i = 0; _i < 2; ++_i) \
;         __builtin_amdgcn_global_load_lds((const unsigned*)((const char*)(gbase) + (voff)[_i]), (PG8_LAS unsigned*)(lds + (bufoff) + ldsw + _i * 8192), 16, 0, 0); } while (0)
; #define PG8_LDA(dst, b, h) do { _Pragma("unroll") for (int m = 0; m < 4; ++m) _Pragma("unroll") for (int k = 0; k < 2; ++k) dst[m][k] = *(const PG8_LAS bf16x8*)(lds + PG8_SA(b, h) + aoff + m * 2048 + k * 1024); } while (0)
; #define PG8_LDB(dst, b, h) do { _Pragma("unroll") for (int n = 0; n < 2; ++n) _Pragma("unroll") for (int k = 0; k < 2; ++k) dst[n][k] = *(const PG8_LAS bf16x8*)(lds + PG8_SB(b, h) + boff + n * 2048 + k * 1024); } while (0)
; #define PG8_MMA(ai, bj, At, Bt) do { __builtin_amdgcn_s_setprio(1); _Pragma("unroll") for (int m = 0; m < 4; ++m) _Pragma("unroll") for (int n = 0; n < 2; ++n) _Pragma("unroll") for (int k = 0; k < 2; ++k) \
;         acc[ai][bj][m][n] = __builtin_amdgcn_mfma_f32_16x16x32_bf16(Bt[n][k], At[m][k], acc[ai][bj][m][n], 0, 0, 0); __builtin_amdgcn_s_setprio(0); } while (0)
; #define PG8_WAIT_V(n) asm volatile("s_waitcnt vmcnt(" #n ")" ::: "memory")
; #define PG8_WAIT_L(n) asm volatile("s_waitcnt lgkmcnt(" #n ")" ::: "memory")
; #define PG8_BAR __builtin_amdgcn_s_barrier()
; #define PG8_SCHED __builtin_amdgcn_sched_barrier(0)
; template <class Epi, class Sched, bool ALIGN_EPI = false, bool SP2 = false>
; __device__ __forceinline__ void gemm_phase(PG8_LAS unsigned char* lds, const Gemm g, const Sched& S, const Epi& E, const int wv  ) {
;     ...
;             const bool last = (t == nt - 2);
;             const char* a1 = cA + (size_t)(t + 1) * kstep;
;             const char* a2 = last ? nA : cA + (size_t)(t + 2) * kstep; const char* b2 = last ? nB : cB + (size_t)(t + 2) * kstep;
;             const char* a3 = a2 + kstep; const char* b3 = b2 + kstep;
;             if (last && has_next) S.a_ready(nxt);
;             if constexpr (SP2) {
;             PG8_LDB(B0, 0, 0); PG8_LDB(B1, 0, 1); PG8_SCHED; PG8_LDA(At, 0, 0); PG8_STAGE(PG8_SA(1, 1), a1 + hstepA, voffA);
;             PG8_WAIT_V(8); PG8_WAIT_L(0); PG8_BAR; PG8_MMA(0, 0, At, B0); PG8_MMA(0, 1, At, B1); PG8_BAR; PG8_SCHED;
;             PG8_LDA(At, 0, 1); PG8_STAGE(PG8_SB(0, 0), b2, voffB); PG8_STAGE(PG8_SB(0, 1), b2 + hstepB, voffB); PG8_STAGE(PG8_SA(0, 0), a2, voffA);
.LBB0_2756:
	ds_read_b128 v[146:149], v152
	ds_read_b128 v[156:159], v152 offset:1024
	ds_read_b128 v[160:163], v152 offset:2048
	ds_read_b128 v[164:167], v152 offset:3072
	ds_read_b128 v[168:171], v153
	ds_read_b128 v[172:175], v153 offset:1024
	ds_read_b128 v[176:179], v153 offset:2048
	ds_read_b128 v[180:183], v153 offset:3072
	s_add_u32 s54, s52, 0x100
	s_addc_u32 s55, s53, 0
	s_cmpk_eq_i32 s84, 0xa8
	s_cselect_b32 s59, s7, s55
	s_cselect_b32 s58, s6, s54
	s_cselect_b32 s57, s51, s83
	s_cselect_b32 s56, s50, s82
	v_lshl_add_u64 v[216:217], s[52:53], 0, v[138:139]
	s_add_i32 m0, s63, 0xc000
	ds_read_b128 v[184:187], v154
	ds_read_b128 v[188:191], v154 offset:1024
	ds_read_b128 v[192:195], v154 offset:2048
	ds_read_b128 v[196:199], v154 offset:3072
	ds_read_b128 v[200:203], v154 offset:4096
	ds_read_b128 v[204:207], v154 offset:5120
	ds_read_b128 v[208:211], v154 offset:6144
	ds_read_b128 v[212:215], v154 offset:7168
	global_load_lds_dwordx4 v[216:217], off
	v_lshl_add_u64 v[216:217], s[52:53], 0, v[140:141]
	s_add_i32 m0, s63, 0xe000
	s_nop 0
	global_load_lds_dwordx4 v[216:217], off
	s_waitcnt vmcnt(8)
	s_waitcnt lgkmcnt(0)
	s_barrier
	s_setprio 3
	s_waitcnt lgkmcnt(0)
	v_mfma_f32_16x16x32_bf16 v[76:79], v[146:149], v[184:187], v[76:79]
	v_mfma_f32_16x16x32_bf16 v[72:75], v[160:163], v[184:187], v[72:75]
	v_mfma_f32_16x16x32_bf16 v[68:71], v[146:149], v[192:195], v[68:71]
	v_mfma_f32_16x16x32_bf16 v[64:67], v[160:163], v[192:195], v[64:67]
	v_mfma_f32_16x16x32_bf16 v[56:59], v[146:149], v[200:203], v[56:59]
	v_mfma_f32_16x16x32_bf16 v[52:55], v[160:163], v[200:203], v[52:55]
	v_mfma_f32_16x16x32_bf16 v[44:47], v[146:149], v[208:211], v[44:47]
	v_mfma_f32_16x16x32_bf16 v[40:43], v[160:163], v[208:211], v[40:43]
	v_mfma_f32_16x16x32_bf16 v[76:79], v[156:159], v[188:191], v[76:79]
	v_mfma_f32_16x16x32_bf16 v[72:75], v[164:167], v[188:191], v[72:75]
	v_mfma_f32_16x16x32_bf16 v[68:71], v[156:159], v[196:199], v[68:71]
	v_mfma_f32_16x16x32_bf16 v[64:67], v[164:167], v[196:199], v[64:67]
	v_mfma_f32_16x16x32_bf16 v[56:59], v[156:159], v[204:207], v[56:59]
	v_mfma_f32_16x16x32_bf16 v[52:55], v[164:167], v[204:207], v[52:55]
	v_mfma_f32_16x16x32_bf16 v[44:47], v[156:159], v[212:215], v[44:47]
	v_mfma_f32_16x16x32_bf16 v[40:43], v[164:167], v[212:215], v[40:43]
	s_setprio 0
	s_setprio 3
	v_mfma_f32_16x16x32_bf16 v[124:127], v[168:171], v[184:187], v[124:127]
	v_mfma_f32_16x16x32_bf16 v[120:123], v[176:179], v[184:187], v[120:123]
	v_mfma_f32_16x16x32_bf16 v[116:119], v[168:171], v[192:195], v[116:119]
	v_mfma_f32_16x16x32_bf16 v[112:115], v[176:179], v[192:195], v[112:115]
	v_mfma_f32_16x16x32_bf16 v[108:111], v[168:171], v[200:203], v[108:111]
	v_mfma_f32_16x16x32_bf16 v[104:107], v[176:179], v[200:203], v[104:107]
	v_mfma_f32_16x16x32_bf16 v[100:103], v[168:171], v[208:211], v[100:103]
	v_mfma_f32_16x16x32_bf16 v[96:99], v[176:179], v[208:211], v[96:99]
	v_mfma_f32_16x16x32_bf16 v[124:127], v[172:175], v[188:191], v[124:127]
	v_mfma_f32_16x16x32_bf16 v[120:123], v[180:183], v[188:191], v[120:123]
	v_mfma_f32_16x16x32_bf16 v[116:119], v[172:175], v[196:199], v[116:119]
	v_mfma_f32_16x16x32_bf16 v[112:115], v[180:183], v[196:199], v[112:115]
	v_mfma_f32_16x16x32_bf16 v[108:111], v[172:175], v[204:207], v[108:111]
	v_mfma_f32_16x16x32_bf16 v[104:107], v[180:183], v[204:207], v[104:107]
	v_mfma_f32_16x16x32_bf16 v[100:103], v[172:175], v[212:215], v[100:103]
	s_setprio 3
	s_barrier
	v_mfma_f32_16x16x32_bf16 v[96:99], v[180:183], v[212:215], v[96:99]
	s_setprio 0
	s_add_i32 s52, s72, s62
	v_lshl_add_u64 v[216:217], s[56:57], 0, v[130:131]
	s_mov_b32 m0, s52
	ds_read_b128 v[184:187], v154 offset:16384
	ds_read_b128 v[188:191], v154 offset:17408
	ds_read_b128 v[192:195], v154 offset:18432
	ds_read_b128 v[196:199], v154 offset:19456
	ds_read_b128 v[200:203], v154 offset:20480
	ds_read_b128 v[204:207], v154 offset:21504
	ds_read_b128 v[208:211], v154 offset:22528
	ds_read_b128 v[212:215], v154 offset:23552
	global_load_lds_dwordx4 v[216:217], off
	s_add_i32 m0, s52, 0x2000
	s_add_u32 s52, s56, 0x2b0000
	v_lshl_add_u64 v[218:219], s[56:57], 0, v[134:135]
	s_addc_u32 s53, s57, 0
	s_add_i32 s85, s73, s62
	global_load_lds_dwordx4 v[218:219], off
	v_lshl_add_u64 v[220:221], s[52:53], 0, v[130:131]
	s_mov_b32 m0, s85
	v_lshl_add_u64 v[222:223], s[58:59], 0, v[132:133]
	global_load_lds_dwordx4 v[220:221], off
	v_lshl_add_u64 v[220:221], s[52:53], 0, v[134:135]
	s_add_i32 m0, s85, 0x2000
	s_nop 0
	global_load_lds_dwordx4 v[220:221], off
	v_lshl_add_u64 v[220:221], s[58:59], 0, v[128:129]
	s_mov_b32 m0, s63
	s_nop 0
	global_load_lds_dwordx4 v[220:221], off
	s_mov_b32 m0, s64
	s_nop 0
	global_load_lds_dwordx4 v[222:223], off
	s_waitcnt vmcnt(8)
	s_waitcnt lgkmcnt(0)
	s_barrier
; #define PG8_STAGE(bufoff, gbase, voff) do { _Pragma("unroll") for (int _i = 0; _i < 2; ++_i) \
;         __builtin_amdgcn_global_load_lds((const unsigned*)((const char*)(gbase) + (voff)[_i]), (PG8_LAS unsigned*)(lds + (bufoff) + ldsw + _i * 8192), 16, 0, 0); } while (0)
; #define PG8_LDA(dst, b, h) do { _Pragma("unroll") for (int m = 0; m < 4; ++m) _Pragma("unroll") for (int k = 0; k < 2; ++k) dst[m][k] = *(const PG8_LAS bf16x8*)(lds + PG8_SA(b, h) + aoff + m * 2048 + k * 1024); } while (0)
; #define PG8_LDB(dst, b, h) do { _Pragma("unroll") for (int n = 0; n < 2; ++n) _Pragma("unroll") for (int k = 0; k < 2; ++k) dst[n][k] = *(const PG8_LAS bf16x8*)(lds + PG8_SB(b, h) + boff + n * 2048 + k * 1024); } while (0)
; #define PG8_MMA(ai, bj, At, Bt) do { __builtin_amdgcn_s_setprio(1); _Pragma("unroll") for (int m = 0; m < 4; ++m) _Pragma("unroll") for (int n = 0; n < 2; ++n) _Pragma("unroll") for (int k = 0; k < 2; ++k) \
;         acc[ai][bj][m][n] = __builtin_amdgcn_mfma_f32_16x16x32_bf16(Bt[n][k], At[m][k], acc[ai][bj][m][n], 0, 0, 0); __builtin_amdgcn_s_setprio(0); } while (0)
; #define PG8_WAIT_V(n) asm volatile("s_waitcnt vmcnt(" #n ")" ::: "memory")
; #define PG8_WAIT_L(n) asm volatile("s_waitcnt lgkmcnt(" #n ")" ::: "memory")
; #define PG8_BAR __builtin_amdgcn_s_barrier()
; #define PG8_SCHED __builtin_amdgcn_sched_barrier(0)
; template <class Epi, class Sched, bool ALIGN_EPI = false, bool SP2 = false>
; __device__ __forceinline__ void gemm_phase(PG8_LAS unsigned char* lds, const Gemm g, const Sched& S, const Epi& E, const int wv  ) {
;     ...
;             PG8_WAIT_V(8); PG8_WAIT_L(0); PG8_BAR; PG8_MMA(1, 0, At, B0); PG8_MMA(1, 1, At, B1); PG8_BAR; PG8_SCHED;
;             PG8_LDB(B0, 1, 0); PG8_LDB(B1, 1, 1); PG8_SCHED; PG8_LDA(At, 1, 0); PG8_STAGE(PG8_SA(0, 1), a2 + hstepA, voffA);
;             PG8_WAIT_V(8); PG8_WAIT_L(0); PG8_BAR; PG8_MMA(0, 0, At, B0); PG8_MMA(0, 1, At, B1); PG8_BAR; PG8_SCHED;
	s_setprio 3
	s_waitcnt lgkmcnt(0)
	v_mfma_f32_16x16x32_bf16 v[28:31], v[146:149], v[184:187], v[28:31]
	v_mfma_f32_16x16x32_bf16 v[24:27], v[160:163], v[184:187], v[24:27]
	v_mfma_f32_16x16x32_bf16 v[20:23], v[146:149], v[192:195], v[20:23]
	v_mfma_f32_16x16x32_bf16 v[16:19], v[160:163], v[192:195], v[16:19]
	v_mfma_f32_16x16x32_bf16 v[12:15], v[146:149], v[200:203], v[12:15]
	v_mfma_f32_16x16x32_bf16 v[8:11], v[160:163], v[200:203], v[8:11]
	v_mfma_f32_16x16x32_bf16 v[4:7], v[146:149], v[208:211], v[4:7]
	v_mfma_f32_16x16x32_bf16 v[0:3], v[160:163], v[208:211], v[0:3]
	v_mfma_f32_16x16x32_bf16 v[28:31], v[156:159], v[188:191], v[28:31]
	v_mfma_f32_16x16x32_bf16 v[24:27], v[164:167], v[188:191], v[24:27]
	v_mfma_f32_16x16x32_bf16 v[20:23], v[156:159], v[196:199], v[20:23]
	v_mfma_f32_16x16x32_bf16 v[16:19], v[164:167], v[196:199], v[16:19]
	v_mfma_f32_16x16x32_bf16 v[12:15], v[156:159], v[204:207], v[12:15]
	v_mfma_f32_16x16x32_bf16 v[8:11], v[164:167], v[204:207], v[8:11]
	v_mfma_f32_16x16x32_bf16 v[4:7], v[156:159], v[212:215], v[4:7]
	v_mfma_f32_16x16x32_bf16 v[0:3], v[164:167], v[212:215], v[0:3]
	s_setprio 0
	s_setprio 3
	v_mfma_f32_16x16x32_bf16 v[92:95], v[168:171], v[184:187], v[92:95]
	v_mfma_f32_16x16x32_bf16 v[88:91], v[176:179], v[184:187], v[88:91]
	v_mfma_f32_16x16x32_bf16 v[84:87], v[168:171], v[192:195], v[84:87]
	v_mfma_f32_16x16x32_bf16 v[80:83], v[176:179], v[192:195], v[80:83]
	v_mfma_f32_16x16x32_bf16 v[60:63], v[168:171], v[200:203], v[60:63]
	v_mfma_f32_16x16x32_bf16 v[48:51], v[176:179], v[200:203], v[48:51]
	v_mfma_f32_16x16x32_bf16 v[36:39], v[168:171], v[208:211], v[36:39]
	v_mfma_f32_16x16x32_bf16 v[32:35], v[176:179], v[208:211], v[32:35]
	v_mfma_f32_16x16x32_bf16 v[92:95], v[172:175], v[188:191], v[92:95]
	v_mfma_f32_16x16x32_bf16 v[88:91], v[180:183], v[188:191], v[88:91]
	v_mfma_f32_16x16x32_bf16 v[84:87], v[172:175], v[196:199], v[84:87]
	v_mfma_f32_16x16x32_bf16 v[80:83], v[180:183], v[196:199], v[80:83]
	v_mfma_f32_16x16x32_bf16 v[60:63], v[172:175], v[204:207], v[60:63]
	v_mfma_f32_16x16x32_bf16 v[48:51], v[180:183], v[204:207], v[48:51]
	v_mfma_f32_16x16x32_bf16 v[36:39], v[172:175], v[212:215], v[36:39]
	s_setprio 3
	s_barrier
	v_mfma_f32_16x16x32_bf16 v[32:35], v[180:183], v[212:215], v[32:35]
	s_setprio 0
	s_add_i32 s85, 0, 0x18000
	v_add_u32_e32 v155, s85, v150
	s_add_i32 s86, 0, 0x1c000
	ds_read_b128 v[146:149], v155
	ds_read_b128 v[156:159], v155 offset:1024
	ds_read_b128 v[160:163], v155 offset:2048
	ds_read_b128 v[164:167], v155 offset:3072
	v_add_u32_e32 v155, s86, v150
	ds_read_b128 v[168:171], v155
	ds_read_b128 v[172:175], v155 offset:1024
	ds_read_b128 v[176:179], v155 offset:2048
	ds_read_b128 v[180:183], v155 offset:3072
	s_add_u32 s52, s58, 0x2b0000
	s_addc_u32 s53, s59, 0
	s_mov_b32 m0, s65
	v_lshl_add_u64 v[224:225], s[52:53], 0, v[128:129]
	ds_read_b128 v[184:187], v154 offset:32768
	ds_read_b128 v[188:191], v154 offset:33792
	ds_read_b128 v[192:195], v154 offset:34816
	ds_read_b128 v[196:199], v154 offset:35840
	ds_read_b128 v[200:203], v154 offset:36864
	ds_read_b128 v[204:207], v154 offset:37888
	ds_read_b128 v[208:211], v154 offset:38912
	ds_read_b128 v[212:215], v154 offset:39936
	global_load_lds_dwordx4 v[224:225], off
	v_lshl_add_u64 v[224:225], s[52:53], 0, v[132:133]
	s_mov_b32 m0, s66
	s_nop 0
	global_load_lds_dwordx4 v[224:225], off
	s_waitcnt vmcnt(8)
	s_waitcnt lgkmcnt(0)
	s_barrier
	s_setprio 3
	s_waitcnt lgkmcnt(0)
	v_mfma_f32_16x16x32_bf16 v[76:79], v[146:149], v[184:187], v[76:79]
	v_mfma_f32_16x16x32_bf16 v[72:75], v[160:163], v[184:187], v[72:75]
	v_mfma_f32_16x16x32_bf16 v[68:71], v[146:149], v[192:195], v[68:71]
	v_mfma_f32_16x16x32_bf16 v[64:67], v[160:163], v[192:195], v[64:67]
	v_mfma_f32_16x16x32_bf16 v[56:59], v[146:149], v[200:203], v[56:59]
	v_mfma_f32_16x16x32_bf16 v[52:55], v[160:163], v[200:203], v[52:55]
	v_mfma_f32_16x16x32_bf16 v[44:47], v[146:149], v[208:211], v[44:47]
	v_mfma_f32_16x16x32_bf16 v[40:43], v[160:163], v[208:211], v[40:43]
	v_mfma_f32_16x16x32_bf16 v[76:79], v[156:159], v[188:191], v[76:79]
	v_mfma_f32_16x16x32_bf16 v[72:75], v[164:167], v[188:191], v[72:75]
	v_mfma_f32_16x16x32_bf16 v[68:71], v[156:159], v[196:199], v[68:71]
	v_mfma_f32_16x16x32_bf16 v[64:67], v[164:167], v[196:199], v[64:67]
	v_mfma_f32_16x16x32_bf16 v[56:59], v[156:159], v[204:207], v[56:59]
	v_mfma_f32_16x16x32_bf16 v[52:55], v[164:167], v[204:207], v[52:55]
	v_mfma_f32_16x16x32_bf16 v[44:47], v[156:159], v[212:215], v[44:47]
	v_mfma_f32_16x16x32_bf16 v[40:43], v[164:167], v[212:215], v[40:43]
	s_setprio 0
	s_setprio 3
	v_mfma_f32_16x16x32_bf16 v[124:127], v[168:171], v[184:187], v[124:127]
	v_mfma_f32_16x16x32_bf16 v[120:123], v[176:179], v[184:187], v[120:123]
	v_mfma_f32_16x16x32_bf16 v[116:119], v[168:171], v[192:195], v[116:119]
	v_mfma_f32_16x16x32_bf16 v[112:115], v[176:179], v[192:195], v[112:115]
	v_mfma_f32_16x16x32_bf16 v[108:111], v[168:171], v[200:203], v[108:111]
	v_mfma_f32_16x16x32_bf16 v[104:107], v[176:179], v[200:203], v[104:107]
	v_mfma_f32_16x16x32_bf16 v[100:103], v[168:171], v[208:211], v[100:103]
	v_mfma_f32_16x16x32_bf16 v[96:99], v[176:179], v[208:211], v[96:99]
	v_mfma_f32_16x16x32_bf16 v[124:127], v[172:175], v[188:191], v[124:127]
	v_mfma_f32_16x16x32_bf16 v[120:123], v[180:183], v[188:191], v[120:123]
	v_mfma_f32_16x16x32_bf16 v[116:119], v[172:175], v[196:199], v[116:119]
	v_mfma_f32_16x16x32_bf16 v[112:115], v[180:183], v[196:199], v[112:115]
	v_mfma_f32_16x16x32_bf16 v[108:111], v[172:175], v[204:207], v[108:111]
	v_mfma_f32_16x16x32_bf16 v[104:107], v[180:183], v[204:207], v[104:107]
	v_mfma_f32_16x16x32_bf16 v[100:103], v[172:175], v[212:215], v[100:103]
	s_setprio 3
	s_barrier
; #define PG8_STAGE(bufoff, gbase, voff) do { _Pragma("unroll") for (int _i = 0; _i < 2; ++_i) \
;         __builtin_amdgcn_global_load_lds((const unsigned*)((const char*)(gbase) + (voff)[_i]), (PG8_LAS unsigned*)(lds + (bufoff) + ldsw + _i * 8192), 16, 0, 0); } while (0)
; #define PG8_LDA(dst, b, h) do { _Pragma("unroll") for (int m = 0; m < 4; ++m) _Pragma("unroll") for (int k = 0; k < 2; ++k) dst[m][k] = *(const PG8_LAS bf16x8*)(lds + PG8_SA(b, h) + aoff + m * 2048 + k * 1024); } while (0)
; #define PG8_MMA(ai, bj, At, Bt) do { __builtin_amdgcn_s_setprio(1); _Pragma("unroll") for (int m = 0; m < 4; ++m) _Pragma("unroll") for (int n = 0; n < 2; ++n) _Pragma("unroll") for (int k = 0; k < 2; ++k) \
;         acc[ai][bj][m][n] = __builtin_amdgcn_mfma_f32_16x16x32_bf16(Bt[n][k], At[m][k], acc[ai][bj][m][n], 0, 0, 0); __builtin_amdgcn_s_setprio(0); } while (0)
; #define PG8_WAIT_V(n) asm volatile("s_waitcnt vmcnt(" #n ")" ::: "memory")
; #define PG8_WAIT_L(n) asm volatile("s_waitcnt lgkmcnt(" #n ")" ::: "memory")
; #define PG8_BAR __builtin_amdgcn_s_barrier()
; #define PG8_SCHED __builtin_amdgcn_sched_barrier(0)
; template <class Epi, class Sched, bool ALIGN_EPI = false, bool SP2 = false>
; __device__ __forceinline__ void gemm_phase(PG8_LAS unsigned char* lds, const Gemm g, const Sched& S, const Epi& E, const int wv  ) {
;     ...
;             PG8_LDA(At, 1, 1); PG8_STAGE(PG8_SB(1, 0), b3, voffB); PG8_STAGE(PG8_SB(1, 1), b3 + hstepB, voffB); PG8_STAGE(PG8_SA(1, 0), a3, voffA);
;             PG8_WAIT_V(8); PG8_WAIT_L(0); PG8_BAR; PG8_MMA(1, 0, At, B0); PG8_MMA(1, 1, At, B1); PG8_BAR; PG8_SCHED;
	v_mfma_f32_16x16x32_bf16 v[96:99], v[180:183], v[212:215], v[96:99]
	s_setprio 0
	s_add_i32 s52, s85, s62
	v_lshl_add_u64 v[216:217], v[216:217], 0, s[12:13]
	s_mov_b32 m0, s52
	ds_read_b128 v[184:187], v154 offset:49152
	ds_read_b128 v[188:191], v154 offset:50176
	ds_read_b128 v[192:195], v154 offset:51200
	ds_read_b128 v[196:199], v154 offset:52224
	ds_read_b128 v[200:203], v154 offset:53248
	ds_read_b128 v[204:207], v154 offset:54272
	ds_read_b128 v[208:211], v154 offset:55296
	ds_read_b128 v[212:215], v154 offset:56320
	global_load_lds_dwordx4 v[216:217], off
	s_add_i32 m0, s52, 0x2000
	s_add_u32 s52, s56, 0x2b0080
	v_lshl_add_u64 v[216:217], v[218:219], 0, s[12:13]
	s_addc_u32 s53, s57, 0
	s_add_i32 s56, s86, s62
	global_load_lds_dwordx4 v[216:217], off
	v_lshl_add_u64 v[216:217], s[52:53], 0, v[130:131]
	s_mov_b32 m0, s56
	s_nop 0
	global_load_lds_dwordx4 v[216:217], off
	v_lshl_add_u64 v[216:217], s[52:53], 0, v[134:135]
	s_add_i32 m0, s56, 0x2000
	s_nop 0
	global_load_lds_dwordx4 v[216:217], off
	v_lshl_add_u64 v[216:217], v[220:221], 0, s[12:13]
	s_mov_b32 m0, s69
	s_nop 0
	global_load_lds_dwordx4 v[216:217], off
	v_lshl_add_u64 v[216:217], v[222:223], 0, s[12:13]
	s_mov_b32 m0, s70
	s_nop 0
	global_load_lds_dwordx4 v[216:217], off
	s_waitcnt vmcnt(8)
	s_waitcnt lgkmcnt(0)
	s_barrier
	s_setprio 3
	s_waitcnt lgkmcnt(0)
	v_mfma_f32_16x16x32_bf16 v[28:31], v[146:149], v[184:187], v[28:31]
	v_mfma_f32_16x16x32_bf16 v[24:27], v[160:163], v[184:187], v[24:27]
	v_mfma_f32_16x16x32_bf16 v[20:23], v[146:149], v[192:195], v[20:23]
	v_mfma_f32_16x16x32_bf16 v[16:19], v[160:163], v[192:195], v[16:19]
	v_mfma_f32_16x16x32_bf16 v[12:15], v[146:149], v[200:203], v[12:15]
	v_mfma_f32_16x16x32_bf16 v[8:11], v[160:163], v[200:203], v[8:11]
	v_mfma_f32_16x16x32_bf16 v[4:7], v[146:149], v[208:211], v[4:7]
	v_mfma_f32_16x16x32_bf16 v[0:3], v[160:163], v[208:211], v[0:3]
	v_mfma_f32_16x16x32_bf16 v[28:31], v[156:159], v[188:191], v[28:31]
	v_mfma_f32_16x16x32_bf16 v[24:27], v[164:167], v[188:191], v[24:27]
	v_mfma_f32_16x16x32_bf16 v[20:23], v[156:159], v[196:199], v[20:23]
	v_mfma_f32_16x16x32_bf16 v[16:19], v[164:167], v[196:199], v[16:19]
	v_mfma_f32_16x16x32_bf16 v[12:15], v[156:159], v[204:207], v[12:15]
	v_mfma_f32_16x16x32_bf16 v[8:11], v[164:167], v[204:207], v[8:11]
	v_mfma_f32_16x16x32_bf16 v[4:7], v[156:159], v[212:215], v[4:7]
	v_mfma_f32_16x16x32_bf16 v[0:3], v[164:167], v[212:215], v[0:3]
	s_setprio 0
	s_setprio 3
	v_mfma_f32_16x16x32_bf16 v[92:95], v[168:171], v[184:187], v[92:95]
	v_mfma_f32_16x16x32_bf16 v[88:91], v[176:179], v[184:187], v[88:91]
	v_mfma_f32_16x16x32_bf16 v[84:87], v[168:171], v[192:195], v[84:87]
	v_mfma_f32_16x16x32_bf16 v[80:83], v[176:179], v[192:195], v[80:83]
	v_mfma_f32_16x16x32_bf16 v[60:63], v[168:171], v[200:203], v[60:63]
	v_mfma_f32_16x16x32_bf16 v[48:51], v[176:179], v[200:203], v[48:51]
	v_mfma_f32_16x16x32_bf16 v[36:39], v[168:171], v[208:211], v[36:39]
	v_mfma_f32_16x16x32_bf16 v[32:35], v[176:179], v[208:211], v[32:35]
	v_mfma_f32_16x16x32_bf16 v[92:95], v[172:175], v[188:191], v[92:95]
	v_mfma_f32_16x16x32_bf16 v[88:91], v[180:183], v[188:191], v[88:91]
	v_mfma_f32_16x16x32_bf16 v[84:87], v[172:175], v[196:199], v[84:87]
	v_mfma_f32_16x16x32_bf16 v[80:83], v[180:183], v[196:199], v[80:83]
	v_mfma_f32_16x16x32_bf16 v[60:63], v[172:175], v[204:207], v[60:63]
	v_mfma_f32_16x16x32_bf16 v[48:51], v[180:183], v[204:207], v[48:51]
	v_mfma_f32_16x16x32_bf16 v[36:39], v[172:175], v[212:215], v[36:39]
	s_setprio 3
	s_barrier
	v_mfma_f32_16x16x32_bf16 v[32:35], v[180:183], v[212:215], v[32:35]
	s_setprio 0
	s_add_i32 s84, s84, 2
	s_add_u32 s82, s82, 0x100
	s_addc_u32 s83, s83, 0
	s_cmpk_gt_u32 s84, 0xa9
	s_mov_b64 s[52:53], s[54:55]
	s_cbranch_scc0 .LBB0_2756
	s_and_b64 vcc, exec, s[14:15]
	s_cbranch_vccz .LBB0_2759
	s_barrier
